# all GEMM K-loops: back edge rotated (counter/pointer updates + next iteration's scalar head moved in front of the loop-back barrier)
# baseline (speedup 1.0000x reference)
; template <class Epi, class Sched, bool ALIGN_EPI = false, bool SP2 = false>
; __device__ __forceinline__ void gemm_phase(PG8_LAS unsigned char* lds, const Gemm g, const Sched& S, const Epi& E) {
;     ...
;         for (int t = 0; t < nt; t += 2) {
;             const bool last = (t == nt - 2);
;             const char* a1 = cA + (size_t)(t + 1) * kstep;
;             const char* a2 = last ? nA : cA + (size_t)(t + 2) * kstep; const char* b2 = last ? nB : cB + (size_t)(t + 2) * kstep;
;             const char* a3 = a2 + kstep; const char* b3 = b2 + kstep;
.LBB0_185:
	s_add_u32 s30, s28, 0xfffc0080
	s_addc_u32 s31, s29, -1
	s_add_i32 s55, 0, 0x10000
	s_cmp_eq_u32 s54, 12
	s_cselect_b32 s35, s23, s31
	s_cselect_b32 s34, s33, s30
	s_cselect_b32 s31, s21, s53
	s_cselect_b32 s30, s51, s52
	s_add_i32 s58, 0, 0x14000
	s_branch .Lrot_odin

; #define PG8_STAGE(bufoff, gbase, voff) do { _Pragma("unroll") for (int _i = 0; _i < 2; ++_i) \
;         __builtin_amdgcn_global_load_lds((const unsigned*)((const char*)(gbase) + (voff)[_i]), (PG8_LAS unsigned*)(lds + (bufoff) + ldsw + _i * 8192), 16, 0, 0); } while (0)
; #define PG8_LDA(dst, b, h) do { _Pragma("unroll") for (int m = 0; m < 4; ++m) _Pragma("unroll") for (int k = 0; k < 2; ++k) dst[m][k] = *(const PG8_LAS bf16x8*)(lds + PG8_SA(b, h) + aoff + m * 2048 + k * 1024); } while (0)
; #define PG8_LDB(dst, b, h) do { _Pragma("unroll") for (int n = 0; n < 2; ++n) _Pragma("unroll") for (int k = 0; k < 2; ++k) dst[n][k] = *(const PG8_LAS bf16x8*)(lds + PG8_SB(b, h) + boff + n * 2048 + k * 1024); } while (0)
; #define PG8_SCHED __builtin_amdgcn_sched_barrier(0)
;     __device__ __forceinline__ void operator()(const f32x4 (&acc)[2][2][4][2], const Unit& u, int wr, int wc, int fr, int fq) const {
;     ...
;             for (int m = 0; m < 4; ++m) rsv[ai][m] = row_rstd(ssq, row0 + ai * HALF + m * 16 + row_off) * sc;
; template <class Epi, class Sched, bool ALIGN_EPI = false, bool SP2 = false>
; __device__ __forceinline__ void gemm_phase(PG8_LAS unsigned char* lds, const Gemm g, const Sched& S, const Epi& E) {
;     ...
;             PG8_LDB(B0, 0, 0); PG8_LDB(B1, 0, 1); PG8_SCHED; PG8_LDA(At, 0, 0); PG8_STAGE(PG8_SA(1, 1), a1 + hstep, voffA);
.Lrot_odin:
	v_add_u32_e32 v146, s55, v151
	s_cmp_lg_u32 s54, 0
	s_cbranch_scc1 .Lodin_nopf
	s_cmp_lt_u32 s39, 0x1000
	s_cbranch_scc0 .Lodin_nopf
	s_lshl_b32 s98, s5, 12
	s_add_u32 s98, s10, s98
	s_addc_u32 s99, s11, 0
	v_lshlrev_b32_e32 v232, 4, v174
	s_add_i32 m0, s39, 0x21000
	s_nop 0
	global_load_lds_dwordx4 v232, s[98:99]

; #define PG8_STAGE(bufoff, gbase, voff) do { _Pragma("unroll") for (int _i = 0; _i < 2; ++_i) \
;         __builtin_amdgcn_global_load_lds((const unsigned*)((const char*)(gbase) + (voff)[_i]), (PG8_LAS unsigned*)(lds + (bufoff) + ldsw + _i * 8192), 16, 0, 0); } while (0)
; #define PG8_LDA(dst, b, h) do { _Pragma("unroll") for (int m = 0; m < 4; ++m) _Pragma("unroll") for (int k = 0; k < 2; ++k) dst[m][k] = *(const PG8_LAS bf16x8*)(lds + PG8_SA(b, h) + aoff + m * 2048 + k * 1024); } while (0)
; #define PG8_MMA(ai, bj, At, Bt) do { __builtin_amdgcn_s_setprio(1); _Pragma("unroll") for (int m = 0; m < 4; ++m) _Pragma("unroll") for (int n = 0; n < 2; ++n) _Pragma("unroll") for (int k = 0; k < 2; ++k) \
;         acc[ai][bj][m][n] = __builtin_amdgcn_mfma_f32_16x16x32_bf16(Bt[n][k], At[m][k], acc[ai][bj][m][n], 0, 0, 0); __builtin_amdgcn_s_setprio(0); } while (0)
; #define PG8_WAIT_V(n) asm volatile("s_waitcnt vmcnt(" #n ")" ::: "memory")
; #define PG8_WAIT_L(n) asm volatile("s_waitcnt lgkmcnt(" #n ")" ::: "memory")
; #define PG8_BAR __builtin_amdgcn_s_barrier()
; #define PG8_SCHED __builtin_amdgcn_sched_barrier(0)
; template <class Epi, class Sched, bool ALIGN_EPI = false, bool SP2 = false>
; __device__ __forceinline__ void gemm_phase(PG8_LAS unsigned char* lds, const Gemm g, const Sched& S, const Epi& E) {
;     ...
;             PG8_WAIT_V(8); PG8_WAIT_L(0); PG8_BAR; PG8_MMA(0, 0, At, B0); PG8_MMA(0, 1, At, B1); PG8_BAR; PG8_SCHED;
;             PG8_LDA(At, 0, 1); PG8_STAGE(PG8_SB(0, 0), b2, voffB); PG8_STAGE(PG8_SB(0, 1), b2 + hstep, voffB); PG8_STAGE(PG8_SA(0, 0), a2, voffA);
;             PG8_WAIT_V(8); PG8_WAIT_L(0); PG8_BAR; PG8_MMA(1, 0, At, B0); PG8_MMA(1, 1, At, B1); PG8_BAR; PG8_SCHED;
.Lodin_noz:
	s_waitcnt vmcnt(8)
	s_waitcnt lgkmcnt(0)
	s_barrier
	s_setprio 1
	s_waitcnt lgkmcnt(0)
	v_mfma_f32_16x16x32_bf16 v[70:73], v[130:133], v[188:191], v[70:73]
	v_mfma_f32_16x16x32_bf16 v[66:69], v[158:161], v[188:191], v[66:69]
	v_mfma_f32_16x16x32_bf16 v[62:65], v[130:133], v[196:199], v[62:65]
	v_mfma_f32_16x16x32_bf16 v[58:61], v[158:161], v[196:199], v[58:61]
	v_mfma_f32_16x16x32_bf16 v[54:57], v[130:133], v[204:207], v[54:57]
	v_mfma_f32_16x16x32_bf16 v[50:53], v[158:161], v[204:207], v[50:53]
	v_mfma_f32_16x16x32_bf16 v[46:49], v[130:133], v[212:215], v[46:49]
	v_mfma_f32_16x16x32_bf16 v[42:45], v[158:161], v[212:215], v[42:45]
	v_mfma_f32_16x16x32_bf16 v[70:73], v[154:157], v[192:195], v[70:73]
	v_mfma_f32_16x16x32_bf16 v[66:69], v[162:165], v[192:195], v[66:69]
	v_mfma_f32_16x16x32_bf16 v[62:65], v[154:157], v[200:203], v[62:65]
	v_mfma_f32_16x16x32_bf16 v[58:61], v[162:165], v[200:203], v[58:61]
	v_mfma_f32_16x16x32_bf16 v[54:57], v[154:157], v[208:211], v[54:57]
	v_mfma_f32_16x16x32_bf16 v[50:53], v[162:165], v[208:211], v[50:53]
	v_mfma_f32_16x16x32_bf16 v[46:49], v[154:157], v[216:219], v[46:49]
	v_mfma_f32_16x16x32_bf16 v[42:45], v[162:165], v[216:219], v[42:45]
	v_mfma_f32_16x16x32_bf16 v[126:129], v[166:169], v[188:191], v[126:129]
	v_mfma_f32_16x16x32_bf16 v[122:125], v[180:183], v[188:191], v[122:125]
	v_mfma_f32_16x16x32_bf16 v[118:121], v[166:169], v[196:199], v[118:121]
	v_mfma_f32_16x16x32_bf16 v[114:117], v[180:183], v[196:199], v[114:117]
	v_mfma_f32_16x16x32_bf16 v[110:113], v[166:169], v[204:207], v[110:113]
	v_mfma_f32_16x16x32_bf16 v[106:109], v[180:183], v[204:207], v[106:109]
	v_mfma_f32_16x16x32_bf16 v[102:105], v[166:169], v[212:215], v[102:105]
	v_mfma_f32_16x16x32_bf16 v[98:101], v[180:183], v[212:215], v[98:101]
	v_mfma_f32_16x16x32_bf16 v[126:129], v[170:173], v[192:195], v[126:129]
	v_mfma_f32_16x16x32_bf16 v[122:125], v[184:187], v[192:195], v[122:125]
	v_mfma_f32_16x16x32_bf16 v[118:121], v[170:173], v[200:203], v[118:121]
	v_mfma_f32_16x16x32_bf16 v[114:117], v[184:187], v[200:203], v[114:117]
	v_mfma_f32_16x16x32_bf16 v[110:113], v[170:173], v[208:211], v[110:113]
	v_mfma_f32_16x16x32_bf16 v[106:109], v[184:187], v[208:211], v[106:109]
	v_mfma_f32_16x16x32_bf16 v[102:105], v[170:173], v[216:219], v[102:105]
	v_mfma_f32_16x16x32_bf16 v[98:101], v[184:187], v[216:219], v[98:101]
	s_setprio 0
	s_barrier
	s_add_i32 s55, s55, s39
	v_lshl_add_u64 v[146:147], s[30:31], 0, v[138:139]
	s_mov_b32 m0, s55
	ds_read_b128 v[188:191], v153 offset:16384
	ds_read_b128 v[192:195], v153 offset:17408
	ds_read_b128 v[196:199], v153 offset:18432
	ds_read_b128 v[200:203], v153 offset:19456
	ds_read_b128 v[204:207], v153 offset:20480
	ds_read_b128 v[208:211], v153 offset:21504
	ds_read_b128 v[212:215], v153 offset:22528
	ds_read_b128 v[216:219], v153 offset:23552
	global_load_lds_dwordx4 v[146:147], off
	s_add_i32 m0, s55, 0x2000
	s_add_u32 s56, s30, 0x40000
	v_lshl_add_u64 v[220:221], s[30:31], 0, v[134:135]
	s_addc_u32 s57, s31, 0
	s_add_i32 s55, s58, s39
	global_load_lds_dwordx4 v[220:221], off
	v_lshl_add_u64 v[222:223], s[56:57], 0, v[138:139]
	s_mov_b32 m0, s55
	v_lshl_add_u64 v[228:229], s[34:35], 0, v[136:137]
	global_load_lds_dwordx4 v[222:223], off
	v_lshl_add_u64 v[222:223], s[56:57], 0, v[134:135]
	s_add_i32 m0, s55, 0x2000
	s_nop 0
	global_load_lds_dwordx4 v[222:223], off
	v_lshl_add_u64 v[222:223], s[34:35], 0, v[140:141]
	s_mov_b32 m0, s40
	s_nop 0
	global_load_lds_dwordx4 v[222:223], off
	s_mov_b32 m0, s41
	s_nop 0
	global_load_lds_dwordx4 v[228:229], off
	s_waitcnt vmcnt(8)
	s_waitcnt lgkmcnt(0)
	s_barrier
	s_setprio 1
	s_waitcnt lgkmcnt(0)
	v_mfma_f32_16x16x32_bf16 v[30:33], v[130:133], v[188:191], v[30:33]
	v_mfma_f32_16x16x32_bf16 v[26:29], v[158:161], v[188:191], v[26:29]
	v_mfma_f32_16x16x32_bf16 v[22:25], v[130:133], v[196:199], v[22:25]
	v_mfma_f32_16x16x32_bf16 v[18:21], v[158:161], v[196:199], v[18:21]
	v_mfma_f32_16x16x32_bf16 v[14:17], v[130:133], v[204:207], v[14:17]
	v_mfma_f32_16x16x32_bf16 v[10:13], v[158:161], v[204:207], v[10:13]
	v_mfma_f32_16x16x32_bf16 v[6:9], v[130:133], v[212:215], v[6:9]
	v_mfma_f32_16x16x32_bf16 v[2:5], v[158:161], v[212:215], v[2:5]
	v_mfma_f32_16x16x32_bf16 v[30:33], v[154:157], v[192:195], v[30:33]
	v_mfma_f32_16x16x32_bf16 v[26:29], v[162:165], v[192:195], v[26:29]
	v_mfma_f32_16x16x32_bf16 v[22:25], v[154:157], v[200:203], v[22:25]
	v_mfma_f32_16x16x32_bf16 v[18:21], v[162:165], v[200:203], v[18:21]
	v_mfma_f32_16x16x32_bf16 v[14:17], v[154:157], v[208:211], v[14:17]
	v_mfma_f32_16x16x32_bf16 v[10:13], v[162:165], v[208:211], v[10:13]
	v_mfma_f32_16x16x32_bf16 v[6:9], v[154:157], v[216:219], v[6:9]
	v_mfma_f32_16x16x32_bf16 v[2:5], v[162:165], v[216:219], v[2:5]
	v_mfma_f32_16x16x32_bf16 v[94:97], v[166:169], v[188:191], v[94:97]
	v_mfma_f32_16x16x32_bf16 v[90:93], v[180:183], v[188:191], v[90:93]
	v_mfma_f32_16x16x32_bf16 v[86:89], v[166:169], v[196:199], v[86:89]
	v_mfma_f32_16x16x32_bf16 v[82:85], v[180:183], v[196:199], v[82:85]
	v_mfma_f32_16x16x32_bf16 v[78:81], v[166:169], v[204:207], v[78:81]
	v_mfma_f32_16x16x32_bf16 v[74:77], v[180:183], v[204:207], v[74:77]
	v_mfma_f32_16x16x32_bf16 v[38:41], v[166:169], v[212:215], v[38:41]
	v_mfma_f32_16x16x32_bf16 v[34:37], v[180:183], v[212:215], v[34:37]
	v_mfma_f32_16x16x32_bf16 v[94:97], v[170:173], v[192:195], v[94:97]
	v_mfma_f32_16x16x32_bf16 v[90:93], v[184:187], v[192:195], v[90:93]
	v_mfma_f32_16x16x32_bf16 v[86:89], v[170:173], v[200:203], v[86:89]
	v_mfma_f32_16x16x32_bf16 v[82:85], v[184:187], v[200:203], v[82:85]
	v_mfma_f32_16x16x32_bf16 v[78:81], v[170:173], v[208:211], v[78:81]
	v_mfma_f32_16x16x32_bf16 v[74:77], v[184:187], v[208:211], v[74:77]
	v_mfma_f32_16x16x32_bf16 v[38:41], v[170:173], v[216:219], v[38:41]
	v_mfma_f32_16x16x32_bf16 v[34:37], v[184:187], v[216:219], v[34:37]
	s_setprio 0
	s_barrier
; #define PG8_STAGE(bufoff, gbase, voff) do { _Pragma("unroll") for (int _i = 0; _i < 2; ++_i) \
;         __builtin_amdgcn_global_load_lds((const unsigned*)((const char*)(gbase) + (voff)[_i]), (PG8_LAS unsigned*)(lds + (bufoff) + ldsw + _i * 8192), 16, 0, 0); } while (0)
; #define PG8_LDA(dst, b, h) do { _Pragma("unroll") for (int m = 0; m < 4; ++m) _Pragma("unroll") for (int k = 0; k < 2; ++k) dst[m][k] = *(const PG8_LAS bf16x8*)(lds + PG8_SA(b, h) + aoff + m * 2048 + k * 1024); } while (0)
; #define PG8_LDB(dst, b, h) do { _Pragma("unroll") for (int n = 0; n < 2; ++n) _Pragma("unroll") for (int k = 0; k < 2; ++k) dst[n][k] = *(const PG8_LAS bf16x8*)(lds + PG8_SB(b, h) + boff + n * 2048 + k * 1024); } while (0)
; #define PG8_MMA(ai, bj, At, Bt) do { __builtin_amdgcn_s_setprio(1); _Pragma("unroll") for (int m = 0; m < 4; ++m) _Pragma("unroll") for (int n = 0; n < 2; ++n) _Pragma("unroll") for (int k = 0; k < 2; ++k) \
;         acc[ai][bj][m][n] = __builtin_amdgcn_mfma_f32_16x16x32_bf16(Bt[n][k], At[m][k], acc[ai][bj][m][n], 0, 0, 0); __builtin_amdgcn_s_setprio(0); } while (0)
; #define PG8_WAIT_V(n) asm volatile("s_waitcnt vmcnt(" #n ")" ::: "memory")
; #define PG8_WAIT_L(n) asm volatile("s_waitcnt lgkmcnt(" #n ")" ::: "memory")
; #define PG8_BAR __builtin_amdgcn_s_barrier()
; #define PG8_SCHED __builtin_amdgcn_sched_barrier(0)
; template <class Epi, class Sched, bool ALIGN_EPI = false, bool SP2 = false>
; __device__ __forceinline__ void gemm_phase(PG8_LAS unsigned char* lds, const Gemm g, const Sched& S, const Epi& E) {
;     ...
;             PG8_LDB(B0, 1, 0); PG8_LDB(B1, 1, 1); PG8_SCHED; PG8_LDA(At, 1, 0); PG8_STAGE(PG8_SA(0, 1), a2 + hstep, voffA);
;             PG8_WAIT_V(8); PG8_WAIT_L(0); PG8_BAR; PG8_MMA(0, 0, At, B0); PG8_MMA(0, 1, At, B1); PG8_BAR; PG8_SCHED;
	s_add_i32 s55, 0, 0x18000
	v_add_u32_e32 v148, s55, v151
	s_add_i32 s56, 0, 0x1c000
	ds_read_b128 v[130:133], v148
	ds_read_b128 v[154:157], v148 offset:1024
	ds_read_b128 v[158:161], v148 offset:2048
	ds_read_b128 v[162:165], v148 offset:3072
	v_add_u32_e32 v148, s56, v151
	ds_read_b128 v[166:169], v148
	ds_read_b128 v[170:173], v148 offset:1024
	ds_read_b128 v[180:183], v148 offset:2048
	ds_read_b128 v[184:187], v148 offset:3072
	s_add_u32 s34, s34, 0x40000
	s_addc_u32 s35, s35, 0
	s_mov_b32 m0, s42
	v_lshl_add_u64 v[230:231], s[34:35], 0, v[140:141]
	ds_read_b128 v[188:191], v153 offset:32768
	ds_read_b128 v[192:195], v153 offset:33792
	ds_read_b128 v[196:199], v153 offset:34816
	ds_read_b128 v[200:203], v153 offset:35840
	ds_read_b128 v[204:207], v153 offset:36864
	ds_read_b128 v[208:211], v153 offset:37888
	ds_read_b128 v[212:215], v153 offset:38912
	ds_read_b128 v[216:219], v153 offset:39936
	global_load_lds_dwordx4 v[230:231], off
	v_lshl_add_u64 v[230:231], s[34:35], 0, v[136:137]
	s_mov_b32 m0, s43
	s_nop 0
	global_load_lds_dwordx4 v[230:231], off
	s_waitcnt vmcnt(8)
	s_waitcnt lgkmcnt(0)
	s_barrier
	s_setprio 1
	s_waitcnt lgkmcnt(0)
	v_mfma_f32_16x16x32_bf16 v[70:73], v[130:133], v[188:191], v[70:73]
	v_mfma_f32_16x16x32_bf16 v[66:69], v[158:161], v[188:191], v[66:69]
	v_mfma_f32_16x16x32_bf16 v[62:65], v[130:133], v[196:199], v[62:65]
	v_mfma_f32_16x16x32_bf16 v[58:61], v[158:161], v[196:199], v[58:61]
	v_mfma_f32_16x16x32_bf16 v[54:57], v[130:133], v[204:207], v[54:57]
	v_mfma_f32_16x16x32_bf16 v[50:53], v[158:161], v[204:207], v[50:53]
	v_mfma_f32_16x16x32_bf16 v[46:49], v[130:133], v[212:215], v[46:49]
	v_mfma_f32_16x16x32_bf16 v[42:45], v[158:161], v[212:215], v[42:45]
	v_mfma_f32_16x16x32_bf16 v[70:73], v[154:157], v[192:195], v[70:73]
	v_mfma_f32_16x16x32_bf16 v[66:69], v[162:165], v[192:195], v[66:69]
	v_mfma_f32_16x16x32_bf16 v[62:65], v[154:157], v[200:203], v[62:65]
	v_mfma_f32_16x16x32_bf16 v[58:61], v[162:165], v[200:203], v[58:61]
	v_mfma_f32_16x16x32_bf16 v[54:57], v[154:157], v[208:211], v[54:57]
	v_mfma_f32_16x16x32_bf16 v[50:53], v[162:165], v[208:211], v[50:53]
	v_mfma_f32_16x16x32_bf16 v[46:49], v[154:157], v[216:219], v[46:49]
	v_mfma_f32_16x16x32_bf16 v[42:45], v[162:165], v[216:219], v[42:45]
	v_mfma_f32_16x16x32_bf16 v[126:129], v[166:169], v[188:191], v[126:129]
	v_mfma_f32_16x16x32_bf16 v[122:125], v[180:183], v[188:191], v[122:125]
	v_mfma_f32_16x16x32_bf16 v[118:121], v[166:169], v[196:199], v[118:121]
	v_mfma_f32_16x16x32_bf16 v[114:117], v[180:183], v[196:199], v[114:117]
	v_mfma_f32_16x16x32_bf16 v[110:113], v[166:169], v[204:207], v[110:113]
	v_mfma_f32_16x16x32_bf16 v[106:109], v[180:183], v[204:207], v[106:109]
	v_mfma_f32_16x16x32_bf16 v[102:105], v[166:169], v[212:215], v[102:105]
	v_mfma_f32_16x16x32_bf16 v[98:101], v[180:183], v[212:215], v[98:101]
	v_mfma_f32_16x16x32_bf16 v[126:129], v[170:173], v[192:195], v[126:129]
	v_mfma_f32_16x16x32_bf16 v[122:125], v[184:187], v[192:195], v[122:125]
	v_mfma_f32_16x16x32_bf16 v[118:121], v[170:173], v[200:203], v[118:121]
	v_mfma_f32_16x16x32_bf16 v[114:117], v[184:187], v[200:203], v[114:117]
	v_mfma_f32_16x16x32_bf16 v[110:113], v[170:173], v[208:211], v[110:113]
	v_mfma_f32_16x16x32_bf16 v[106:109], v[184:187], v[208:211], v[106:109]
	v_mfma_f32_16x16x32_bf16 v[102:105], v[170:173], v[216:219], v[102:105]
	v_mfma_f32_16x16x32_bf16 v[98:101], v[184:187], v[216:219], v[98:101]
	s_setprio 0
	s_barrier
; #define PG8_STAGE(bufoff, gbase, voff) do { _Pragma("unroll") for (int _i = 0; _i < 2; ++_i) \
;         __builtin_amdgcn_global_load_lds((const unsigned*)((const char*)(gbase) + (voff)[_i]), (PG8_LAS unsigned*)(lds + (bufoff) + ldsw + _i * 8192), 16, 0, 0); } while (0)
; #define PG8_LDA(dst, b, h) do { _Pragma("unroll") for (int m = 0; m < 4; ++m) _Pragma("unroll") for (int k = 0; k < 2; ++k) dst[m][k] = *(const PG8_LAS bf16x8*)(lds + PG8_SA(b, h) + aoff + m * 2048 + k * 1024); } while (0)
; #define PG8_MMA(ai, bj, At, Bt) do { __builtin_amdgcn_s_setprio(1); _Pragma("unroll") for (int m = 0; m < 4; ++m) _Pragma("unroll") for (int n = 0; n < 2; ++n) _Pragma("unroll") for (int k = 0; k < 2; ++k) \
;         acc[ai][bj][m][n] = __builtin_amdgcn_mfma_f32_16x16x32_bf16(Bt[n][k], At[m][k], acc[ai][bj][m][n], 0, 0, 0); __builtin_amdgcn_s_setprio(0); } while (0)
; #define PG8_WAIT_V(n) asm volatile("s_waitcnt vmcnt(" #n ")" ::: "memory")
; #define PG8_WAIT_L(n) asm volatile("s_waitcnt lgkmcnt(" #n ")" ::: "memory")
; #define PG8_BAR __builtin_amdgcn_s_barrier()
; #define PG8_SCHED __builtin_amdgcn_sched_barrier(0)
; template <class Epi, class Sched, bool ALIGN_EPI = false, bool SP2 = false>
; __device__ __forceinline__ void gemm_phase(PG8_LAS unsigned char* lds, const Gemm g, const Sched& S, const Epi& E) {
;     ...
;         for (int t = 0; t < nt; t += 2) {
;             const bool last = (t == nt - 2);
;             const char* a1 = cA + (size_t)(t + 1) * kstep;
;             const char* a2 = last ? nA : cA + (size_t)(t + 2) * kstep; const char* b2 = last ? nB : cB + (size_t)(t + 2) * kstep;
;             const char* a3 = a2 + kstep; const char* b3 = b2 + kstep;
;     ...
;             PG8_LDA(At, 1, 1); PG8_STAGE(PG8_SB(1, 0), b3, voffB); PG8_STAGE(PG8_SB(1, 1), b3 + hstep, voffB); PG8_STAGE(PG8_SA(1, 0), a3, voffA);
;             PG8_WAIT_V(8); PG8_WAIT_L(0); PG8_BAR; PG8_MMA(1, 0, At, B0); PG8_MMA(1, 1, At, B1); PG8_BAR; PG8_SCHED;
	s_add_i32 s34, s55, s39
	v_lshl_add_u64 v[146:147], v[146:147], 0, s[96:97]
	s_mov_b32 m0, s34
	ds_read_b128 v[188:191], v153 offset:49152
	ds_read_b128 v[192:195], v153 offset:50176
	ds_read_b128 v[196:199], v153 offset:51200
	ds_read_b128 v[200:203], v153 offset:52224
	ds_read_b128 v[204:207], v153 offset:53248
	ds_read_b128 v[208:211], v153 offset:54272
	ds_read_b128 v[212:215], v153 offset:55296
	ds_read_b128 v[216:219], v153 offset:56320
	global_load_lds_dwordx4 v[146:147], off
	s_add_i32 m0, s34, 0x2000
	s_add_u32 s30, s30, 0x40080
	v_lshl_add_u64 v[146:147], v[220:221], 0, s[96:97]
	s_addc_u32 s31, s31, 0
	s_add_i32 s34, s56, s39
	global_load_lds_dwordx4 v[146:147], off
	v_lshl_add_u64 v[146:147], s[30:31], 0, v[138:139]
	s_mov_b32 m0, s34
	s_nop 0
	global_load_lds_dwordx4 v[146:147], off
	v_lshl_add_u64 v[146:147], s[30:31], 0, v[134:135]
	s_add_i32 m0, s34, 0x2000
	s_nop 0
	global_load_lds_dwordx4 v[146:147], off
	v_lshl_add_u64 v[146:147], v[222:223], 0, s[96:97]
	s_mov_b32 m0, s48
	s_nop 0
	global_load_lds_dwordx4 v[146:147], off
	v_lshl_add_u64 v[146:147], v[228:229], 0, s[96:97]
	s_mov_b32 m0, s49
	s_nop 0
	global_load_lds_dwordx4 v[146:147], off
	s_waitcnt vmcnt(8)
	s_waitcnt lgkmcnt(0)
	s_barrier
	s_setprio 1
	s_waitcnt lgkmcnt(0)
	v_mfma_f32_16x16x32_bf16 v[30:33], v[130:133], v[188:191], v[30:33]
	v_mfma_f32_16x16x32_bf16 v[26:29], v[158:161], v[188:191], v[26:29]
	v_mfma_f32_16x16x32_bf16 v[22:25], v[130:133], v[196:199], v[22:25]
	v_mfma_f32_16x16x32_bf16 v[18:21], v[158:161], v[196:199], v[18:21]
	v_mfma_f32_16x16x32_bf16 v[14:17], v[130:133], v[204:207], v[14:17]
	v_mfma_f32_16x16x32_bf16 v[10:13], v[158:161], v[204:207], v[10:13]
	v_mfma_f32_16x16x32_bf16 v[6:9], v[130:133], v[212:215], v[6:9]
	v_mfma_f32_16x16x32_bf16 v[2:5], v[158:161], v[212:215], v[2:5]
	v_mfma_f32_16x16x32_bf16 v[30:33], v[154:157], v[192:195], v[30:33]
	v_mfma_f32_16x16x32_bf16 v[26:29], v[162:165], v[192:195], v[26:29]
	v_mfma_f32_16x16x32_bf16 v[22:25], v[154:157], v[200:203], v[22:25]
	v_mfma_f32_16x16x32_bf16 v[18:21], v[162:165], v[200:203], v[18:21]
	v_mfma_f32_16x16x32_bf16 v[14:17], v[154:157], v[208:211], v[14:17]
	v_mfma_f32_16x16x32_bf16 v[10:13], v[162:165], v[208:211], v[10:13]
	v_mfma_f32_16x16x32_bf16 v[6:9], v[154:157], v[216:219], v[6:9]
	v_mfma_f32_16x16x32_bf16 v[2:5], v[162:165], v[216:219], v[2:5]
	v_mfma_f32_16x16x32_bf16 v[94:97], v[166:169], v[188:191], v[94:97]
	v_mfma_f32_16x16x32_bf16 v[90:93], v[180:183], v[188:191], v[90:93]
	v_mfma_f32_16x16x32_bf16 v[86:89], v[166:169], v[196:199], v[86:89]
	v_mfma_f32_16x16x32_bf16 v[82:85], v[180:183], v[196:199], v[82:85]
	v_mfma_f32_16x16x32_bf16 v[78:81], v[166:169], v[204:207], v[78:81]
	v_mfma_f32_16x16x32_bf16 v[74:77], v[180:183], v[204:207], v[74:77]
	v_mfma_f32_16x16x32_bf16 v[38:41], v[166:169], v[212:215], v[38:41]
	v_mfma_f32_16x16x32_bf16 v[34:37], v[180:183], v[212:215], v[34:37]
	v_mfma_f32_16x16x32_bf16 v[94:97], v[170:173], v[192:195], v[94:97]
	v_mfma_f32_16x16x32_bf16 v[90:93], v[184:187], v[192:195], v[90:93]
	v_mfma_f32_16x16x32_bf16 v[86:89], v[170:173], v[200:203], v[86:89]
	v_mfma_f32_16x16x32_bf16 v[82:85], v[184:187], v[200:203], v[82:85]
	v_mfma_f32_16x16x32_bf16 v[78:81], v[170:173], v[208:211], v[78:81]
	v_mfma_f32_16x16x32_bf16 v[74:77], v[184:187], v[208:211], v[74:77]
	v_mfma_f32_16x16x32_bf16 v[38:41], v[170:173], v[216:219], v[38:41]
	v_mfma_f32_16x16x32_bf16 v[34:37], v[184:187], v[216:219], v[34:37]
	s_setprio 0
	s_add_i32 s54, s54, 2
	s_add_u32 s28, s28, 0x100
	s_addc_u32 s29, s29, 0
	s_add_u32 s52, s52, 0x100
	s_addc_u32 s53, s53, 0
	s_add_u32 s30, s28, 0xfffc0080
	s_addc_u32 s31, s29, -1
	s_add_i32 s55, 0, 0x10000
	s_cmp_eq_u32 s54, 12
	s_cselect_b32 s35, s23, s31
	s_cselect_b32 s34, s33, s30
	s_cselect_b32 s31, s21, s53
	s_cselect_b32 s30, s51, s52
	s_add_i32 s58, 0, 0x14000
	s_cmp_gt_u32 s54, 13
	s_cbranch_scc0 .Lrotb_odin
	s_barrier
	s_and_b64 vcc, exec, s[16:17]
	s_cbranch_vccz .LBB0_188
	s_barrier

; template <class Epi, class Sched, bool ALIGN_EPI = false, bool SP2 = false>
; __device__ __forceinline__ void gemm_phase(PG8_LAS unsigned char* lds, const Gemm g, const Sched& S, const Epi& E) {
;     ...
;         for (int t = 0; t < nt; t += 2) {
;             const bool last = (t == nt - 2);
;             const char* a1 = cA + (size_t)(t + 1) * kstep;
;             const char* a2 = last ? nA : cA + (size_t)(t + 2) * kstep; const char* b2 = last ? nB : cB + (size_t)(t + 2) * kstep;
;             const char* a3 = a2 + kstep; const char* b3 = b2 + kstep;
.LBB0_633:
	s_add_u32 s12, s10, 0xfffc0080
	s_addc_u32 s13, s11, -1
	s_add_i32 s56, 0, 0x10000
	s_cmp_eq_u32 s55, 12
	s_cselect_b32 s37, s5, s13
	s_cselect_b32 s36, s25, s12
	s_cselect_b32 s13, s27, s54
	s_cselect_b32 s12, s29, s33
	s_add_i32 s58, 0, 0x14000
	s_branch .Lrot_odout

; #define PG8_STAGE(bufoff, gbase, voff) do { _Pragma("unroll") for (int _i = 0; _i < 2; ++_i) \
;         __builtin_amdgcn_global_load_lds((const unsigned*)((const char*)(gbase) + (voff)[_i]), (PG8_LAS unsigned*)(lds + (bufoff) + ldsw + _i * 8192), 16, 0, 0); } while (0)
; #define PG8_LDA(dst, b, h) do { _Pragma("unroll") for (int m = 0; m < 4; ++m) _Pragma("unroll") for (int k = 0; k < 2; ++k) dst[m][k] = *(const PG8_LAS bf16x8*)(lds + PG8_SA(b, h) + aoff + m * 2048 + k * 1024); } while (0)
; #define PG8_LDB(dst, b, h) do { _Pragma("unroll") for (int n = 0; n < 2; ++n) _Pragma("unroll") for (int k = 0; k < 2; ++k) dst[n][k] = *(const PG8_LAS bf16x8*)(lds + PG8_SB(b, h) + boff + n * 2048 + k * 1024); } while (0)
; #define PG8_MMA(ai, bj, At, Bt) do { __builtin_amdgcn_s_setprio(1); _Pragma("unroll") for (int m = 0; m < 4; ++m) _Pragma("unroll") for (int n = 0; n < 2; ++n) _Pragma("unroll") for (int k = 0; k < 2; ++k) \
;         acc[ai][bj][m][n] = __builtin_amdgcn_mfma_f32_16x16x32_bf16(Bt[n][k], At[m][k], acc[ai][bj][m][n], 0, 0, 0); __builtin_amdgcn_s_setprio(0); } while (0)
; #define PG8_WAIT_V(n) asm volatile("s_waitcnt vmcnt(" #n ")" ::: "memory")
; #define PG8_WAIT_L(n) asm volatile("s_waitcnt lgkmcnt(" #n ")" ::: "memory")
; #define PG8_BAR __builtin_amdgcn_s_barrier()
; #define PG8_SCHED __builtin_amdgcn_sched_barrier(0)
; template <class Epi, class Sched, bool ALIGN_EPI = false, bool SP2 = false>
; __device__ __forceinline__ void gemm_phase(PG8_LAS unsigned char* lds, const Gemm g, const Sched& S, const Epi& E) {
;     ...
;             PG8_LDB(B0, 0, 0); PG8_LDB(B1, 0, 1); PG8_SCHED; PG8_LDA(At, 0, 0); PG8_STAGE(PG8_SA(1, 1), a1 + hstep, voffA);
;             PG8_WAIT_V(8); PG8_WAIT_L(0); PG8_BAR; PG8_MMA(0, 0, At, B0); PG8_MMA(0, 1, At, B1); PG8_BAR; PG8_SCHED;
;     ...
;         for (int a = 0; a < 2; ++a)
; #pragma unroll
;             for (int b = 0; b < 2; ++b)
; #pragma unroll
;                 for (int m = 0; m < 4; ++m)
; #pragma unroll
;                     for (int n = 0; n < 2; ++n) acc[a][b][m][n] = (f32x4){0.f, 0.f, 0.f, 0.f};
.Lrot_odout:
	v_add_u32_e32 v94, s56, v203
	v_add_u32_e32 v134, s58, v203
	ds_read_b128 v[66:69], v94
	ds_read_b128 v[70:73], v94 offset:1024
	ds_read_b128 v[82:85], v94 offset:2048
	ds_read_b128 v[94:97], v94 offset:3072
	ds_read_b128 v[106:109], v134
	ds_read_b128 v[118:121], v134 offset:1024
	ds_read_b128 v[130:133], v134 offset:2048
	ds_read_b128 v[134:137], v134 offset:3072
	v_lshl_add_u64 v[200:201], s[10:11], 0, v[184:185]
	s_add_i32 m0, s43, 0xc000
	ds_read_b128 v[162:165], v204
	ds_read_b128 v[166:169], v204 offset:1024
	ds_read_b128 v[188:191], v204 offset:2048
	ds_read_b128 v[192:195], v204 offset:3072
	ds_read_b128 v[196:199], v204 offset:4096
	ds_read_b128 v[206:209], v204 offset:5120
	ds_read_b128 v[210:213], v204 offset:6144
	ds_read_b128 v[214:217], v204 offset:7168
	global_load_lds_dwordx4 v[200:201], off
	v_lshl_add_u64 v[200:201], s[10:11], 0, v[186:187]
	s_add_i32 m0, s43, 0xe000
	s_nop 0
	global_load_lds_dwordx4 v[200:201], off
	s_cmp_lg_u32 s55, -2
	s_cbranch_scc1 .Lodout_noz
	v_mov_b32_e32 v2, 0
	v_mov_b32_e32 v3, v2
	v_mov_b32_e32 v4, v2
	v_mov_b32_e32 v5, v2
	v_mov_b32_e32 v6, v2
	v_mov_b32_e32 v7, v2
	v_mov_b32_e32 v8, v2
	v_mov_b32_e32 v9, v2
	v_mov_b32_e32 v18, v2
	v_mov_b32_e32 v19, v2
	v_mov_b32_e32 v20, v2
	v_mov_b32_e32 v21, v2
	v_mov_b32_e32 v22, v2
	v_mov_b32_e32 v23, v2
	v_mov_b32_e32 v24, v2
	v_mov_b32_e32 v25, v2
	v_mov_b32_e32 v34, v2
	v_mov_b32_e32 v35, v2
	v_mov_b32_e32 v36, v2
	v_mov_b32_e32 v37, v2
	v_mov_b32_e32 v38, v2
	v_mov_b32_e32 v39, v2
	v_mov_b32_e32 v40, v2
	v_mov_b32_e32 v41, v2
	v_mov_b32_e32 v50, v2
	v_mov_b32_e32 v51, v2
	v_mov_b32_e32 v52, v2
	v_mov_b32_e32 v53, v2
	v_mov_b32_e32 v54, v2
	v_mov_b32_e32 v55, v2
	v_mov_b32_e32 v56, v2
	v_mov_b32_e32 v57, v2
	v_mov_b32_e32 v10, v2
	v_mov_b32_e32 v11, v2
	v_mov_b32_e32 v12, v2
	v_mov_b32_e32 v13, v2
	v_mov_b32_e32 v14, v2
	v_mov_b32_e32 v15, v2
	v_mov_b32_e32 v16, v2
	v_mov_b32_e32 v17, v2
	v_mov_b32_e32 v26, v2
	v_mov_b32_e32 v27, v2
	v_mov_b32_e32 v28, v2
	v_mov_b32_e32 v29, v2
	v_mov_b32_e32 v30, v2
	v_mov_b32_e32 v31, v2
	v_mov_b32_e32 v32, v2
	v_mov_b32_e32 v33, v2
	v_mov_b32_e32 v42, v2
	v_mov_b32_e32 v43, v2
	v_mov_b32_e32 v44, v2
	v_mov_b32_e32 v45, v2
	v_mov_b32_e32 v46, v2
	v_mov_b32_e32 v47, v2
	v_mov_b32_e32 v48, v2
	v_mov_b32_e32 v49, v2
	v_mov_b32_e32 v58, v2
	v_mov_b32_e32 v59, v2
	v_mov_b32_e32 v60, v2
	v_mov_b32_e32 v61, v2
	v_mov_b32_e32 v62, v2
	v_mov_b32_e32 v63, v2
	v_mov_b32_e32 v64, v2
	v_mov_b32_e32 v65, v2
	v_mov_b32_e32 v74, v2
	v_mov_b32_e32 v75, v2
	v_mov_b32_e32 v76, v2
	v_mov_b32_e32 v77, v2
	v_mov_b32_e32 v78, v2
	v_mov_b32_e32 v79, v2
	v_mov_b32_e32 v80, v2
	v_mov_b32_e32 v81, v2
	v_mov_b32_e32 v98, v2
	v_mov_b32_e32 v99, v2
	v_mov_b32_e32 v100, v2
	v_mov_b32_e32 v101, v2
	v_mov_b32_e32 v102, v2
	v_mov_b32_e32 v103, v2
	v_mov_b32_e32 v104, v2
	v_mov_b32_e32 v105, v2
	v_mov_b32_e32 v122, v2
	v_mov_b32_e32 v123, v2
	v_mov_b32_e32 v124, v2
	v_mov_b32_e32 v125, v2
	v_mov_b32_e32 v126, v2
	v_mov_b32_e32 v127, v2
	v_mov_b32_e32 v128, v2
	v_mov_b32_e32 v129, v2
	v_mov_b32_e32 v146, v2
	v_mov_b32_e32 v147, v2
	v_mov_b32_e32 v148, v2
	v_mov_b32_e32 v149, v2
	v_mov_b32_e32 v150, v2
	v_mov_b32_e32 v151, v2
	v_mov_b32_e32 v152, v2
	v_mov_b32_e32 v153, v2
	v_mov_b32_e32 v86, v2
	v_mov_b32_e32 v87, v2
	v_mov_b32_e32 v88, v2
	v_mov_b32_e32 v89, v2
	v_mov_b32_e32 v90, v2
	v_mov_b32_e32 v91, v2
	v_mov_b32_e32 v92, v2
	v_mov_b32_e32 v93, v2
	v_mov_b32_e32 v110, v2
	v_mov_b32_e32 v111, v2
	v_mov_b32_e32 v112, v2
	v_mov_b32_e32 v113, v2
	v_mov_b32_e32 v114, v2
	v_mov_b32_e32 v115, v2
	v_mov_b32_e32 v116, v2
	v_mov_b32_e32 v117, v2
	v_mov_b32_e32 v138, v2
	v_mov_b32_e32 v139, v2
	v_mov_b32_e32 v140, v2
	v_mov_b32_e32 v141, v2
	v_mov_b32_e32 v142, v2
	v_mov_b32_e32 v143, v2
	v_mov_b32_e32 v144, v2
	v_mov_b32_e32 v145, v2
	v_mov_b32_e32 v154, v2
	v_mov_b32_e32 v155, v2
	v_mov_b32_e32 v156, v2
	v_mov_b32_e32 v157, v2
	v_mov_b32_e32 v158, v2
	v_mov_b32_e32 v159, v2
	v_mov_b32_e32 v160, v2
	v_mov_b32_e32 v161, v2
.Lodout_noz:
	s_waitcnt vmcnt(8)
	s_waitcnt lgkmcnt(0)
	s_barrier
	s_setprio 1
	s_waitcnt lgkmcnt(0)
	v_mfma_f32_16x16x32_bf16 v[158:161], v[66:69], v[162:165], v[158:161]
	v_mfma_f32_16x16x32_bf16 v[154:157], v[82:85], v[162:165], v[154:157]
	v_mfma_f32_16x16x32_bf16 v[142:145], v[66:69], v[188:191], v[142:145]
	v_mfma_f32_16x16x32_bf16 v[138:141], v[82:85], v[188:191], v[138:141]
	v_mfma_f32_16x16x32_bf16 v[114:117], v[66:69], v[196:199], v[114:117]
	v_mfma_f32_16x16x32_bf16 v[110:113], v[82:85], v[196:199], v[110:113]
	v_mfma_f32_16x16x32_bf16 v[90:93], v[66:69], v[210:213], v[90:93]
	v_mfma_f32_16x16x32_bf16 v[86:89], v[82:85], v[210:213], v[86:89]
	v_mfma_f32_16x16x32_bf16 v[158:161], v[70:73], v[166:169], v[158:161]
	v_mfma_f32_16x16x32_bf16 v[154:157], v[94:97], v[166:169], v[154:157]
	v_mfma_f32_16x16x32_bf16 v[142:145], v[70:73], v[192:195], v[142:145]
	v_mfma_f32_16x16x32_bf16 v[138:141], v[94:97], v[192:195], v[138:141]
	v_mfma_f32_16x16x32_bf16 v[114:117], v[70:73], v[206:209], v[114:117]
	v_mfma_f32_16x16x32_bf16 v[110:113], v[94:97], v[206:209], v[110:113]
	v_mfma_f32_16x16x32_bf16 v[90:93], v[70:73], v[214:217], v[90:93]
	v_mfma_f32_16x16x32_bf16 v[86:89], v[94:97], v[214:217], v[86:89]
	v_mfma_f32_16x16x32_bf16 v[150:153], v[106:109], v[162:165], v[150:153]
	v_mfma_f32_16x16x32_bf16 v[146:149], v[130:133], v[162:165], v[146:149]
	v_mfma_f32_16x16x32_bf16 v[126:129], v[106:109], v[188:191], v[126:129]
	v_mfma_f32_16x16x32_bf16 v[122:125], v[130:133], v[188:191], v[122:125]
	v_mfma_f32_16x16x32_bf16 v[102:105], v[106:109], v[196:199], v[102:105]
	v_mfma_f32_16x16x32_bf16 v[98:101], v[130:133], v[196:199], v[98:101]
	v_mfma_f32_16x16x32_bf16 v[78:81], v[106:109], v[210:213], v[78:81]
	v_mfma_f32_16x16x32_bf16 v[74:77], v[130:133], v[210:213], v[74:77]
	v_mfma_f32_16x16x32_bf16 v[150:153], v[118:121], v[166:169], v[150:153]
	v_mfma_f32_16x16x32_bf16 v[146:149], v[134:137], v[166:169], v[146:149]
	v_mfma_f32_16x16x32_bf16 v[126:129], v[118:121], v[192:195], v[126:129]
	v_mfma_f32_16x16x32_bf16 v[122:125], v[134:137], v[192:195], v[122:125]
	v_mfma_f32_16x16x32_bf16 v[102:105], v[118:121], v[206:209], v[102:105]
	v_mfma_f32_16x16x32_bf16 v[98:101], v[134:137], v[206:209], v[98:101]
	v_mfma_f32_16x16x32_bf16 v[78:81], v[118:121], v[214:217], v[78:81]
	v_mfma_f32_16x16x32_bf16 v[74:77], v[134:137], v[214:217], v[74:77]
	s_setprio 0
	s_barrier
; #define PG8_STAGE(bufoff, gbase, voff) do { _Pragma("unroll") for (int _i = 0; _i < 2; ++_i) \
;         __builtin_amdgcn_global_load_lds((const unsigned*)((const char*)(gbase) + (voff)[_i]), (PG8_LAS unsigned*)(lds + (bufoff) + ldsw + _i * 8192), 16, 0, 0); } while (0)
; #define PG8_LDA(dst, b, h) do { _Pragma("unroll") for (int m = 0; m < 4; ++m) _Pragma("unroll") for (int k = 0; k < 2; ++k) dst[m][k] = *(const PG8_LAS bf16x8*)(lds + PG8_SA(b, h) + aoff + m * 2048 + k * 1024); } while (0)
; #define PG8_LDB(dst, b, h) do { _Pragma("unroll") for (int n = 0; n < 2; ++n) _Pragma("unroll") for (int k = 0; k < 2; ++k) dst[n][k] = *(const PG8_LAS bf16x8*)(lds + PG8_SB(b, h) + boff + n * 2048 + k * 1024); } while (0)
; #define PG8_MMA(ai, bj, At, Bt) do { __builtin_amdgcn_s_setprio(1); _Pragma("unroll") for (int m = 0; m < 4; ++m) _Pragma("unroll") for (int n = 0; n < 2; ++n) _Pragma("unroll") for (int k = 0; k < 2; ++k) \
;         acc[ai][bj][m][n] = __builtin_amdgcn_mfma_f32_16x16x32_bf16(Bt[n][k], At[m][k], acc[ai][bj][m][n], 0, 0, 0); __builtin_amdgcn_s_setprio(0); } while (0)
; #define PG8_WAIT_V(n) asm volatile("s_waitcnt vmcnt(" #n ")" ::: "memory")
; #define PG8_WAIT_L(n) asm volatile("s_waitcnt lgkmcnt(" #n ")" ::: "memory")
; #define PG8_BAR __builtin_amdgcn_s_barrier()
; #define PG8_SCHED __builtin_amdgcn_sched_barrier(0)
; template <class Epi, class Sched, bool ALIGN_EPI = false, bool SP2 = false>
; __device__ __forceinline__ void gemm_phase(PG8_LAS unsigned char* lds, const Gemm g, const Sched& S, const Epi& E) {
;     ...
;             PG8_LDA(At, 0, 1); PG8_STAGE(PG8_SB(0, 0), b2, voffB); PG8_STAGE(PG8_SB(0, 1), b2 + hstep, voffB); PG8_STAGE(PG8_SA(0, 0), a2, voffA);
;             PG8_WAIT_V(8); PG8_WAIT_L(0); PG8_BAR; PG8_MMA(1, 0, At, B0); PG8_MMA(1, 1, At, B1); PG8_BAR; PG8_SCHED;
;             PG8_LDB(B0, 1, 0); PG8_LDB(B1, 1, 1); PG8_SCHED; PG8_LDA(At, 1, 0); PG8_STAGE(PG8_SA(0, 1), a2 + hstep, voffA);
;             PG8_WAIT_V(8); PG8_WAIT_L(0); PG8_BAR; PG8_MMA(0, 0, At, B0); PG8_MMA(0, 1, At, B1); PG8_BAR; PG8_SCHED;
	s_add_i32 s56, s56, s42
	v_lshl_add_u64 v[200:201], s[12:13], 0, v[180:181]
	s_mov_b32 m0, s56
	ds_read_b128 v[162:165], v204 offset:16384
	ds_read_b128 v[166:169], v204 offset:17408
	ds_read_b128 v[188:191], v204 offset:18432
	ds_read_b128 v[192:195], v204 offset:19456
	ds_read_b128 v[196:199], v204 offset:20480
	ds_read_b128 v[206:209], v204 offset:21504
	ds_read_b128 v[210:213], v204 offset:22528
	ds_read_b128 v[214:217], v204 offset:23552
	global_load_lds_dwordx4 v[200:201], off
	s_add_i32 m0, s56, 0x2000
	s_add_u32 s56, s12, 0x40000
	v_lshl_add_u64 v[218:219], s[12:13], 0, v[170:171]
	s_addc_u32 s57, s13, 0
	s_add_i32 s58, s58, s42
	global_load_lds_dwordx4 v[218:219], off
	v_lshl_add_u64 v[220:221], s[56:57], 0, v[180:181]
	s_mov_b32 m0, s58
	v_lshl_add_u64 v[222:223], s[36:37], 0, v[172:173]
	global_load_lds_dwordx4 v[220:221], off
	v_lshl_add_u64 v[220:221], s[56:57], 0, v[170:171]
	s_add_i32 m0, s58, 0x2000
	s_nop 0
	global_load_lds_dwordx4 v[220:221], off
	v_lshl_add_u64 v[220:221], s[36:37], 0, v[182:183]
	s_mov_b32 m0, s43
	s_nop 0
	global_load_lds_dwordx4 v[220:221], off
	s_mov_b32 m0, s44
	s_nop 0
	global_load_lds_dwordx4 v[222:223], off
	s_waitcnt vmcnt(8)
	s_waitcnt lgkmcnt(0)
	s_barrier
	s_setprio 1
	s_waitcnt lgkmcnt(0)
	v_mfma_f32_16x16x32_bf16 v[62:65], v[66:69], v[162:165], v[62:65]
	v_mfma_f32_16x16x32_bf16 v[58:61], v[82:85], v[162:165], v[58:61]
	v_mfma_f32_16x16x32_bf16 v[46:49], v[66:69], v[188:191], v[46:49]
	v_mfma_f32_16x16x32_bf16 v[42:45], v[82:85], v[188:191], v[42:45]
	v_mfma_f32_16x16x32_bf16 v[30:33], v[66:69], v[196:199], v[30:33]
	v_mfma_f32_16x16x32_bf16 v[26:29], v[82:85], v[196:199], v[26:29]
	v_mfma_f32_16x16x32_bf16 v[14:17], v[66:69], v[210:213], v[14:17]
	v_mfma_f32_16x16x32_bf16 v[10:13], v[82:85], v[210:213], v[10:13]
	v_mfma_f32_16x16x32_bf16 v[62:65], v[70:73], v[166:169], v[62:65]
	v_mfma_f32_16x16x32_bf16 v[58:61], v[94:97], v[166:169], v[58:61]
	v_mfma_f32_16x16x32_bf16 v[46:49], v[70:73], v[192:195], v[46:49]
	v_mfma_f32_16x16x32_bf16 v[42:45], v[94:97], v[192:195], v[42:45]
	v_mfma_f32_16x16x32_bf16 v[30:33], v[70:73], v[206:209], v[30:33]
	v_mfma_f32_16x16x32_bf16 v[26:29], v[94:97], v[206:209], v[26:29]
	v_mfma_f32_16x16x32_bf16 v[14:17], v[70:73], v[214:217], v[14:17]
	v_mfma_f32_16x16x32_bf16 v[10:13], v[94:97], v[214:217], v[10:13]
	v_mfma_f32_16x16x32_bf16 v[54:57], v[106:109], v[162:165], v[54:57]
	v_mfma_f32_16x16x32_bf16 v[50:53], v[130:133], v[162:165], v[50:53]
	v_mfma_f32_16x16x32_bf16 v[38:41], v[106:109], v[188:191], v[38:41]
	v_mfma_f32_16x16x32_bf16 v[34:37], v[130:133], v[188:191], v[34:37]
	v_mfma_f32_16x16x32_bf16 v[22:25], v[106:109], v[196:199], v[22:25]
	v_mfma_f32_16x16x32_bf16 v[18:21], v[130:133], v[196:199], v[18:21]
	v_mfma_f32_16x16x32_bf16 v[6:9], v[106:109], v[210:213], v[6:9]
	v_mfma_f32_16x16x32_bf16 v[2:5], v[130:133], v[210:213], v[2:5]
	v_mfma_f32_16x16x32_bf16 v[54:57], v[118:121], v[166:169], v[54:57]
	v_mfma_f32_16x16x32_bf16 v[50:53], v[134:137], v[166:169], v[50:53]
	v_mfma_f32_16x16x32_bf16 v[38:41], v[118:121], v[192:195], v[38:41]
	v_mfma_f32_16x16x32_bf16 v[34:37], v[134:137], v[192:195], v[34:37]
	v_mfma_f32_16x16x32_bf16 v[22:25], v[118:121], v[206:209], v[22:25]
	v_mfma_f32_16x16x32_bf16 v[18:21], v[134:137], v[206:209], v[18:21]
	v_mfma_f32_16x16x32_bf16 v[6:9], v[118:121], v[214:217], v[6:9]
	v_mfma_f32_16x16x32_bf16 v[2:5], v[134:137], v[214:217], v[2:5]
	s_setprio 0
	s_barrier
	s_add_i32 s56, 0, 0x18000
	s_add_i32 s57, 0, 0x1c000
	v_add_u32_e32 v94, s56, v203
	v_add_u32_e32 v134, s57, v203
	ds_read_b128 v[66:69], v94
	ds_read_b128 v[70:73], v94 offset:1024
	ds_read_b128 v[82:85], v94 offset:2048
	ds_read_b128 v[94:97], v94 offset:3072
	ds_read_b128 v[106:109], v134
	ds_read_b128 v[118:121], v134 offset:1024
	ds_read_b128 v[130:133], v134 offset:2048
	ds_read_b128 v[134:137], v134 offset:3072
	s_add_u32 s36, s36, 0x40000
	s_addc_u32 s37, s37, 0
	s_mov_b32 m0, s45
	v_lshl_add_u64 v[228:229], s[36:37], 0, v[182:183]
	ds_read_b128 v[162:165], v204 offset:32768
	ds_read_b128 v[166:169], v204 offset:33792
	ds_read_b128 v[188:191], v204 offset:34816
	ds_read_b128 v[192:195], v204 offset:35840
	ds_read_b128 v[196:199], v204 offset:36864
	ds_read_b128 v[206:209], v204 offset:37888
	ds_read_b128 v[210:213], v204 offset:38912
	ds_read_b128 v[214:217], v204 offset:39936
	global_load_lds_dwordx4 v[228:229], off
	v_lshl_add_u64 v[228:229], s[36:37], 0, v[172:173]
	s_mov_b32 m0, s46
	s_nop 0
	global_load_lds_dwordx4 v[228:229], off
	s_waitcnt vmcnt(8)
	s_waitcnt lgkmcnt(0)
	s_barrier
; #define PG8_STAGE(bufoff, gbase, voff) do { _Pragma("unroll") for (int _i = 0; _i < 2; ++_i) \
;         __builtin_amdgcn_global_load_lds((const unsigned*)((const char*)(gbase) + (voff)[_i]), (PG8_LAS unsigned*)(lds + (bufoff) + ldsw + _i * 8192), 16, 0, 0); } while (0)
; #define PG8_LDA(dst, b, h) do { _Pragma("unroll") for (int m = 0; m < 4; ++m) _Pragma("unroll") for (int k = 0; k < 2; ++k) dst[m][k] = *(const PG8_LAS bf16x8*)(lds + PG8_SA(b, h) + aoff + m * 2048 + k * 1024); } while (0)
; #define PG8_MMA(ai, bj, At, Bt) do { __builtin_amdgcn_s_setprio(1); _Pragma("unroll") for (int m = 0; m < 4; ++m) _Pragma("unroll") for (int n = 0; n < 2; ++n) _Pragma("unroll") for (int k = 0; k < 2; ++k) \
;         acc[ai][bj][m][n] = __builtin_amdgcn_mfma_f32_16x16x32_bf16(Bt[n][k], At[m][k], acc[ai][bj][m][n], 0, 0, 0); __builtin_amdgcn_s_setprio(0); } while (0)
; #define PG8_WAIT_V(n) asm volatile("s_waitcnt vmcnt(" #n ")" ::: "memory")
; #define PG8_WAIT_L(n) asm volatile("s_waitcnt lgkmcnt(" #n ")" ::: "memory")
; #define PG8_BAR __builtin_amdgcn_s_barrier()
; #define PG8_SCHED __builtin_amdgcn_sched_barrier(0)
; template <class Epi, class Sched, bool ALIGN_EPI = false, bool SP2 = false>
; __device__ __forceinline__ void gemm_phase(PG8_LAS unsigned char* lds, const Gemm g, const Sched& S, const Epi& E) {
;     ...
;         for (int t = 0; t < nt; t += 2) {
;             const bool last = (t == nt - 2);
;             const char* a1 = cA + (size_t)(t + 1) * kstep;
;             const char* a2 = last ? nA : cA + (size_t)(t + 2) * kstep; const char* b2 = last ? nB : cB + (size_t)(t + 2) * kstep;
;             const char* a3 = a2 + kstep; const char* b3 = b2 + kstep;
;     ...
;             PG8_WAIT_V(8); PG8_WAIT_L(0); PG8_BAR; PG8_MMA(0, 0, At, B0); PG8_MMA(0, 1, At, B1); PG8_BAR; PG8_SCHED;
;             PG8_LDA(At, 1, 1); PG8_STAGE(PG8_SB(1, 0), b3, voffB); PG8_STAGE(PG8_SB(1, 1), b3 + hstep, voffB); PG8_STAGE(PG8_SA(1, 0), a3, voffA);
;             PG8_WAIT_V(8); PG8_WAIT_L(0); PG8_BAR; PG8_MMA(1, 0, At, B0); PG8_MMA(1, 1, At, B1); PG8_BAR; PG8_SCHED;
	s_setprio 1
	s_waitcnt lgkmcnt(0)
	v_mfma_f32_16x16x32_bf16 v[158:161], v[66:69], v[162:165], v[158:161]
	v_mfma_f32_16x16x32_bf16 v[154:157], v[82:85], v[162:165], v[154:157]
	v_mfma_f32_16x16x32_bf16 v[142:145], v[66:69], v[188:191], v[142:145]
	v_mfma_f32_16x16x32_bf16 v[138:141], v[82:85], v[188:191], v[138:141]
	v_mfma_f32_16x16x32_bf16 v[114:117], v[66:69], v[196:199], v[114:117]
	v_mfma_f32_16x16x32_bf16 v[110:113], v[82:85], v[196:199], v[110:113]
	v_mfma_f32_16x16x32_bf16 v[90:93], v[66:69], v[210:213], v[90:93]
	v_mfma_f32_16x16x32_bf16 v[86:89], v[82:85], v[210:213], v[86:89]
	v_mfma_f32_16x16x32_bf16 v[158:161], v[70:73], v[166:169], v[158:161]
	v_mfma_f32_16x16x32_bf16 v[154:157], v[94:97], v[166:169], v[154:157]
	v_mfma_f32_16x16x32_bf16 v[142:145], v[70:73], v[192:195], v[142:145]
	v_mfma_f32_16x16x32_bf16 v[138:141], v[94:97], v[192:195], v[138:141]
	v_mfma_f32_16x16x32_bf16 v[114:117], v[70:73], v[206:209], v[114:117]
	v_mfma_f32_16x16x32_bf16 v[110:113], v[94:97], v[206:209], v[110:113]
	v_mfma_f32_16x16x32_bf16 v[90:93], v[70:73], v[214:217], v[90:93]
	v_mfma_f32_16x16x32_bf16 v[86:89], v[94:97], v[214:217], v[86:89]
	v_mfma_f32_16x16x32_bf16 v[150:153], v[106:109], v[162:165], v[150:153]
	v_mfma_f32_16x16x32_bf16 v[146:149], v[130:133], v[162:165], v[146:149]
	v_mfma_f32_16x16x32_bf16 v[126:129], v[106:109], v[188:191], v[126:129]
	v_mfma_f32_16x16x32_bf16 v[122:125], v[130:133], v[188:191], v[122:125]
	v_mfma_f32_16x16x32_bf16 v[102:105], v[106:109], v[196:199], v[102:105]
	v_mfma_f32_16x16x32_bf16 v[98:101], v[130:133], v[196:199], v[98:101]
	v_mfma_f32_16x16x32_bf16 v[78:81], v[106:109], v[210:213], v[78:81]
	v_mfma_f32_16x16x32_bf16 v[74:77], v[130:133], v[210:213], v[74:77]
	v_mfma_f32_16x16x32_bf16 v[150:153], v[118:121], v[166:169], v[150:153]
	v_mfma_f32_16x16x32_bf16 v[146:149], v[134:137], v[166:169], v[146:149]
	v_mfma_f32_16x16x32_bf16 v[126:129], v[118:121], v[192:195], v[126:129]
	v_mfma_f32_16x16x32_bf16 v[122:125], v[134:137], v[192:195], v[122:125]
	v_mfma_f32_16x16x32_bf16 v[102:105], v[118:121], v[206:209], v[102:105]
	v_mfma_f32_16x16x32_bf16 v[98:101], v[134:137], v[206:209], v[98:101]
	v_mfma_f32_16x16x32_bf16 v[78:81], v[118:121], v[214:217], v[78:81]
	v_mfma_f32_16x16x32_bf16 v[74:77], v[134:137], v[214:217], v[74:77]
	s_setprio 0
	s_barrier
	s_add_i32 s36, s56, s42
	v_lshl_add_u64 v[200:201], v[200:201], 0, s[96:97]
	s_mov_b32 m0, s36
	ds_read_b128 v[162:165], v204 offset:49152
	ds_read_b128 v[166:169], v204 offset:50176
	ds_read_b128 v[188:191], v204 offset:51200
	ds_read_b128 v[192:195], v204 offset:52224
	ds_read_b128 v[196:199], v204 offset:53248
	ds_read_b128 v[206:209], v204 offset:54272
	ds_read_b128 v[210:213], v204 offset:55296
	ds_read_b128 v[214:217], v204 offset:56320
	global_load_lds_dwordx4 v[200:201], off
	s_add_i32 m0, s36, 0x2000
	s_add_u32 s12, s12, 0x40080
	v_lshl_add_u64 v[200:201], v[218:219], 0, s[96:97]
	s_addc_u32 s13, s13, 0
	s_add_i32 s36, s57, s42
	global_load_lds_dwordx4 v[200:201], off
	v_lshl_add_u64 v[200:201], s[12:13], 0, v[180:181]
	s_mov_b32 m0, s36
	s_nop 0
	global_load_lds_dwordx4 v[200:201], off
	v_lshl_add_u64 v[200:201], s[12:13], 0, v[170:171]
	s_add_i32 m0, s36, 0x2000
	s_nop 0
	global_load_lds_dwordx4 v[200:201], off
	v_lshl_add_u64 v[200:201], v[220:221], 0, s[96:97]
	s_mov_b32 m0, s50
	s_nop 0
	global_load_lds_dwordx4 v[200:201], off
	v_lshl_add_u64 v[200:201], v[222:223], 0, s[96:97]
	s_mov_b32 m0, s51
	s_nop 0
	global_load_lds_dwordx4 v[200:201], off
	s_waitcnt vmcnt(8)
	s_waitcnt lgkmcnt(0)
	s_barrier
	s_setprio 1
	s_waitcnt lgkmcnt(0)
	v_mfma_f32_16x16x32_bf16 v[62:65], v[66:69], v[162:165], v[62:65]
	v_mfma_f32_16x16x32_bf16 v[58:61], v[82:85], v[162:165], v[58:61]
	v_mfma_f32_16x16x32_bf16 v[46:49], v[66:69], v[188:191], v[46:49]
	v_mfma_f32_16x16x32_bf16 v[42:45], v[82:85], v[188:191], v[42:45]
	v_mfma_f32_16x16x32_bf16 v[30:33], v[66:69], v[196:199], v[30:33]
	v_mfma_f32_16x16x32_bf16 v[26:29], v[82:85], v[196:199], v[26:29]
	v_mfma_f32_16x16x32_bf16 v[14:17], v[66:69], v[210:213], v[14:17]
	v_mfma_f32_16x16x32_bf16 v[10:13], v[82:85], v[210:213], v[10:13]
	v_mfma_f32_16x16x32_bf16 v[62:65], v[70:73], v[166:169], v[62:65]
	v_mfma_f32_16x16x32_bf16 v[58:61], v[94:97], v[166:169], v[58:61]
	v_mfma_f32_16x16x32_bf16 v[46:49], v[70:73], v[192:195], v[46:49]
	v_mfma_f32_16x16x32_bf16 v[42:45], v[94:97], v[192:195], v[42:45]
	v_mfma_f32_16x16x32_bf16 v[30:33], v[70:73], v[206:209], v[30:33]
	v_mfma_f32_16x16x32_bf16 v[26:29], v[94:97], v[206:209], v[26:29]
	v_mfma_f32_16x16x32_bf16 v[14:17], v[70:73], v[214:217], v[14:17]
	v_mfma_f32_16x16x32_bf16 v[10:13], v[94:97], v[214:217], v[10:13]
	v_mfma_f32_16x16x32_bf16 v[54:57], v[106:109], v[162:165], v[54:57]
	v_mfma_f32_16x16x32_bf16 v[50:53], v[130:133], v[162:165], v[50:53]
	v_mfma_f32_16x16x32_bf16 v[38:41], v[106:109], v[188:191], v[38:41]
	v_mfma_f32_16x16x32_bf16 v[34:37], v[130:133], v[188:191], v[34:37]
	v_mfma_f32_16x16x32_bf16 v[22:25], v[106:109], v[196:199], v[22:25]
	v_mfma_f32_16x16x32_bf16 v[18:21], v[130:133], v[196:199], v[18:21]
	v_mfma_f32_16x16x32_bf16 v[6:9], v[106:109], v[210:213], v[6:9]
	v_mfma_f32_16x16x32_bf16 v[2:5], v[130:133], v[210:213], v[2:5]
	v_mfma_f32_16x16x32_bf16 v[54:57], v[118:121], v[166:169], v[54:57]
	v_mfma_f32_16x16x32_bf16 v[50:53], v[134:137], v[166:169], v[50:53]
	v_mfma_f32_16x16x32_bf16 v[38:41], v[118:121], v[192:195], v[38:41]
	v_mfma_f32_16x16x32_bf16 v[34:37], v[134:137], v[192:195], v[34:37]
	v_mfma_f32_16x16x32_bf16 v[22:25], v[118:121], v[206:209], v[22:25]
	v_mfma_f32_16x16x32_bf16 v[18:21], v[134:137], v[206:209], v[18:21]
	v_mfma_f32_16x16x32_bf16 v[6:9], v[118:121], v[214:217], v[6:9]
	v_mfma_f32_16x16x32_bf16 v[2:5], v[134:137], v[214:217], v[2:5]
	s_setprio 0
	s_add_i32 s55, s55, 2
	s_add_u32 s10, s10, 0x100
	s_addc_u32 s11, s11, 0
	s_add_u32 s33, s33, 0x100
	s_addc_u32 s54, s54, 0
	s_add_u32 s12, s10, 0xfffc0080
	s_addc_u32 s13, s11, -1
	s_add_i32 s56, 0, 0x10000
	s_cmp_eq_u32 s55, 12
	s_cselect_b32 s37, s5, s13
	s_cselect_b32 s36, s25, s12
	s_cselect_b32 s13, s27, s54
	s_cselect_b32 s12, s29, s33
	s_add_i32 s58, 0, 0x14000
	s_cmp_gt_u32 s55, 13
	s_cbranch_scc0 .Lrotb_odout
	s_barrier
	s_and_b64 vcc, exec, s[20:21]
	s_cbranch_vccz .LBB0_636
	s_barrier

; template <class Epi, class Sched, bool ALIGN_EPI = false, bool SP2 = false>
; __device__ __forceinline__ void gemm_phase(PG8_LAS unsigned char* lds, const Gemm g, const Sched& S, const Epi& E) {
;     ...
;         const char* nA = has_next ? (const char*)g.A + (size_t)nxt.pm * tstep : cA; const char* nB = has_next ? (const char*)g.Bt + (size_t)nxt.pn * tstep : cB;
;         for (int t = 0; t < nt; t += 2) {
;             const bool last = (t == nt - 2);
;             const char* a1 = cA + (size_t)(t + 1) * kstep;
;             const char* a2 = last ? nA : cA + (size_t)(t + 2) * kstep; const char* b2 = last ? nB : cB + (size_t)(t + 2) * kstep;
;             const char* a3 = a2 + kstep; const char* b3 = b2 + kstep;
.LBB0_812:
	s_add_u32 s26, s24, 0xfffc0080
	s_addc_u32 s27, s25, -1
	s_add_i32 s49, 0, 0x10000
	s_cmp_eq_u32 s48, 12
	s_cselect_b32 s29, s19, s27
	s_cselect_b32 s28, s33, s26
	s_cselect_b32 s27, s17, s47
	s_cselect_b32 s26, s45, s46
	s_add_i32 s52, 0, 0x14000
	s_branch .Lrot_evin

; #define PG8_STAGE(bufoff, gbase, voff) do { _Pragma("unroll") for (int _i = 0; _i < 2; ++_i) \
;         __builtin_amdgcn_global_load_lds((const unsigned*)((const char*)(gbase) + (voff)[_i]), (PG8_LAS unsigned*)(lds + (bufoff) + ldsw + _i * 8192), 16, 0, 0); } while (0)
; #define PG8_LDA(dst, b, h) do { _Pragma("unroll") for (int m = 0; m < 4; ++m) _Pragma("unroll") for (int k = 0; k < 2; ++k) dst[m][k] = *(const PG8_LAS bf16x8*)(lds + PG8_SA(b, h) + aoff + m * 2048 + k * 1024); } while (0)
; #define PG8_LDB(dst, b, h) do { _Pragma("unroll") for (int n = 0; n < 2; ++n) _Pragma("unroll") for (int k = 0; k < 2; ++k) dst[n][k] = *(const PG8_LAS bf16x8*)(lds + PG8_SB(b, h) + boff + n * 2048 + k * 1024); } while (0)
; #define PG8_SCHED __builtin_amdgcn_sched_barrier(0)
; template <class Epi, class Sched, bool ALIGN_EPI = false, bool SP2 = false>
; __device__ __forceinline__ void gemm_phase(PG8_LAS unsigned char* lds, const Gemm g, const Sched& S, const Epi& E) {
;     ...
;         for (int t = 0; t < nt; t += 2) {
;             const bool last = (t == nt - 2);
;             const char* a1 = cA + (size_t)(t + 1) * kstep;
;             const char* a2 = last ? nA : cA + (size_t)(t + 2) * kstep; const char* b2 = last ? nB : cB + (size_t)(t + 2) * kstep;
;             const char* a3 = a2 + kstep; const char* b3 = b2 + kstep;
;             if (last && has_next) S.a_ready(nxt);
;             if constexpr (SP2) {
;             PG8_LDB(B0, 0, 0); PG8_LDB(B1, 0, 1); PG8_SCHED; PG8_LDA(At, 0, 0); PG8_STAGE(PG8_SA(1, 1), a1 + hstep, voffA);
.Lrot_evin:
	v_add_u32_e32 v142, s49, v145
	s_cmp_lg_u32 s48, 0
	s_cbranch_scc1 .Levin_nopf
	s_cmp_lt_u32 s35, 0x1000
	s_cbranch_scc0 .Levin_nopf
	s_lshl_b32 s98, s5, 12
	s_add_u32 s98, s10, s98
	s_addc_u32 s99, s11, 0
	v_lshlrev_b32_e32 v232, 4, v174
	s_add_i32 m0, s35, 0x21000
	s_nop 0
	global_load_lds_dwordx4 v232, s[98:99]

; #define PG8_STAGE(bufoff, gbase, voff) do { _Pragma("unroll") for (int _i = 0; _i < 2; ++_i) \
;         __builtin_amdgcn_global_load_lds((const unsigned*)((const char*)(gbase) + (voff)[_i]), (PG8_LAS unsigned*)(lds + (bufoff) + ldsw + _i * 8192), 16, 0, 0); } while (0)
; #define PG8_LDA(dst, b, h) do { _Pragma("unroll") for (int m = 0; m < 4; ++m) _Pragma("unroll") for (int k = 0; k < 2; ++k) dst[m][k] = *(const PG8_LAS bf16x8*)(lds + PG8_SA(b, h) + aoff + m * 2048 + k * 1024); } while (0)
; #define PG8_MMA(ai, bj, At, Bt) do { __builtin_amdgcn_s_setprio(1); _Pragma("unroll") for (int m = 0; m < 4; ++m) _Pragma("unroll") for (int n = 0; n < 2; ++n) _Pragma("unroll") for (int k = 0; k < 2; ++k) \
;         acc[ai][bj][m][n] = __builtin_amdgcn_mfma_f32_16x16x32_bf16(Bt[n][k], At[m][k], acc[ai][bj][m][n], 0, 0, 0); __builtin_amdgcn_s_setprio(0); } while (0)
; #define PG8_WAIT_V(n) asm volatile("s_waitcnt vmcnt(" #n ")" ::: "memory")
; #define PG8_WAIT_L(n) asm volatile("s_waitcnt lgkmcnt(" #n ")" ::: "memory")
; #define PG8_BAR __builtin_amdgcn_s_barrier()
; #define PG8_SCHED __builtin_amdgcn_sched_barrier(0)
; template <class Epi, class Sched, bool ALIGN_EPI = false, bool SP2 = false>
; __device__ __forceinline__ void gemm_phase(PG8_LAS unsigned char* lds, const Gemm g, const Sched& S, const Epi& E) {
;     ...
;             PG8_WAIT_V(8); PG8_WAIT_L(0); PG8_BAR; PG8_MMA(0, 0, At, B0); PG8_MMA(0, 1, At, B1); PG8_BAR; PG8_SCHED;
;             PG8_LDA(At, 0, 1); PG8_STAGE(PG8_SB(0, 0), b2, voffB); PG8_STAGE(PG8_SB(0, 1), b2 + hstep, voffB); PG8_STAGE(PG8_SA(0, 0), a2, voffA);
;             PG8_WAIT_V(8); PG8_WAIT_L(0); PG8_BAR; PG8_MMA(1, 0, At, B0); PG8_MMA(1, 1, At, B1); PG8_BAR; PG8_SCHED;
.Levin_noz:
	s_waitcnt vmcnt(8)
	s_waitcnt lgkmcnt(0)
	s_barrier
	s_setprio 1
	s_waitcnt lgkmcnt(0)
	v_mfma_f32_16x16x32_bf16 v[126:129], v[150:153], v[188:191], v[126:129]
	v_mfma_f32_16x16x32_bf16 v[122:125], v[158:161], v[188:191], v[122:125]
	v_mfma_f32_16x16x32_bf16 v[114:117], v[150:153], v[196:199], v[114:117]
	v_mfma_f32_16x16x32_bf16 v[106:109], v[158:161], v[196:199], v[106:109]
	v_mfma_f32_16x16x32_bf16 v[98:101], v[150:153], v[204:207], v[98:101]
	v_mfma_f32_16x16x32_bf16 v[90:93], v[158:161], v[204:207], v[90:93]
	v_mfma_f32_16x16x32_bf16 v[82:85], v[150:153], v[212:215], v[82:85]
	v_mfma_f32_16x16x32_bf16 v[74:77], v[158:161], v[212:215], v[74:77]
	v_mfma_f32_16x16x32_bf16 v[126:129], v[154:157], v[192:195], v[126:129]
	v_mfma_f32_16x16x32_bf16 v[122:125], v[162:165], v[192:195], v[122:125]
	v_mfma_f32_16x16x32_bf16 v[114:117], v[154:157], v[200:203], v[114:117]
	v_mfma_f32_16x16x32_bf16 v[106:109], v[162:165], v[200:203], v[106:109]
	v_mfma_f32_16x16x32_bf16 v[98:101], v[154:157], v[208:211], v[98:101]
	v_mfma_f32_16x16x32_bf16 v[90:93], v[162:165], v[208:211], v[90:93]
	v_mfma_f32_16x16x32_bf16 v[82:85], v[154:157], v[216:219], v[82:85]
	v_mfma_f32_16x16x32_bf16 v[74:77], v[162:165], v[216:219], v[74:77]
	v_mfma_f32_16x16x32_bf16 v[118:121], v[166:169], v[188:191], v[118:121]
	v_mfma_f32_16x16x32_bf16 v[110:113], v[180:183], v[188:191], v[110:113]
	v_mfma_f32_16x16x32_bf16 v[102:105], v[166:169], v[196:199], v[102:105]
	v_mfma_f32_16x16x32_bf16 v[94:97], v[180:183], v[196:199], v[94:97]
	v_mfma_f32_16x16x32_bf16 v[86:89], v[166:169], v[204:207], v[86:89]
	v_mfma_f32_16x16x32_bf16 v[78:81], v[180:183], v[204:207], v[78:81]
	v_mfma_f32_16x16x32_bf16 v[70:73], v[166:169], v[212:215], v[70:73]
	v_mfma_f32_16x16x32_bf16 v[66:69], v[180:183], v[212:215], v[66:69]
	v_mfma_f32_16x16x32_bf16 v[118:121], v[170:173], v[192:195], v[118:121]
	v_mfma_f32_16x16x32_bf16 v[110:113], v[184:187], v[192:195], v[110:113]
	v_mfma_f32_16x16x32_bf16 v[102:105], v[170:173], v[200:203], v[102:105]
	v_mfma_f32_16x16x32_bf16 v[94:97], v[184:187], v[200:203], v[94:97]
	v_mfma_f32_16x16x32_bf16 v[86:89], v[170:173], v[208:211], v[86:89]
	v_mfma_f32_16x16x32_bf16 v[78:81], v[184:187], v[208:211], v[78:81]
	v_mfma_f32_16x16x32_bf16 v[70:73], v[170:173], v[216:219], v[70:73]
	v_mfma_f32_16x16x32_bf16 v[66:69], v[184:187], v[216:219], v[66:69]
	s_setprio 0
	s_barrier
	s_add_i32 s49, s49, s35
	v_lshl_add_u64 v[146:147], s[26:27], 0, v[134:135]
	s_mov_b32 m0, s49
	ds_read_b128 v[188:191], v149 offset:16384
	ds_read_b128 v[192:195], v149 offset:17408
	ds_read_b128 v[196:199], v149 offset:18432
	ds_read_b128 v[200:203], v149 offset:19456
	ds_read_b128 v[204:207], v149 offset:20480
	ds_read_b128 v[208:211], v149 offset:21504
	ds_read_b128 v[212:215], v149 offset:22528
	ds_read_b128 v[216:219], v149 offset:23552
	global_load_lds_dwordx4 v[146:147], off
	s_add_i32 m0, s49, 0x2000
	s_add_u32 s50, s26, 0x40000
	v_lshl_add_u64 v[220:221], s[26:27], 0, v[130:131]
	s_addc_u32 s51, s27, 0
	s_add_i32 s49, s52, s35
	global_load_lds_dwordx4 v[220:221], off
	v_lshl_add_u64 v[222:223], s[50:51], 0, v[134:135]
	s_mov_b32 m0, s49
	v_lshl_add_u64 v[228:229], s[28:29], 0, v[132:133]
	global_load_lds_dwordx4 v[222:223], off
	v_lshl_add_u64 v[222:223], s[50:51], 0, v[130:131]
	s_add_i32 m0, s49, 0x2000
	s_nop 0
	global_load_lds_dwordx4 v[222:223], off
	v_lshl_add_u64 v[222:223], s[28:29], 0, v[136:137]
	s_mov_b32 m0, s36
	s_nop 0
	global_load_lds_dwordx4 v[222:223], off
	s_mov_b32 m0, s37
	s_nop 0
	global_load_lds_dwordx4 v[228:229], off
	s_waitcnt vmcnt(8)
	s_waitcnt lgkmcnt(0)
	s_barrier
	s_setprio 1
	s_waitcnt lgkmcnt(0)
	v_mfma_f32_16x16x32_bf16 v[62:65], v[150:153], v[188:191], v[62:65]
	v_mfma_f32_16x16x32_bf16 v[58:61], v[158:161], v[188:191], v[58:61]
	v_mfma_f32_16x16x32_bf16 v[50:53], v[150:153], v[196:199], v[50:53]
	v_mfma_f32_16x16x32_bf16 v[42:45], v[158:161], v[196:199], v[42:45]
	v_mfma_f32_16x16x32_bf16 v[34:37], v[150:153], v[204:207], v[34:37]
	v_mfma_f32_16x16x32_bf16 v[26:29], v[158:161], v[204:207], v[26:29]
	v_mfma_f32_16x16x32_bf16 v[18:21], v[150:153], v[212:215], v[18:21]
	v_mfma_f32_16x16x32_bf16 v[10:13], v[158:161], v[212:215], v[10:13]
	v_mfma_f32_16x16x32_bf16 v[62:65], v[154:157], v[192:195], v[62:65]
	v_mfma_f32_16x16x32_bf16 v[58:61], v[162:165], v[192:195], v[58:61]
	v_mfma_f32_16x16x32_bf16 v[50:53], v[154:157], v[200:203], v[50:53]
	v_mfma_f32_16x16x32_bf16 v[42:45], v[162:165], v[200:203], v[42:45]
	v_mfma_f32_16x16x32_bf16 v[34:37], v[154:157], v[208:211], v[34:37]
	v_mfma_f32_16x16x32_bf16 v[26:29], v[162:165], v[208:211], v[26:29]
	v_mfma_f32_16x16x32_bf16 v[18:21], v[154:157], v[216:219], v[18:21]
	v_mfma_f32_16x16x32_bf16 v[10:13], v[162:165], v[216:219], v[10:13]
	v_mfma_f32_16x16x32_bf16 v[54:57], v[166:169], v[188:191], v[54:57]
	v_mfma_f32_16x16x32_bf16 v[46:49], v[180:183], v[188:191], v[46:49]
	v_mfma_f32_16x16x32_bf16 v[38:41], v[166:169], v[196:199], v[38:41]
	v_mfma_f32_16x16x32_bf16 v[30:33], v[180:183], v[196:199], v[30:33]
	v_mfma_f32_16x16x32_bf16 v[22:25], v[166:169], v[204:207], v[22:25]
	v_mfma_f32_16x16x32_bf16 v[14:17], v[180:183], v[204:207], v[14:17]
	v_mfma_f32_16x16x32_bf16 v[6:9], v[166:169], v[212:215], v[6:9]
	v_mfma_f32_16x16x32_bf16 v[2:5], v[180:183], v[212:215], v[2:5]
	v_mfma_f32_16x16x32_bf16 v[54:57], v[170:173], v[192:195], v[54:57]
	v_mfma_f32_16x16x32_bf16 v[46:49], v[184:187], v[192:195], v[46:49]
	v_mfma_f32_16x16x32_bf16 v[38:41], v[170:173], v[200:203], v[38:41]
	v_mfma_f32_16x16x32_bf16 v[30:33], v[184:187], v[200:203], v[30:33]
	v_mfma_f32_16x16x32_bf16 v[22:25], v[170:173], v[208:211], v[22:25]
	v_mfma_f32_16x16x32_bf16 v[14:17], v[184:187], v[208:211], v[14:17]
	v_mfma_f32_16x16x32_bf16 v[6:9], v[170:173], v[216:219], v[6:9]
	v_mfma_f32_16x16x32_bf16 v[2:5], v[184:187], v[216:219], v[2:5]
	s_setprio 0
	s_barrier
; #define PG8_STAGE(bufoff, gbase, voff) do { _Pragma("unroll") for (int _i = 0; _i < 2; ++_i) \
;         __builtin_amdgcn_global_load_lds((const unsigned*)((const char*)(gbase) + (voff)[_i]), (PG8_LAS unsigned*)(lds + (bufoff) + ldsw + _i * 8192), 16, 0, 0); } while (0)
; #define PG8_LDA(dst, b, h) do { _Pragma("unroll") for (int m = 0; m < 4; ++m) _Pragma("unroll") for (int k = 0; k < 2; ++k) dst[m][k] = *(const PG8_LAS bf16x8*)(lds + PG8_SA(b, h) + aoff + m * 2048 + k * 1024); } while (0)
; #define PG8_LDB(dst, b, h) do { _Pragma("unroll") for (int n = 0; n < 2; ++n) _Pragma("unroll") for (int k = 0; k < 2; ++k) dst[n][k] = *(const PG8_LAS bf16x8*)(lds + PG8_SB(b, h) + boff + n * 2048 + k * 1024); } while (0)
; #define PG8_MMA(ai, bj, At, Bt) do { __builtin_amdgcn_s_setprio(1); _Pragma("unroll") for (int m = 0; m < 4; ++m) _Pragma("unroll") for (int n = 0; n < 2; ++n) _Pragma("unroll") for (int k = 0; k < 2; ++k) \
;         acc[ai][bj][m][n] = __builtin_amdgcn_mfma_f32_16x16x32_bf16(Bt[n][k], At[m][k], acc[ai][bj][m][n], 0, 0, 0); __builtin_amdgcn_s_setprio(0); } while (0)
; #define PG8_WAIT_V(n) asm volatile("s_waitcnt vmcnt(" #n ")" ::: "memory")
; #define PG8_WAIT_L(n) asm volatile("s_waitcnt lgkmcnt(" #n ")" ::: "memory")
; #define PG8_BAR __builtin_amdgcn_s_barrier()
; #define PG8_SCHED __builtin_amdgcn_sched_barrier(0)
; template <class Epi, class Sched, bool ALIGN_EPI = false, bool SP2 = false>
; __device__ __forceinline__ void gemm_phase(PG8_LAS unsigned char* lds, const Gemm g, const Sched& S, const Epi& E) {
;     ...
;             PG8_LDB(B0, 1, 0); PG8_LDB(B1, 1, 1); PG8_SCHED; PG8_LDA(At, 1, 0); PG8_STAGE(PG8_SA(0, 1), a2 + hstep, voffA);
;             PG8_WAIT_V(8); PG8_WAIT_L(0); PG8_BAR; PG8_MMA(0, 0, At, B0); PG8_MMA(0, 1, At, B1); PG8_BAR; PG8_SCHED;
	s_add_i32 s49, 0, 0x18000
	v_add_u32_e32 v142, s49, v145
	s_add_i32 s50, 0, 0x1c000
	ds_read_b128 v[150:153], v142
	ds_read_b128 v[154:157], v142 offset:1024
	ds_read_b128 v[158:161], v142 offset:2048
	ds_read_b128 v[162:165], v142 offset:3072
	v_add_u32_e32 v142, s50, v145
	ds_read_b128 v[166:169], v142
	ds_read_b128 v[170:173], v142 offset:1024
	ds_read_b128 v[180:183], v142 offset:2048
	ds_read_b128 v[184:187], v142 offset:3072
	s_add_u32 s28, s28, 0x40000
	s_addc_u32 s29, s29, 0
	s_mov_b32 m0, s38
	v_lshl_add_u64 v[230:231], s[28:29], 0, v[136:137]
	ds_read_b128 v[188:191], v149 offset:32768
	ds_read_b128 v[192:195], v149 offset:33792
	ds_read_b128 v[196:199], v149 offset:34816
	ds_read_b128 v[200:203], v149 offset:35840
	ds_read_b128 v[204:207], v149 offset:36864
	ds_read_b128 v[208:211], v149 offset:37888
	ds_read_b128 v[212:215], v149 offset:38912
	ds_read_b128 v[216:219], v149 offset:39936
	global_load_lds_dwordx4 v[230:231], off
	v_lshl_add_u64 v[230:231], s[28:29], 0, v[132:133]
	s_mov_b32 m0, s39
	s_nop 0
	global_load_lds_dwordx4 v[230:231], off
	s_waitcnt vmcnt(8)
	s_waitcnt lgkmcnt(0)
	s_barrier
	s_setprio 1
	s_waitcnt lgkmcnt(0)
	v_mfma_f32_16x16x32_bf16 v[126:129], v[150:153], v[188:191], v[126:129]
	v_mfma_f32_16x16x32_bf16 v[122:125], v[158:161], v[188:191], v[122:125]
	v_mfma_f32_16x16x32_bf16 v[114:117], v[150:153], v[196:199], v[114:117]
	v_mfma_f32_16x16x32_bf16 v[106:109], v[158:161], v[196:199], v[106:109]
	v_mfma_f32_16x16x32_bf16 v[98:101], v[150:153], v[204:207], v[98:101]
	v_mfma_f32_16x16x32_bf16 v[90:93], v[158:161], v[204:207], v[90:93]
	v_mfma_f32_16x16x32_bf16 v[82:85], v[150:153], v[212:215], v[82:85]
	v_mfma_f32_16x16x32_bf16 v[74:77], v[158:161], v[212:215], v[74:77]
	v_mfma_f32_16x16x32_bf16 v[126:129], v[154:157], v[192:195], v[126:129]
	v_mfma_f32_16x16x32_bf16 v[122:125], v[162:165], v[192:195], v[122:125]
	v_mfma_f32_16x16x32_bf16 v[114:117], v[154:157], v[200:203], v[114:117]
	v_mfma_f32_16x16x32_bf16 v[106:109], v[162:165], v[200:203], v[106:109]
	v_mfma_f32_16x16x32_bf16 v[98:101], v[154:157], v[208:211], v[98:101]
	v_mfma_f32_16x16x32_bf16 v[90:93], v[162:165], v[208:211], v[90:93]
	v_mfma_f32_16x16x32_bf16 v[82:85], v[154:157], v[216:219], v[82:85]
	v_mfma_f32_16x16x32_bf16 v[74:77], v[162:165], v[216:219], v[74:77]
	v_mfma_f32_16x16x32_bf16 v[118:121], v[166:169], v[188:191], v[118:121]
	v_mfma_f32_16x16x32_bf16 v[110:113], v[180:183], v[188:191], v[110:113]
	v_mfma_f32_16x16x32_bf16 v[102:105], v[166:169], v[196:199], v[102:105]
	v_mfma_f32_16x16x32_bf16 v[94:97], v[180:183], v[196:199], v[94:97]
	v_mfma_f32_16x16x32_bf16 v[86:89], v[166:169], v[204:207], v[86:89]
	v_mfma_f32_16x16x32_bf16 v[78:81], v[180:183], v[204:207], v[78:81]
	v_mfma_f32_16x16x32_bf16 v[70:73], v[166:169], v[212:215], v[70:73]
	v_mfma_f32_16x16x32_bf16 v[66:69], v[180:183], v[212:215], v[66:69]
	v_mfma_f32_16x16x32_bf16 v[118:121], v[170:173], v[192:195], v[118:121]
	v_mfma_f32_16x16x32_bf16 v[110:113], v[184:187], v[192:195], v[110:113]
	v_mfma_f32_16x16x32_bf16 v[102:105], v[170:173], v[200:203], v[102:105]
	v_mfma_f32_16x16x32_bf16 v[94:97], v[184:187], v[200:203], v[94:97]
	v_mfma_f32_16x16x32_bf16 v[86:89], v[170:173], v[208:211], v[86:89]
	v_mfma_f32_16x16x32_bf16 v[78:81], v[184:187], v[208:211], v[78:81]
	v_mfma_f32_16x16x32_bf16 v[70:73], v[170:173], v[216:219], v[70:73]
	v_mfma_f32_16x16x32_bf16 v[66:69], v[184:187], v[216:219], v[66:69]
	s_setprio 0
	s_barrier
; #define PG8_STAGE(bufoff, gbase, voff) do { _Pragma("unroll") for (int _i = 0; _i < 2; ++_i) \
;         __builtin_amdgcn_global_load_lds((const unsigned*)((const char*)(gbase) + (voff)[_i]), (PG8_LAS unsigned*)(lds + (bufoff) + ldsw + _i * 8192), 16, 0, 0); } while (0)
; #define PG8_LDA(dst, b, h) do { _Pragma("unroll") for (int m = 0; m < 4; ++m) _Pragma("unroll") for (int k = 0; k < 2; ++k) dst[m][k] = *(const PG8_LAS bf16x8*)(lds + PG8_SA(b, h) + aoff + m * 2048 + k * 1024); } while (0)
; #define PG8_MMA(ai, bj, At, Bt) do { __builtin_amdgcn_s_setprio(1); _Pragma("unroll") for (int m = 0; m < 4; ++m) _Pragma("unroll") for (int n = 0; n < 2; ++n) _Pragma("unroll") for (int k = 0; k < 2; ++k) \
;         acc[ai][bj][m][n] = __builtin_amdgcn_mfma_f32_16x16x32_bf16(Bt[n][k], At[m][k], acc[ai][bj][m][n], 0, 0, 0); __builtin_amdgcn_s_setprio(0); } while (0)
; #define PG8_WAIT_V(n) asm volatile("s_waitcnt vmcnt(" #n ")" ::: "memory")
; #define PG8_WAIT_L(n) asm volatile("s_waitcnt lgkmcnt(" #n ")" ::: "memory")
; #define PG8_BAR __builtin_amdgcn_s_barrier()
; #define PG8_SCHED __builtin_amdgcn_sched_barrier(0)
; template <class Epi, class Sched, bool ALIGN_EPI = false, bool SP2 = false>
; __device__ __forceinline__ void gemm_phase(PG8_LAS unsigned char* lds, const Gemm g, const Sched& S, const Epi& E) {
;     ...
;         for (int t = 0; t < nt; t += 2) {
;             const bool last = (t == nt - 2);
;             const char* a1 = cA + (size_t)(t + 1) * kstep;
;             const char* a2 = last ? nA : cA + (size_t)(t + 2) * kstep; const char* b2 = last ? nB : cB + (size_t)(t + 2) * kstep;
;             const char* a3 = a2 + kstep; const char* b3 = b2 + kstep;
;     ...
;             PG8_LDA(At, 1, 1); PG8_STAGE(PG8_SB(1, 0), b3, voffB); PG8_STAGE(PG8_SB(1, 1), b3 + hstep, voffB); PG8_STAGE(PG8_SA(1, 0), a3, voffA);
;             PG8_WAIT_V(8); PG8_WAIT_L(0); PG8_BAR; PG8_MMA(1, 0, At, B0); PG8_MMA(1, 1, At, B1); PG8_BAR; PG8_SCHED;
	s_add_i32 s28, s49, s35
	v_lshl_add_u64 v[146:147], v[146:147], 0, s[96:97]
	s_mov_b32 m0, s28
	ds_read_b128 v[188:191], v149 offset:49152
	ds_read_b128 v[192:195], v149 offset:50176
	ds_read_b128 v[196:199], v149 offset:51200
	ds_read_b128 v[200:203], v149 offset:52224
	ds_read_b128 v[204:207], v149 offset:53248
	ds_read_b128 v[208:211], v149 offset:54272
	ds_read_b128 v[212:215], v149 offset:55296
	ds_read_b128 v[216:219], v149 offset:56320
	global_load_lds_dwordx4 v[146:147], off
	s_add_i32 m0, s28, 0x2000
	s_add_u32 s26, s26, 0x40080
	v_lshl_add_u64 v[146:147], v[220:221], 0, s[96:97]
	s_addc_u32 s27, s27, 0
	s_add_i32 s28, s50, s35
	global_load_lds_dwordx4 v[146:147], off
	v_lshl_add_u64 v[146:147], s[26:27], 0, v[134:135]
	s_mov_b32 m0, s28
	s_nop 0
	global_load_lds_dwordx4 v[146:147], off
	v_lshl_add_u64 v[146:147], s[26:27], 0, v[130:131]
	s_add_i32 m0, s28, 0x2000
	s_nop 0
	global_load_lds_dwordx4 v[146:147], off
	v_lshl_add_u64 v[146:147], v[222:223], 0, s[96:97]
	s_mov_b32 m0, s42
	s_nop 0
	global_load_lds_dwordx4 v[146:147], off
	v_lshl_add_u64 v[146:147], v[228:229], 0, s[96:97]
	s_mov_b32 m0, s43
	s_nop 0
	global_load_lds_dwordx4 v[146:147], off
	s_waitcnt vmcnt(8)
	s_waitcnt lgkmcnt(0)
	s_barrier
	s_setprio 1
	s_waitcnt lgkmcnt(0)
	v_mfma_f32_16x16x32_bf16 v[62:65], v[150:153], v[188:191], v[62:65]
	v_mfma_f32_16x16x32_bf16 v[58:61], v[158:161], v[188:191], v[58:61]
	v_mfma_f32_16x16x32_bf16 v[50:53], v[150:153], v[196:199], v[50:53]
	v_mfma_f32_16x16x32_bf16 v[42:45], v[158:161], v[196:199], v[42:45]
	v_mfma_f32_16x16x32_bf16 v[34:37], v[150:153], v[204:207], v[34:37]
	v_mfma_f32_16x16x32_bf16 v[26:29], v[158:161], v[204:207], v[26:29]
	v_mfma_f32_16x16x32_bf16 v[18:21], v[150:153], v[212:215], v[18:21]
	v_mfma_f32_16x16x32_bf16 v[10:13], v[158:161], v[212:215], v[10:13]
	v_mfma_f32_16x16x32_bf16 v[62:65], v[154:157], v[192:195], v[62:65]
	v_mfma_f32_16x16x32_bf16 v[58:61], v[162:165], v[192:195], v[58:61]
	v_mfma_f32_16x16x32_bf16 v[50:53], v[154:157], v[200:203], v[50:53]
	v_mfma_f32_16x16x32_bf16 v[42:45], v[162:165], v[200:203], v[42:45]
	v_mfma_f32_16x16x32_bf16 v[34:37], v[154:157], v[208:211], v[34:37]
	v_mfma_f32_16x16x32_bf16 v[26:29], v[162:165], v[208:211], v[26:29]
	v_mfma_f32_16x16x32_bf16 v[18:21], v[154:157], v[216:219], v[18:21]
	v_mfma_f32_16x16x32_bf16 v[10:13], v[162:165], v[216:219], v[10:13]
	v_mfma_f32_16x16x32_bf16 v[54:57], v[166:169], v[188:191], v[54:57]
	v_mfma_f32_16x16x32_bf16 v[46:49], v[180:183], v[188:191], v[46:49]
	v_mfma_f32_16x16x32_bf16 v[38:41], v[166:169], v[196:199], v[38:41]
	v_mfma_f32_16x16x32_bf16 v[30:33], v[180:183], v[196:199], v[30:33]
	v_mfma_f32_16x16x32_bf16 v[22:25], v[166:169], v[204:207], v[22:25]
	v_mfma_f32_16x16x32_bf16 v[14:17], v[180:183], v[204:207], v[14:17]
	v_mfma_f32_16x16x32_bf16 v[6:9], v[166:169], v[212:215], v[6:9]
	v_mfma_f32_16x16x32_bf16 v[2:5], v[180:183], v[212:215], v[2:5]
	v_mfma_f32_16x16x32_bf16 v[54:57], v[170:173], v[192:195], v[54:57]
	v_mfma_f32_16x16x32_bf16 v[46:49], v[184:187], v[192:195], v[46:49]
	v_mfma_f32_16x16x32_bf16 v[38:41], v[170:173], v[200:203], v[38:41]
	v_mfma_f32_16x16x32_bf16 v[30:33], v[184:187], v[200:203], v[30:33]
	v_mfma_f32_16x16x32_bf16 v[22:25], v[170:173], v[208:211], v[22:25]
	v_mfma_f32_16x16x32_bf16 v[14:17], v[184:187], v[208:211], v[14:17]
	v_mfma_f32_16x16x32_bf16 v[6:9], v[170:173], v[216:219], v[6:9]
	v_mfma_f32_16x16x32_bf16 v[2:5], v[184:187], v[216:219], v[2:5]
	s_setprio 0
	s_add_i32 s48, s48, 2
	s_add_u32 s24, s24, 0x100
	s_addc_u32 s25, s25, 0
	s_add_u32 s46, s46, 0x100
	s_addc_u32 s47, s47, 0
	s_add_u32 s26, s24, 0xfffc0080
	s_addc_u32 s27, s25, -1
	s_add_i32 s49, 0, 0x10000
	s_cmp_eq_u32 s48, 12
	s_cselect_b32 s29, s19, s27
	s_cselect_b32 s28, s33, s26
	s_cselect_b32 s27, s17, s47
	s_cselect_b32 s26, s45, s46
	s_add_i32 s52, 0, 0x14000
	s_cmp_gt_u32 s48, 13
	s_cbranch_scc0 .Lrotb_evin
	s_barrier
	s_and_b64 vcc, exec, s[14:15]
	s_cbranch_vccz .LBB0_815
	s_barrier

; template <class Epi, class Sched, bool ALIGN_EPI = false, bool SP2 = false>
; __device__ __forceinline__ void gemm_phase(PG8_LAS unsigned char* lds, const Gemm g, const Sched& S, const Epi& E) {
;     ...
;         const char* nA = has_next ? (const char*)g.A + (size_t)nxt.pm * tstep : cA; const char* nB = has_next ? (const char*)g.Bt + (size_t)nxt.pn * tstep : cB;
;         for (int t = 0; t < nt; t += 2) {
;             const bool last = (t == nt - 2);
;             const char* a1 = cA + (size_t)(t + 1) * kstep;
;             const char* a2 = last ? nA : cA + (size_t)(t + 2) * kstep; const char* b2 = last ? nB : cB + (size_t)(t + 2) * kstep;
;             const char* a3 = a2 + kstep; const char* b3 = b2 + kstep;
.LBB0_1075:
	s_add_u32 s10, s8, 0xfffc0080
	s_addc_u32 s11, s9, -1
	s_add_i32 s56, 0, 0x10000
	s_cmp_eq_u32 s55, 12
	s_cselect_b32 s37, s5, s11
	s_cselect_b32 s36, s25, s10
	s_cselect_b32 s11, s27, s54
	s_cselect_b32 s10, s29, s33
	s_add_i32 s58, 0, 0x14000
	s_branch .Lrot_evout

; #define PG8_STAGE(bufoff, gbase, voff) do { _Pragma("unroll") for (int _i = 0; _i < 2; ++_i) \
;         __builtin_amdgcn_global_load_lds((const unsigned*)((const char*)(gbase) + (voff)[_i]), (PG8_LAS unsigned*)(lds + (bufoff) + ldsw + _i * 8192), 16, 0, 0); } while (0)
; #define PG8_LDA(dst, b, h) do { _Pragma("unroll") for (int m = 0; m < 4; ++m) _Pragma("unroll") for (int k = 0; k < 2; ++k) dst[m][k] = *(const PG8_LAS bf16x8*)(lds + PG8_SA(b, h) + aoff + m * 2048 + k * 1024); } while (0)
; #define PG8_LDB(dst, b, h) do { _Pragma("unroll") for (int n = 0; n < 2; ++n) _Pragma("unroll") for (int k = 0; k < 2; ++k) dst[n][k] = *(const PG8_LAS bf16x8*)(lds + PG8_SB(b, h) + boff + n * 2048 + k * 1024); } while (0)
; #define PG8_MMA(ai, bj, At, Bt) do { __builtin_amdgcn_s_setprio(1); _Pragma("unroll") for (int m = 0; m < 4; ++m) _Pragma("unroll") for (int n = 0; n < 2; ++n) _Pragma("unroll") for (int k = 0; k < 2; ++k) \
;         acc[ai][bj][m][n] = __builtin_amdgcn_mfma_f32_16x16x32_bf16(Bt[n][k], At[m][k], acc[ai][bj][m][n], 0, 0, 0); __builtin_amdgcn_s_setprio(0); } while (0)
; #define PG8_WAIT_V(n) asm volatile("s_waitcnt vmcnt(" #n ")" ::: "memory")
; #define PG8_WAIT_L(n) asm volatile("s_waitcnt lgkmcnt(" #n ")" ::: "memory")
; #define PG8_BAR __builtin_amdgcn_s_barrier()
; #define PG8_SCHED __builtin_amdgcn_sched_barrier(0)
; template <class Epi, class Sched, bool ALIGN_EPI = false, bool SP2 = false>
; __device__ __forceinline__ void gemm_phase(PG8_LAS unsigned char* lds, const Gemm g, const Sched& S, const Epi& E) {
;     ...
;             PG8_LDB(B0, 0, 0); PG8_LDB(B1, 0, 1); PG8_SCHED; PG8_LDA(At, 0, 0); PG8_STAGE(PG8_SA(1, 1), a1 + hstep, voffA);
;             PG8_WAIT_V(8); PG8_WAIT_L(0); PG8_BAR; PG8_MMA(0, 0, At, B0); PG8_MMA(0, 1, At, B1); PG8_BAR; PG8_SCHED;
;     ...
;         for (int a = 0; a < 2; ++a)
; #pragma unroll
;             for (int b = 0; b < 2; ++b)
; #pragma unroll
;                 for (int m = 0; m < 4; ++m)
; #pragma unroll
;                     for (int n = 0; n < 2; ++n) acc[a][b][m][n] = (f32x4){0.f, 0.f, 0.f, 0.f};
.Lrot_evout:
	v_add_u32_e32 v94, s56, v203
	v_add_u32_e32 v134, s58, v203
	ds_read_b128 v[66:69], v94
	ds_read_b128 v[70:73], v94 offset:1024
	ds_read_b128 v[82:85], v94 offset:2048
	ds_read_b128 v[94:97], v94 offset:3072
	ds_read_b128 v[106:109], v134
	ds_read_b128 v[118:121], v134 offset:1024
	ds_read_b128 v[130:133], v134 offset:2048
	ds_read_b128 v[134:137], v134 offset:3072
	v_lshl_add_u64 v[200:201], s[8:9], 0, v[184:185]
	s_add_i32 m0, s43, 0xc000
	ds_read_b128 v[162:165], v204
	ds_read_b128 v[166:169], v204 offset:1024
	ds_read_b128 v[188:191], v204 offset:2048
	ds_read_b128 v[192:195], v204 offset:3072
	ds_read_b128 v[196:199], v204 offset:4096
	ds_read_b128 v[206:209], v204 offset:5120
	ds_read_b128 v[210:213], v204 offset:6144
	ds_read_b128 v[214:217], v204 offset:7168
	global_load_lds_dwordx4 v[200:201], off
	v_lshl_add_u64 v[200:201], s[8:9], 0, v[186:187]
	s_add_i32 m0, s43, 0xe000
	s_nop 0
	global_load_lds_dwordx4 v[200:201], off
	s_cmp_lg_u32 s55, -2
	s_cbranch_scc1 .Levout_noz
	v_mov_b32_e32 v2, 0
	v_mov_b32_e32 v3, v2
	v_mov_b32_e32 v4, v2
	v_mov_b32_e32 v5, v2
	v_mov_b32_e32 v6, v2
	v_mov_b32_e32 v7, v2
	v_mov_b32_e32 v8, v2
	v_mov_b32_e32 v9, v2
	v_mov_b32_e32 v18, v2
	v_mov_b32_e32 v19, v2
	v_mov_b32_e32 v20, v2
	v_mov_b32_e32 v21, v2
	v_mov_b32_e32 v22, v2
	v_mov_b32_e32 v23, v2
	v_mov_b32_e32 v24, v2
	v_mov_b32_e32 v25, v2
	v_mov_b32_e32 v34, v2
	v_mov_b32_e32 v35, v2
	v_mov_b32_e32 v36, v2
	v_mov_b32_e32 v37, v2
	v_mov_b32_e32 v38, v2
	v_mov_b32_e32 v39, v2
	v_mov_b32_e32 v40, v2
	v_mov_b32_e32 v41, v2
	v_mov_b32_e32 v50, v2
	v_mov_b32_e32 v51, v2
	v_mov_b32_e32 v52, v2
	v_mov_b32_e32 v53, v2
	v_mov_b32_e32 v54, v2
	v_mov_b32_e32 v55, v2
	v_mov_b32_e32 v56, v2
	v_mov_b32_e32 v57, v2
	v_mov_b32_e32 v10, v2
	v_mov_b32_e32 v11, v2
	v_mov_b32_e32 v12, v2
	v_mov_b32_e32 v13, v2
	v_mov_b32_e32 v14, v2
	v_mov_b32_e32 v15, v2
	v_mov_b32_e32 v16, v2
	v_mov_b32_e32 v17, v2
	v_mov_b32_e32 v26, v2
	v_mov_b32_e32 v27, v2
	v_mov_b32_e32 v28, v2
	v_mov_b32_e32 v29, v2
	v_mov_b32_e32 v30, v2
	v_mov_b32_e32 v31, v2
	v_mov_b32_e32 v32, v2
	v_mov_b32_e32 v33, v2
	v_mov_b32_e32 v42, v2
	v_mov_b32_e32 v43, v2
	v_mov_b32_e32 v44, v2
	v_mov_b32_e32 v45, v2
	v_mov_b32_e32 v46, v2
	v_mov_b32_e32 v47, v2
	v_mov_b32_e32 v48, v2
	v_mov_b32_e32 v49, v2
	v_mov_b32_e32 v58, v2
	v_mov_b32_e32 v59, v2
	v_mov_b32_e32 v60, v2
	v_mov_b32_e32 v61, v2
	v_mov_b32_e32 v62, v2
	v_mov_b32_e32 v63, v2
	v_mov_b32_e32 v64, v2
	v_mov_b32_e32 v65, v2
	v_mov_b32_e32 v74, v2
	v_mov_b32_e32 v75, v2
	v_mov_b32_e32 v76, v2
	v_mov_b32_e32 v77, v2
	v_mov_b32_e32 v78, v2
	v_mov_b32_e32 v79, v2
	v_mov_b32_e32 v80, v2
	v_mov_b32_e32 v81, v2
	v_mov_b32_e32 v98, v2
	v_mov_b32_e32 v99, v2
	v_mov_b32_e32 v100, v2
	v_mov_b32_e32 v101, v2
	v_mov_b32_e32 v102, v2
	v_mov_b32_e32 v103, v2
	v_mov_b32_e32 v104, v2
	v_mov_b32_e32 v105, v2
	v_mov_b32_e32 v122, v2
	v_mov_b32_e32 v123, v2
	v_mov_b32_e32 v124, v2
	v_mov_b32_e32 v125, v2
	v_mov_b32_e32 v126, v2
	v_mov_b32_e32 v127, v2
	v_mov_b32_e32 v128, v2
	v_mov_b32_e32 v129, v2
	v_mov_b32_e32 v146, v2
	v_mov_b32_e32 v147, v2
	v_mov_b32_e32 v148, v2
	v_mov_b32_e32 v149, v2
	v_mov_b32_e32 v150, v2
	v_mov_b32_e32 v151, v2
	v_mov_b32_e32 v152, v2
	v_mov_b32_e32 v153, v2
	v_mov_b32_e32 v86, v2
	v_mov_b32_e32 v87, v2
	v_mov_b32_e32 v88, v2
	v_mov_b32_e32 v89, v2
	v_mov_b32_e32 v90, v2
	v_mov_b32_e32 v91, v2
	v_mov_b32_e32 v92, v2
	v_mov_b32_e32 v93, v2
	v_mov_b32_e32 v110, v2
	v_mov_b32_e32 v111, v2
	v_mov_b32_e32 v112, v2
	v_mov_b32_e32 v113, v2
	v_mov_b32_e32 v114, v2
	v_mov_b32_e32 v115, v2
	v_mov_b32_e32 v116, v2
	v_mov_b32_e32 v117, v2
	v_mov_b32_e32 v138, v2
	v_mov_b32_e32 v139, v2
	v_mov_b32_e32 v140, v2
	v_mov_b32_e32 v141, v2
	v_mov_b32_e32 v142, v2
	v_mov_b32_e32 v143, v2
	v_mov_b32_e32 v144, v2
	v_mov_b32_e32 v145, v2
	v_mov_b32_e32 v154, v2
	v_mov_b32_e32 v155, v2
	v_mov_b32_e32 v156, v2
	v_mov_b32_e32 v157, v2
	v_mov_b32_e32 v158, v2
	v_mov_b32_e32 v159, v2
	v_mov_b32_e32 v160, v2
	v_mov_b32_e32 v161, v2
.Levout_noz:
	s_waitcnt vmcnt(8)
	s_waitcnt lgkmcnt(0)
	s_barrier
	s_setprio 1
	s_waitcnt lgkmcnt(0)
	v_mfma_f32_16x16x32_bf16 v[158:161], v[66:69], v[162:165], v[158:161]
	v_mfma_f32_16x16x32_bf16 v[154:157], v[82:85], v[162:165], v[154:157]
	v_mfma_f32_16x16x32_bf16 v[142:145], v[66:69], v[188:191], v[142:145]
	v_mfma_f32_16x16x32_bf16 v[138:141], v[82:85], v[188:191], v[138:141]
	v_mfma_f32_16x16x32_bf16 v[114:117], v[66:69], v[196:199], v[114:117]
	v_mfma_f32_16x16x32_bf16 v[110:113], v[82:85], v[196:199], v[110:113]
	v_mfma_f32_16x16x32_bf16 v[90:93], v[66:69], v[210:213], v[90:93]
	v_mfma_f32_16x16x32_bf16 v[86:89], v[82:85], v[210:213], v[86:89]
	v_mfma_f32_16x16x32_bf16 v[158:161], v[70:73], v[166:169], v[158:161]
	v_mfma_f32_16x16x32_bf16 v[154:157], v[94:97], v[166:169], v[154:157]
	v_mfma_f32_16x16x32_bf16 v[142:145], v[70:73], v[192:195], v[142:145]
	v_mfma_f32_16x16x32_bf16 v[138:141], v[94:97], v[192:195], v[138:141]
	v_mfma_f32_16x16x32_bf16 v[114:117], v[70:73], v[206:209], v[114:117]
	v_mfma_f32_16x16x32_bf16 v[110:113], v[94:97], v[206:209], v[110:113]
	v_mfma_f32_16x16x32_bf16 v[90:93], v[70:73], v[214:217], v[90:93]
	v_mfma_f32_16x16x32_bf16 v[86:89], v[94:97], v[214:217], v[86:89]
	v_mfma_f32_16x16x32_bf16 v[150:153], v[106:109], v[162:165], v[150:153]
	v_mfma_f32_16x16x32_bf16 v[146:149], v[130:133], v[162:165], v[146:149]
	v_mfma_f32_16x16x32_bf16 v[126:129], v[106:109], v[188:191], v[126:129]
	v_mfma_f32_16x16x32_bf16 v[122:125], v[130:133], v[188:191], v[122:125]
	v_mfma_f32_16x16x32_bf16 v[102:105], v[106:109], v[196:199], v[102:105]
	v_mfma_f32_16x16x32_bf16 v[98:101], v[130:133], v[196:199], v[98:101]
	v_mfma_f32_16x16x32_bf16 v[78:81], v[106:109], v[210:213], v[78:81]
	v_mfma_f32_16x16x32_bf16 v[74:77], v[130:133], v[210:213], v[74:77]
	v_mfma_f32_16x16x32_bf16 v[150:153], v[118:121], v[166:169], v[150:153]
	v_mfma_f32_16x16x32_bf16 v[146:149], v[134:137], v[166:169], v[146:149]
	v_mfma_f32_16x16x32_bf16 v[126:129], v[118:121], v[192:195], v[126:129]
	v_mfma_f32_16x16x32_bf16 v[122:125], v[134:137], v[192:195], v[122:125]
	v_mfma_f32_16x16x32_bf16 v[102:105], v[118:121], v[206:209], v[102:105]
	v_mfma_f32_16x16x32_bf16 v[98:101], v[134:137], v[206:209], v[98:101]
	v_mfma_f32_16x16x32_bf16 v[78:81], v[118:121], v[214:217], v[78:81]
	v_mfma_f32_16x16x32_bf16 v[74:77], v[134:137], v[214:217], v[74:77]
	s_setprio 0
	s_barrier
; #define PG8_STAGE(bufoff, gbase, voff) do { _Pragma("unroll") for (int _i = 0; _i < 2; ++_i) \
;         __builtin_amdgcn_global_load_lds((const unsigned*)((const char*)(gbase) + (voff)[_i]), (PG8_LAS unsigned*)(lds + (bufoff) + ldsw + _i * 8192), 16, 0, 0); } while (0)
; #define PG8_LDA(dst, b, h) do { _Pragma("unroll") for (int m = 0; m < 4; ++m) _Pragma("unroll") for (int k = 0; k < 2; ++k) dst[m][k] = *(const PG8_LAS bf16x8*)(lds + PG8_SA(b, h) + aoff + m * 2048 + k * 1024); } while (0)
; #define PG8_LDB(dst, b, h) do { _Pragma("unroll") for (int n = 0; n < 2; ++n) _Pragma("unroll") for (int k = 0; k < 2; ++k) dst[n][k] = *(const PG8_LAS bf16x8*)(lds + PG8_SB(b, h) + boff + n * 2048 + k * 1024); } while (0)
; #define PG8_MMA(ai, bj, At, Bt) do { __builtin_amdgcn_s_setprio(1); _Pragma("unroll") for (int m = 0; m < 4; ++m) _Pragma("unroll") for (int n = 0; n < 2; ++n) _Pragma("unroll") for (int k = 0; k < 2; ++k) \
;         acc[ai][bj][m][n] = __builtin_amdgcn_mfma_f32_16x16x32_bf16(Bt[n][k], At[m][k], acc[ai][bj][m][n], 0, 0, 0); __builtin_amdgcn_s_setprio(0); } while (0)
; #define PG8_WAIT_V(n) asm volatile("s_waitcnt vmcnt(" #n ")" ::: "memory")
; #define PG8_WAIT_L(n) asm volatile("s_waitcnt lgkmcnt(" #n ")" ::: "memory")
; #define PG8_BAR __builtin_amdgcn_s_barrier()
; #define PG8_SCHED __builtin_amdgcn_sched_barrier(0)
; template <class Epi, class Sched, bool ALIGN_EPI = false, bool SP2 = false>
; __device__ __forceinline__ void gemm_phase(PG8_LAS unsigned char* lds, const Gemm g, const Sched& S, const Epi& E) {
;     ...
;             PG8_LDA(At, 0, 1); PG8_STAGE(PG8_SB(0, 0), b2, voffB); PG8_STAGE(PG8_SB(0, 1), b2 + hstep, voffB); PG8_STAGE(PG8_SA(0, 0), a2, voffA);
;             PG8_WAIT_V(8); PG8_WAIT_L(0); PG8_BAR; PG8_MMA(1, 0, At, B0); PG8_MMA(1, 1, At, B1); PG8_BAR; PG8_SCHED;
;             PG8_LDB(B0, 1, 0); PG8_LDB(B1, 1, 1); PG8_SCHED; PG8_LDA(At, 1, 0); PG8_STAGE(PG8_SA(0, 1), a2 + hstep, voffA);
;             PG8_WAIT_V(8); PG8_WAIT_L(0); PG8_BAR; PG8_MMA(0, 0, At, B0); PG8_MMA(0, 1, At, B1); PG8_BAR; PG8_SCHED;
	s_add_i32 s56, s56, s42
	v_lshl_add_u64 v[200:201], s[10:11], 0, v[180:181]
	s_mov_b32 m0, s56
	ds_read_b128 v[162:165], v204 offset:16384
	ds_read_b128 v[166:169], v204 offset:17408
	ds_read_b128 v[188:191], v204 offset:18432
	ds_read_b128 v[192:195], v204 offset:19456
	ds_read_b128 v[196:199], v204 offset:20480
	ds_read_b128 v[206:209], v204 offset:21504
	ds_read_b128 v[210:213], v204 offset:22528
	ds_read_b128 v[214:217], v204 offset:23552
	global_load_lds_dwordx4 v[200:201], off
	s_add_i32 m0, s56, 0x2000
	s_add_u32 s56, s10, 0x40000
	v_lshl_add_u64 v[218:219], s[10:11], 0, v[170:171]
	s_addc_u32 s57, s11, 0
	s_add_i32 s58, s58, s42
	global_load_lds_dwordx4 v[218:219], off
	v_lshl_add_u64 v[220:221], s[56:57], 0, v[180:181]
	s_mov_b32 m0, s58
	v_lshl_add_u64 v[222:223], s[36:37], 0, v[172:173]
	global_load_lds_dwordx4 v[220:221], off
	v_lshl_add_u64 v[220:221], s[56:57], 0, v[170:171]
	s_add_i32 m0, s58, 0x2000
	s_nop 0
	global_load_lds_dwordx4 v[220:221], off
	v_lshl_add_u64 v[220:221], s[36:37], 0, v[182:183]
	s_mov_b32 m0, s43
	s_nop 0
	global_load_lds_dwordx4 v[220:221], off
	s_mov_b32 m0, s44
	s_nop 0
	global_load_lds_dwordx4 v[222:223], off
	s_waitcnt vmcnt(8)
	s_waitcnt lgkmcnt(0)
	s_barrier
	s_setprio 1
	s_waitcnt lgkmcnt(0)
	v_mfma_f32_16x16x32_bf16 v[62:65], v[66:69], v[162:165], v[62:65]
	v_mfma_f32_16x16x32_bf16 v[58:61], v[82:85], v[162:165], v[58:61]
	v_mfma_f32_16x16x32_bf16 v[46:49], v[66:69], v[188:191], v[46:49]
	v_mfma_f32_16x16x32_bf16 v[42:45], v[82:85], v[188:191], v[42:45]
	v_mfma_f32_16x16x32_bf16 v[30:33], v[66:69], v[196:199], v[30:33]
	v_mfma_f32_16x16x32_bf16 v[26:29], v[82:85], v[196:199], v[26:29]
	v_mfma_f32_16x16x32_bf16 v[14:17], v[66:69], v[210:213], v[14:17]
	v_mfma_f32_16x16x32_bf16 v[10:13], v[82:85], v[210:213], v[10:13]
	v_mfma_f32_16x16x32_bf16 v[62:65], v[70:73], v[166:169], v[62:65]
	v_mfma_f32_16x16x32_bf16 v[58:61], v[94:97], v[166:169], v[58:61]
	v_mfma_f32_16x16x32_bf16 v[46:49], v[70:73], v[192:195], v[46:49]
	v_mfma_f32_16x16x32_bf16 v[42:45], v[94:97], v[192:195], v[42:45]
	v_mfma_f32_16x16x32_bf16 v[30:33], v[70:73], v[206:209], v[30:33]
	v_mfma_f32_16x16x32_bf16 v[26:29], v[94:97], v[206:209], v[26:29]
	v_mfma_f32_16x16x32_bf16 v[14:17], v[70:73], v[214:217], v[14:17]
	v_mfma_f32_16x16x32_bf16 v[10:13], v[94:97], v[214:217], v[10:13]
	v_mfma_f32_16x16x32_bf16 v[54:57], v[106:109], v[162:165], v[54:57]
	v_mfma_f32_16x16x32_bf16 v[50:53], v[130:133], v[162:165], v[50:53]
	v_mfma_f32_16x16x32_bf16 v[38:41], v[106:109], v[188:191], v[38:41]
	v_mfma_f32_16x16x32_bf16 v[34:37], v[130:133], v[188:191], v[34:37]
	v_mfma_f32_16x16x32_bf16 v[22:25], v[106:109], v[196:199], v[22:25]
	v_mfma_f32_16x16x32_bf16 v[18:21], v[130:133], v[196:199], v[18:21]
	v_mfma_f32_16x16x32_bf16 v[6:9], v[106:109], v[210:213], v[6:9]
	v_mfma_f32_16x16x32_bf16 v[2:5], v[130:133], v[210:213], v[2:5]
	v_mfma_f32_16x16x32_bf16 v[54:57], v[118:121], v[166:169], v[54:57]
	v_mfma_f32_16x16x32_bf16 v[50:53], v[134:137], v[166:169], v[50:53]
	v_mfma_f32_16x16x32_bf16 v[38:41], v[118:121], v[192:195], v[38:41]
	v_mfma_f32_16x16x32_bf16 v[34:37], v[134:137], v[192:195], v[34:37]
	v_mfma_f32_16x16x32_bf16 v[22:25], v[118:121], v[206:209], v[22:25]
	v_mfma_f32_16x16x32_bf16 v[18:21], v[134:137], v[206:209], v[18:21]
	v_mfma_f32_16x16x32_bf16 v[6:9], v[118:121], v[214:217], v[6:9]
	v_mfma_f32_16x16x32_bf16 v[2:5], v[134:137], v[214:217], v[2:5]
	s_setprio 0
	s_barrier
	s_add_i32 s56, 0, 0x18000
	s_add_i32 s57, 0, 0x1c000
	v_add_u32_e32 v94, s56, v203
	v_add_u32_e32 v134, s57, v203
	ds_read_b128 v[66:69], v94
	ds_read_b128 v[70:73], v94 offset:1024
	ds_read_b128 v[82:85], v94 offset:2048
	ds_read_b128 v[94:97], v94 offset:3072
	ds_read_b128 v[106:109], v134
	ds_read_b128 v[118:121], v134 offset:1024
	ds_read_b128 v[130:133], v134 offset:2048
	ds_read_b128 v[134:137], v134 offset:3072
	s_add_u32 s36, s36, 0x40000
	s_addc_u32 s37, s37, 0
	s_mov_b32 m0, s45
	v_lshl_add_u64 v[228:229], s[36:37], 0, v[182:183]
	ds_read_b128 v[162:165], v204 offset:32768
	ds_read_b128 v[166:169], v204 offset:33792
	ds_read_b128 v[188:191], v204 offset:34816
	ds_read_b128 v[192:195], v204 offset:35840
	ds_read_b128 v[196:199], v204 offset:36864
	ds_read_b128 v[206:209], v204 offset:37888
	ds_read_b128 v[210:213], v204 offset:38912
	ds_read_b128 v[214:217], v204 offset:39936
	global_load_lds_dwordx4 v[228:229], off
	v_lshl_add_u64 v[228:229], s[36:37], 0, v[172:173]
	s_mov_b32 m0, s46
	s_nop 0
	global_load_lds_dwordx4 v[228:229], off
	s_waitcnt vmcnt(8)
	s_waitcnt lgkmcnt(0)
	s_barrier
; #define PG8_STAGE(bufoff, gbase, voff) do { _Pragma("unroll") for (int _i = 0; _i < 2; ++_i) \
;         __builtin_amdgcn_global_load_lds((const unsigned*)((const char*)(gbase) + (voff)[_i]), (PG8_LAS unsigned*)(lds + (bufoff) + ldsw + _i * 8192), 16, 0, 0); } while (0)
; #define PG8_LDA(dst, b, h) do { _Pragma("unroll") for (int m = 0; m < 4; ++m) _Pragma("unroll") for (int k = 0; k < 2; ++k) dst[m][k] = *(const PG8_LAS bf16x8*)(lds + PG8_SA(b, h) + aoff + m * 2048 + k * 1024); } while (0)
; #define PG8_MMA(ai, bj, At, Bt) do { __builtin_amdgcn_s_setprio(1); _Pragma("unroll") for (int m = 0; m < 4; ++m) _Pragma("unroll") for (int n = 0; n < 2; ++n) _Pragma("unroll") for (int k = 0; k < 2; ++k) \
;         acc[ai][bj][m][n] = __builtin_amdgcn_mfma_f32_16x16x32_bf16(Bt[n][k], At[m][k], acc[ai][bj][m][n], 0, 0, 0); __builtin_amdgcn_s_setprio(0); } while (0)
; #define PG8_WAIT_V(n) asm volatile("s_waitcnt vmcnt(" #n ")" ::: "memory")
; #define PG8_WAIT_L(n) asm volatile("s_waitcnt lgkmcnt(" #n ")" ::: "memory")
; #define PG8_BAR __builtin_amdgcn_s_barrier()
; #define PG8_SCHED __builtin_amdgcn_sched_barrier(0)
; template <class Epi, class Sched, bool ALIGN_EPI = false, bool SP2 = false>
; __device__ __forceinline__ void gemm_phase(PG8_LAS unsigned char* lds, const Gemm g, const Sched& S, const Epi& E) {
;     ...
;         for (int t = 0; t < nt; t += 2) {
;             const bool last = (t == nt - 2);
;             const char* a1 = cA + (size_t)(t + 1) * kstep;
;             const char* a2 = last ? nA : cA + (size_t)(t + 2) * kstep; const char* b2 = last ? nB : cB + (size_t)(t + 2) * kstep;
;             const char* a3 = a2 + kstep; const char* b3 = b2 + kstep;
;     ...
;             PG8_WAIT_V(8); PG8_WAIT_L(0); PG8_BAR; PG8_MMA(0, 0, At, B0); PG8_MMA(0, 1, At, B1); PG8_BAR; PG8_SCHED;
;             PG8_LDA(At, 1, 1); PG8_STAGE(PG8_SB(1, 0), b3, voffB); PG8_STAGE(PG8_SB(1, 1), b3 + hstep, voffB); PG8_STAGE(PG8_SA(1, 0), a3, voffA);
;             PG8_WAIT_V(8); PG8_WAIT_L(0); PG8_BAR; PG8_MMA(1, 0, At, B0); PG8_MMA(1, 1, At, B1); PG8_BAR; PG8_SCHED;
	s_setprio 1
	s_waitcnt lgkmcnt(0)
	v_mfma_f32_16x16x32_bf16 v[158:161], v[66:69], v[162:165], v[158:161]
	v_mfma_f32_16x16x32_bf16 v[154:157], v[82:85], v[162:165], v[154:157]
	v_mfma_f32_16x16x32_bf16 v[142:145], v[66:69], v[188:191], v[142:145]
	v_mfma_f32_16x16x32_bf16 v[138:141], v[82:85], v[188:191], v[138:141]
	v_mfma_f32_16x16x32_bf16 v[114:117], v[66:69], v[196:199], v[114:117]
	v_mfma_f32_16x16x32_bf16 v[110:113], v[82:85], v[196:199], v[110:113]
	v_mfma_f32_16x16x32_bf16 v[90:93], v[66:69], v[210:213], v[90:93]
	v_mfma_f32_16x16x32_bf16 v[86:89], v[82:85], v[210:213], v[86:89]
	v_mfma_f32_16x16x32_bf16 v[158:161], v[70:73], v[166:169], v[158:161]
	v_mfma_f32_16x16x32_bf16 v[154:157], v[94:97], v[166:169], v[154:157]
	v_mfma_f32_16x16x32_bf16 v[142:145], v[70:73], v[192:195], v[142:145]
	v_mfma_f32_16x16x32_bf16 v[138:141], v[94:97], v[192:195], v[138:141]
	v_mfma_f32_16x16x32_bf16 v[114:117], v[70:73], v[206:209], v[114:117]
	v_mfma_f32_16x16x32_bf16 v[110:113], v[94:97], v[206:209], v[110:113]
	v_mfma_f32_16x16x32_bf16 v[90:93], v[70:73], v[214:217], v[90:93]
	v_mfma_f32_16x16x32_bf16 v[86:89], v[94:97], v[214:217], v[86:89]
	v_mfma_f32_16x16x32_bf16 v[150:153], v[106:109], v[162:165], v[150:153]
	v_mfma_f32_16x16x32_bf16 v[146:149], v[130:133], v[162:165], v[146:149]
	v_mfma_f32_16x16x32_bf16 v[126:129], v[106:109], v[188:191], v[126:129]
	v_mfma_f32_16x16x32_bf16 v[122:125], v[130:133], v[188:191], v[122:125]
	v_mfma_f32_16x16x32_bf16 v[102:105], v[106:109], v[196:199], v[102:105]
	v_mfma_f32_16x16x32_bf16 v[98:101], v[130:133], v[196:199], v[98:101]
	v_mfma_f32_16x16x32_bf16 v[78:81], v[106:109], v[210:213], v[78:81]
	v_mfma_f32_16x16x32_bf16 v[74:77], v[130:133], v[210:213], v[74:77]
	v_mfma_f32_16x16x32_bf16 v[150:153], v[118:121], v[166:169], v[150:153]
	v_mfma_f32_16x16x32_bf16 v[146:149], v[134:137], v[166:169], v[146:149]
	v_mfma_f32_16x16x32_bf16 v[126:129], v[118:121], v[192:195], v[126:129]
	v_mfma_f32_16x16x32_bf16 v[122:125], v[134:137], v[192:195], v[122:125]
	v_mfma_f32_16x16x32_bf16 v[102:105], v[118:121], v[206:209], v[102:105]
	v_mfma_f32_16x16x32_bf16 v[98:101], v[134:137], v[206:209], v[98:101]
	v_mfma_f32_16x16x32_bf16 v[78:81], v[118:121], v[214:217], v[78:81]
	v_mfma_f32_16x16x32_bf16 v[74:77], v[134:137], v[214:217], v[74:77]
	s_setprio 0
	s_barrier
	s_add_i32 s36, s56, s42
	v_lshl_add_u64 v[200:201], v[200:201], 0, s[96:97]
	s_mov_b32 m0, s36
	ds_read_b128 v[162:165], v204 offset:49152
	ds_read_b128 v[166:169], v204 offset:50176
	ds_read_b128 v[188:191], v204 offset:51200
	ds_read_b128 v[192:195], v204 offset:52224
	ds_read_b128 v[196:199], v204 offset:53248
	ds_read_b128 v[206:209], v204 offset:54272
	ds_read_b128 v[210:213], v204 offset:55296
	ds_read_b128 v[214:217], v204 offset:56320
	global_load_lds_dwordx4 v[200:201], off
	s_add_i32 m0, s36, 0x2000
	s_add_u32 s10, s10, 0x40080
	v_lshl_add_u64 v[200:201], v[218:219], 0, s[96:97]
	s_addc_u32 s11, s11, 0
	s_add_i32 s36, s57, s42
	global_load_lds_dwordx4 v[200:201], off
	v_lshl_add_u64 v[200:201], s[10:11], 0, v[180:181]
	s_mov_b32 m0, s36
	s_nop 0
	global_load_lds_dwordx4 v[200:201], off
	v_lshl_add_u64 v[200:201], s[10:11], 0, v[170:171]
	s_add_i32 m0, s36, 0x2000
	s_nop 0
	global_load_lds_dwordx4 v[200:201], off
	v_lshl_add_u64 v[200:201], v[220:221], 0, s[96:97]
	s_mov_b32 m0, s50
	s_nop 0
	global_load_lds_dwordx4 v[200:201], off
	v_lshl_add_u64 v[200:201], v[222:223], 0, s[96:97]
	s_mov_b32 m0, s51
	s_nop 0
	global_load_lds_dwordx4 v[200:201], off
	s_waitcnt vmcnt(8)
	s_waitcnt lgkmcnt(0)
	s_barrier
	s_setprio 1
	s_waitcnt lgkmcnt(0)
	v_mfma_f32_16x16x32_bf16 v[62:65], v[66:69], v[162:165], v[62:65]
	v_mfma_f32_16x16x32_bf16 v[58:61], v[82:85], v[162:165], v[58:61]
	v_mfma_f32_16x16x32_bf16 v[46:49], v[66:69], v[188:191], v[46:49]
	v_mfma_f32_16x16x32_bf16 v[42:45], v[82:85], v[188:191], v[42:45]
	v_mfma_f32_16x16x32_bf16 v[30:33], v[66:69], v[196:199], v[30:33]
	v_mfma_f32_16x16x32_bf16 v[26:29], v[82:85], v[196:199], v[26:29]
	v_mfma_f32_16x16x32_bf16 v[14:17], v[66:69], v[210:213], v[14:17]
	v_mfma_f32_16x16x32_bf16 v[10:13], v[82:85], v[210:213], v[10:13]
	v_mfma_f32_16x16x32_bf16 v[62:65], v[70:73], v[166:169], v[62:65]
	v_mfma_f32_16x16x32_bf16 v[58:61], v[94:97], v[166:169], v[58:61]
	v_mfma_f32_16x16x32_bf16 v[46:49], v[70:73], v[192:195], v[46:49]
	v_mfma_f32_16x16x32_bf16 v[42:45], v[94:97], v[192:195], v[42:45]
	v_mfma_f32_16x16x32_bf16 v[30:33], v[70:73], v[206:209], v[30:33]
	v_mfma_f32_16x16x32_bf16 v[26:29], v[94:97], v[206:209], v[26:29]
	v_mfma_f32_16x16x32_bf16 v[14:17], v[70:73], v[214:217], v[14:17]
	v_mfma_f32_16x16x32_bf16 v[10:13], v[94:97], v[214:217], v[10:13]
	v_mfma_f32_16x16x32_bf16 v[54:57], v[106:109], v[162:165], v[54:57]
	v_mfma_f32_16x16x32_bf16 v[50:53], v[130:133], v[162:165], v[50:53]
	v_mfma_f32_16x16x32_bf16 v[38:41], v[106:109], v[188:191], v[38:41]
	v_mfma_f32_16x16x32_bf16 v[34:37], v[130:133], v[188:191], v[34:37]
	v_mfma_f32_16x16x32_bf16 v[22:25], v[106:109], v[196:199], v[22:25]
	v_mfma_f32_16x16x32_bf16 v[18:21], v[130:133], v[196:199], v[18:21]
	v_mfma_f32_16x16x32_bf16 v[6:9], v[106:109], v[210:213], v[6:9]
	v_mfma_f32_16x16x32_bf16 v[2:5], v[130:133], v[210:213], v[2:5]
	v_mfma_f32_16x16x32_bf16 v[54:57], v[118:121], v[166:169], v[54:57]
	v_mfma_f32_16x16x32_bf16 v[50:53], v[134:137], v[166:169], v[50:53]
	v_mfma_f32_16x16x32_bf16 v[38:41], v[118:121], v[192:195], v[38:41]
	v_mfma_f32_16x16x32_bf16 v[34:37], v[134:137], v[192:195], v[34:37]
	v_mfma_f32_16x16x32_bf16 v[22:25], v[118:121], v[206:209], v[22:25]
	v_mfma_f32_16x16x32_bf16 v[18:21], v[134:137], v[206:209], v[18:21]
	v_mfma_f32_16x16x32_bf16 v[6:9], v[118:121], v[214:217], v[6:9]
	v_mfma_f32_16x16x32_bf16 v[2:5], v[134:137], v[214:217], v[2:5]
	s_setprio 0
	s_add_i32 s55, s55, 2
	s_add_u32 s8, s8, 0x100
	s_addc_u32 s9, s9, 0
	s_add_u32 s33, s33, 0x100
	s_addc_u32 s54, s54, 0
	s_add_u32 s10, s8, 0xfffc0080
	s_addc_u32 s11, s9, -1
	s_add_i32 s56, 0, 0x10000
	s_cmp_eq_u32 s55, 12
	s_cselect_b32 s37, s5, s11
	s_cselect_b32 s36, s25, s10
	s_cselect_b32 s11, s27, s54
	s_cselect_b32 s10, s29, s33
	s_add_i32 s58, 0, 0x14000
	s_cmp_gt_u32 s55, 13
	s_cbranch_scc0 .Lrotb_evout
	s_barrier
	s_and_b64 vcc, exec, s[20:21]
	s_cbranch_vccz .LBB0_1078
	s_barrier

; template <class Epi, class Sched, bool ALIGN_EPI = false, bool SP2 = false>
; __device__ __forceinline__ void gemm_phase(PG8_LAS unsigned char* lds, const Gemm g, const Sched& S, const Epi& E) {
;     ...
;         const char* nA = has_next ? (const char*)g.A + (size_t)nxt.pm * tstep : cA; const char* nB = has_next ? (const char*)g.Bt + (size_t)nxt.pn * tstep : cB;
;         for (int t = 0; t < nt; t += 2) {
;             const bool last = (t == nt - 2);
;             const char* a1 = cA + (size_t)(t + 1) * kstep;
;             const char* a2 = last ? nA : cA + (size_t)(t + 2) * kstep; const char* b2 = last ? nB : cB + (size_t)(t + 2) * kstep;
;             const char* a3 = a2 + kstep; const char* b3 = b2 + kstep;
.LBB0_1247:
	s_add_u32 s44, s8, 0xfffc0080
	s_addc_u32 s45, s9, -1
	s_add_i32 s69, 0, 0x10000
	s_cmp_eq_u32 s68, 12
	s_cselect_b32 s47, s37, s45
	s_cselect_b32 s46, s43, s44
	s_cselect_b32 s45, s35, s67
	s_cselect_b32 s44, s65, s66
	s_add_i32 s72, 0, 0x14000
	s_branch .Lrot_ffin

; #define PG8_STAGE(bufoff, gbase, voff) do { _Pragma("unroll") for (int _i = 0; _i < 2; ++_i) \
;         __builtin_amdgcn_global_load_lds((const unsigned*)((const char*)(gbase) + (voff)[_i]), (PG8_LAS unsigned*)(lds + (bufoff) + ldsw + _i * 8192), 16, 0, 0); } while (0)
; #define PG8_LDA(dst, b, h) do { _Pragma("unroll") for (int m = 0; m < 4; ++m) _Pragma("unroll") for (int k = 0; k < 2; ++k) dst[m][k] = *(const PG8_LAS bf16x8*)(lds + PG8_SA(b, h) + aoff + m * 2048 + k * 1024); } while (0)
; #define PG8_LDB(dst, b, h) do { _Pragma("unroll") for (int n = 0; n < 2; ++n) _Pragma("unroll") for (int k = 0; k < 2; ++k) dst[n][k] = *(const PG8_LAS bf16x8*)(lds + PG8_SB(b, h) + boff + n * 2048 + k * 1024); } while (0)
; #define PG8_SCHED __builtin_amdgcn_sched_barrier(0)
; template <class Epi, class Sched, bool ALIGN_EPI = false, bool SP2 = false>
; __device__ __forceinline__ void gemm_phase(PG8_LAS unsigned char* lds, const Gemm g, const Sched& S, const Epi& E) {
;     ...
;         for (int t = 0; t < nt; t += 2) {
;             const bool last = (t == nt - 2);
;             const char* a1 = cA + (size_t)(t + 1) * kstep;
;             const char* a2 = last ? nA : cA + (size_t)(t + 2) * kstep; const char* b2 = last ? nB : cB + (size_t)(t + 2) * kstep;
;             const char* a3 = a2 + kstep; const char* b3 = b2 + kstep;
;             if (last && has_next) S.a_ready(nxt);
;             if constexpr (SP2) {
;             PG8_LDB(B0, 0, 0); PG8_LDB(B1, 0, 1); PG8_SCHED; PG8_LDA(At, 0, 0); PG8_STAGE(PG8_SA(1, 1), a1 + hstep, voffA);
.Lrot_ffin:
	s_cmp_lg_u32 s68, 0
	s_cbranch_scc1 .Lffin_nopf
	s_cmp_lt_u32 s52, 0x1000
	s_cbranch_scc0 .Lffin_pf_w
	s_lshl_b32 s98, s42, 12
	s_add_u32 s98, s12, s98
	s_addc_u32 s99, s13, 0
	v_lshlrev_b32_e32 v232, 4, v174
	s_add_i32 m0, s52, 0x21000
	s_nop 0
	global_load_lds_dwordx4 v232, s[98:99]
	s_branch .Lffin_nopf

; #define PG8_STAGE(bufoff, gbase, voff) do { _Pragma("unroll") for (int _i = 0; _i < 2; ++_i) \
;         __builtin_amdgcn_global_load_lds((const unsigned*)((const char*)(gbase) + (voff)[_i]), (PG8_LAS unsigned*)(lds + (bufoff) + ldsw + _i * 8192), 16, 0, 0); } while (0)
; #define PG8_LDA(dst, b, h) do { _Pragma("unroll") for (int m = 0; m < 4; ++m) _Pragma("unroll") for (int k = 0; k < 2; ++k) dst[m][k] = *(const PG8_LAS bf16x8*)(lds + PG8_SA(b, h) + aoff + m * 2048 + k * 1024); } while (0)
; #define PG8_LDB(dst, b, h) do { _Pragma("unroll") for (int n = 0; n < 2; ++n) _Pragma("unroll") for (int k = 0; k < 2; ++k) dst[n][k] = *(const PG8_LAS bf16x8*)(lds + PG8_SB(b, h) + boff + n * 2048 + k * 1024); } while (0)
; #define PG8_MMA(ai, bj, At, Bt) do { __builtin_amdgcn_s_setprio(1); _Pragma("unroll") for (int m = 0; m < 4; ++m) _Pragma("unroll") for (int n = 0; n < 2; ++n) _Pragma("unroll") for (int k = 0; k < 2; ++k) \
;         acc[ai][bj][m][n] = __builtin_amdgcn_mfma_f32_16x16x32_bf16(Bt[n][k], At[m][k], acc[ai][bj][m][n], 0, 0, 0); __builtin_amdgcn_s_setprio(0); } while (0)
; #define PG8_WAIT_V(n) asm volatile("s_waitcnt vmcnt(" #n ")" ::: "memory")
; #define PG8_WAIT_L(n) asm volatile("s_waitcnt lgkmcnt(" #n ")" ::: "memory")
; #define PG8_BAR __builtin_amdgcn_s_barrier()
; #define PG8_SCHED __builtin_amdgcn_sched_barrier(0)
; template <class Epi, class Sched, bool ALIGN_EPI = false, bool SP2 = false>
; __device__ __forceinline__ void gemm_phase(PG8_LAS unsigned char* lds, const Gemm g, const Sched& S, const Epi& E) {
;     ...
;             PG8_WAIT_V(8); PG8_WAIT_L(0); PG8_BAR; PG8_MMA(1, 0, At, B0); PG8_MMA(1, 1, At, B1); PG8_BAR; PG8_SCHED;
;             PG8_LDB(B0, 1, 0); PG8_LDB(B1, 1, 1); PG8_SCHED; PG8_LDA(At, 1, 0); PG8_STAGE(PG8_SA(0, 1), a2 + hstep, voffA);
;             PG8_WAIT_V(8); PG8_WAIT_L(0); PG8_BAR; PG8_MMA(0, 0, At, B0); PG8_MMA(0, 1, At, B1); PG8_BAR; PG8_SCHED;
.Lffin_wd:
	s_waitcnt lgkmcnt(0)
	s_barrier
	s_setprio 1
	s_waitcnt lgkmcnt(0)
	v_mfma_f32_16x16x32_bf16 v[62:65], v[106:109], v[162:165], v[62:65]
	v_mfma_f32_16x16x32_bf16 v[58:61], v[114:117], v[162:165], v[58:61]
	v_mfma_f32_16x16x32_bf16 v[46:49], v[106:109], v[170:173], v[46:49]
	v_mfma_f32_16x16x32_bf16 v[42:45], v[114:117], v[170:173], v[42:45]
	v_mfma_f32_16x16x32_bf16 v[30:33], v[106:109], v[196:199], v[30:33]
	v_mfma_f32_16x16x32_bf16 v[26:29], v[114:117], v[196:199], v[26:29]
	v_mfma_f32_16x16x32_bf16 v[14:17], v[106:109], v[204:207], v[14:17]
	v_mfma_f32_16x16x32_bf16 v[10:13], v[114:117], v[204:207], v[10:13]
	v_mfma_f32_16x16x32_bf16 v[62:65], v[110:113], v[166:169], v[62:65]
	v_mfma_f32_16x16x32_bf16 v[58:61], v[118:121], v[166:169], v[58:61]
	v_mfma_f32_16x16x32_bf16 v[46:49], v[110:113], v[192:195], v[46:49]
	v_mfma_f32_16x16x32_bf16 v[42:45], v[118:121], v[192:195], v[42:45]
	v_mfma_f32_16x16x32_bf16 v[30:33], v[110:113], v[200:203], v[30:33]
	v_mfma_f32_16x16x32_bf16 v[26:29], v[118:121], v[200:203], v[26:29]
	v_mfma_f32_16x16x32_bf16 v[14:17], v[110:113], v[208:211], v[14:17]
	v_mfma_f32_16x16x32_bf16 v[10:13], v[118:121], v[208:211], v[10:13]
	v_mfma_f32_16x16x32_bf16 v[54:57], v[122:125], v[162:165], v[54:57]
	v_mfma_f32_16x16x32_bf16 v[50:53], v[130:133], v[162:165], v[50:53]
	v_mfma_f32_16x16x32_bf16 v[38:41], v[122:125], v[170:173], v[38:41]
	v_mfma_f32_16x16x32_bf16 v[34:37], v[130:133], v[170:173], v[34:37]
	v_mfma_f32_16x16x32_bf16 v[22:25], v[122:125], v[196:199], v[22:25]
	v_mfma_f32_16x16x32_bf16 v[18:21], v[130:133], v[196:199], v[18:21]
	v_mfma_f32_16x16x32_bf16 v[6:9], v[122:125], v[204:207], v[6:9]
	v_mfma_f32_16x16x32_bf16 v[2:5], v[130:133], v[204:207], v[2:5]
	v_mfma_f32_16x16x32_bf16 v[54:57], v[126:129], v[166:169], v[54:57]
	v_mfma_f32_16x16x32_bf16 v[50:53], v[134:137], v[166:169], v[50:53]
	v_mfma_f32_16x16x32_bf16 v[38:41], v[126:129], v[192:195], v[38:41]
	v_mfma_f32_16x16x32_bf16 v[34:37], v[134:137], v[192:195], v[34:37]
	v_mfma_f32_16x16x32_bf16 v[22:25], v[126:129], v[200:203], v[22:25]
	v_mfma_f32_16x16x32_bf16 v[18:21], v[134:137], v[200:203], v[18:21]
	v_mfma_f32_16x16x32_bf16 v[6:9], v[126:129], v[208:211], v[6:9]
	v_mfma_f32_16x16x32_bf16 v[2:5], v[134:137], v[208:211], v[2:5]
	s_setprio 0
	s_barrier
	s_add_i32 s69, 0, 0x18000
	s_add_i32 s70, 0, 0x1c000
	v_add_u32_e32 v118, s69, v229
	v_add_u32_e32 v134, s70, v229
	ds_read_b128 v[106:109], v118
	ds_read_b128 v[110:113], v118 offset:1024
	ds_read_b128 v[114:117], v118 offset:2048
	ds_read_b128 v[118:121], v118 offset:3072
	ds_read_b128 v[122:125], v134
	ds_read_b128 v[126:129], v134 offset:1024
	ds_read_b128 v[130:133], v134 offset:2048
	ds_read_b128 v[134:137], v134 offset:3072
	s_add_u32 s46, s46, 0x40000
	s_addc_u32 s47, s47, 0
	s_mov_b32 m0, s55
	v_lshl_add_u64 v[220:221], s[46:47], 0, v[186:187]
	ds_read_b128 v[162:165], v230 offset:32768
	ds_read_b128 v[166:169], v230 offset:33792
	ds_read_b128 v[170:173], v230 offset:34816
	ds_read_b128 v[192:195], v230 offset:35840
	ds_read_b128 v[196:199], v230 offset:36864
	ds_read_b128 v[200:203], v230 offset:37888
	ds_read_b128 v[204:207], v230 offset:38912
	ds_read_b128 v[208:211], v230 offset:39936
	global_load_lds_dwordx4 v[220:221], off
	v_lshl_add_u64 v[220:221], s[46:47], 0, v[182:183]
	s_mov_b32 m0, s56
	s_nop 0
	global_load_lds_dwordx4 v[220:221], off
	s_waitcnt vmcnt(8)
	s_waitcnt lgkmcnt(0)
	s_barrier
	s_setprio 1
	s_waitcnt lgkmcnt(0)
	v_mfma_f32_16x16x32_bf16 v[158:161], v[106:109], v[162:165], v[158:161]
	v_mfma_f32_16x16x32_bf16 v[154:157], v[114:117], v[162:165], v[154:157]
	v_mfma_f32_16x16x32_bf16 v[142:145], v[106:109], v[170:173], v[142:145]
	v_mfma_f32_16x16x32_bf16 v[138:141], v[114:117], v[170:173], v[138:141]
	v_mfma_f32_16x16x32_bf16 v[94:97], v[106:109], v[196:199], v[94:97]
	v_mfma_f32_16x16x32_bf16 v[90:93], v[114:117], v[196:199], v[90:93]
	v_mfma_f32_16x16x32_bf16 v[78:81], v[106:109], v[204:207], v[78:81]
	v_mfma_f32_16x16x32_bf16 v[74:77], v[114:117], v[204:207], v[74:77]
	v_mfma_f32_16x16x32_bf16 v[158:161], v[110:113], v[166:169], v[158:161]
	v_mfma_f32_16x16x32_bf16 v[154:157], v[118:121], v[166:169], v[154:157]
	v_mfma_f32_16x16x32_bf16 v[142:145], v[110:113], v[192:195], v[142:145]
	v_mfma_f32_16x16x32_bf16 v[138:141], v[118:121], v[192:195], v[138:141]
	v_mfma_f32_16x16x32_bf16 v[94:97], v[110:113], v[200:203], v[94:97]
	v_mfma_f32_16x16x32_bf16 v[90:93], v[118:121], v[200:203], v[90:93]
	v_mfma_f32_16x16x32_bf16 v[78:81], v[110:113], v[208:211], v[78:81]
	v_mfma_f32_16x16x32_bf16 v[74:77], v[118:121], v[208:211], v[74:77]
	v_mfma_f32_16x16x32_bf16 v[150:153], v[122:125], v[162:165], v[150:153]
	v_mfma_f32_16x16x32_bf16 v[146:149], v[130:133], v[162:165], v[146:149]
	v_mfma_f32_16x16x32_bf16 v[102:105], v[122:125], v[170:173], v[102:105]
	v_mfma_f32_16x16x32_bf16 v[98:101], v[130:133], v[170:173], v[98:101]
	v_mfma_f32_16x16x32_bf16 v[86:89], v[122:125], v[196:199], v[86:89]
	v_mfma_f32_16x16x32_bf16 v[82:85], v[130:133], v[196:199], v[82:85]
	v_mfma_f32_16x16x32_bf16 v[70:73], v[122:125], v[204:207], v[70:73]
	v_mfma_f32_16x16x32_bf16 v[66:69], v[130:133], v[204:207], v[66:69]
	v_mfma_f32_16x16x32_bf16 v[150:153], v[126:129], v[166:169], v[150:153]
	v_mfma_f32_16x16x32_bf16 v[146:149], v[134:137], v[166:169], v[146:149]
	v_mfma_f32_16x16x32_bf16 v[102:105], v[126:129], v[192:195], v[102:105]
	v_mfma_f32_16x16x32_bf16 v[98:101], v[134:137], v[192:195], v[98:101]
	v_mfma_f32_16x16x32_bf16 v[86:89], v[126:129], v[200:203], v[86:89]
	v_mfma_f32_16x16x32_bf16 v[82:85], v[134:137], v[200:203], v[82:85]
	v_mfma_f32_16x16x32_bf16 v[70:73], v[126:129], v[208:211], v[70:73]
	v_mfma_f32_16x16x32_bf16 v[66:69], v[134:137], v[208:211], v[66:69]
	s_setprio 0
	s_barrier
; #define PG8_STAGE(bufoff, gbase, voff) do { _Pragma("unroll") for (int _i = 0; _i < 2; ++_i) \
;         __builtin_amdgcn_global_load_lds((const unsigned*)((const char*)(gbase) + (voff)[_i]), (PG8_LAS unsigned*)(lds + (bufoff) + ldsw + _i * 8192), 16, 0, 0); } while (0)
; #define PG8_LDA(dst, b, h) do { _Pragma("unroll") for (int m = 0; m < 4; ++m) _Pragma("unroll") for (int k = 0; k < 2; ++k) dst[m][k] = *(const PG8_LAS bf16x8*)(lds + PG8_SA(b, h) + aoff + m * 2048 + k * 1024); } while (0)
; #define PG8_MMA(ai, bj, At, Bt) do { __builtin_amdgcn_s_setprio(1); _Pragma("unroll") for (int m = 0; m < 4; ++m) _Pragma("unroll") for (int n = 0; n < 2; ++n) _Pragma("unroll") for (int k = 0; k < 2; ++k) \
;         acc[ai][bj][m][n] = __builtin_amdgcn_mfma_f32_16x16x32_bf16(Bt[n][k], At[m][k], acc[ai][bj][m][n], 0, 0, 0); __builtin_amdgcn_s_setprio(0); } while (0)
; #define PG8_WAIT_V(n) asm volatile("s_waitcnt vmcnt(" #n ")" ::: "memory")
; #define PG8_WAIT_L(n) asm volatile("s_waitcnt lgkmcnt(" #n ")" ::: "memory")
; #define PG8_BAR __builtin_amdgcn_s_barrier()
; #define PG8_SCHED __builtin_amdgcn_sched_barrier(0)
; template <class Epi, class Sched, bool ALIGN_EPI = false, bool SP2 = false>
; __device__ __forceinline__ void gemm_phase(PG8_LAS unsigned char* lds, const Gemm g, const Sched& S, const Epi& E) {
;     ...
;         for (int t = 0; t < nt; t += 2) {
;             const bool last = (t == nt - 2);
;             const char* a1 = cA + (size_t)(t + 1) * kstep;
;             const char* a2 = last ? nA : cA + (size_t)(t + 2) * kstep; const char* b2 = last ? nB : cB + (size_t)(t + 2) * kstep;
;             const char* a3 = a2 + kstep; const char* b3 = b2 + kstep;
;     ...
;             PG8_LDA(At, 1, 1); PG8_STAGE(PG8_SB(1, 0), b3, voffB); PG8_STAGE(PG8_SB(1, 1), b3 + hstep, voffB); PG8_STAGE(PG8_SA(1, 0), a3, voffA);
;             PG8_WAIT_V(8); PG8_WAIT_L(0); PG8_BAR; PG8_MMA(1, 0, At, B0); PG8_MMA(1, 1, At, B1); PG8_BAR; PG8_SCHED;
	s_add_i32 s46, s69, s52
	v_lshl_add_u64 v[212:213], v[212:213], 0, s[96:97]
	s_mov_b32 m0, s46
	ds_read_b128 v[162:165], v230 offset:49152
	ds_read_b128 v[166:169], v230 offset:50176
	ds_read_b128 v[170:173], v230 offset:51200
	ds_read_b128 v[192:195], v230 offset:52224
	ds_read_b128 v[196:199], v230 offset:53248
	ds_read_b128 v[200:203], v230 offset:54272
	ds_read_b128 v[204:207], v230 offset:55296
	ds_read_b128 v[208:211], v230 offset:56320
	global_load_lds_dwordx4 v[212:213], off
	s_add_i32 m0, s46, 0x2000
	s_add_u32 s44, s44, 0x40080
	v_lshl_add_u64 v[212:213], v[214:215], 0, s[96:97]
	s_addc_u32 s45, s45, 0
	s_add_i32 s46, s70, s52
	global_load_lds_dwordx4 v[212:213], off
	v_lshl_add_u64 v[212:213], s[44:45], 0, v[184:185]
	s_mov_b32 m0, s46
	s_nop 0
	global_load_lds_dwordx4 v[212:213], off
	v_lshl_add_u64 v[212:213], s[44:45], 0, v[180:181]
	s_add_i32 m0, s46, 0x2000
	s_nop 0
	global_load_lds_dwordx4 v[212:213], off
	v_lshl_add_u64 v[212:213], v[216:217], 0, s[96:97]
	s_mov_b32 m0, s60
	s_nop 0
	global_load_lds_dwordx4 v[212:213], off
	v_lshl_add_u64 v[212:213], v[218:219], 0, s[96:97]
	s_mov_b32 m0, s61
	s_nop 0
	global_load_lds_dwordx4 v[212:213], off
	s_waitcnt vmcnt(8)
	s_waitcnt lgkmcnt(0)
	s_barrier
	s_setprio 1
	s_waitcnt lgkmcnt(0)
	v_mfma_f32_16x16x32_bf16 v[62:65], v[106:109], v[162:165], v[62:65]
	v_mfma_f32_16x16x32_bf16 v[58:61], v[114:117], v[162:165], v[58:61]
	v_mfma_f32_16x16x32_bf16 v[46:49], v[106:109], v[170:173], v[46:49]
	v_mfma_f32_16x16x32_bf16 v[42:45], v[114:117], v[170:173], v[42:45]
	v_mfma_f32_16x16x32_bf16 v[30:33], v[106:109], v[196:199], v[30:33]
	v_mfma_f32_16x16x32_bf16 v[26:29], v[114:117], v[196:199], v[26:29]
	v_mfma_f32_16x16x32_bf16 v[14:17], v[106:109], v[204:207], v[14:17]
	v_mfma_f32_16x16x32_bf16 v[10:13], v[114:117], v[204:207], v[10:13]
	v_mfma_f32_16x16x32_bf16 v[62:65], v[110:113], v[166:169], v[62:65]
	v_mfma_f32_16x16x32_bf16 v[58:61], v[118:121], v[166:169], v[58:61]
	v_mfma_f32_16x16x32_bf16 v[46:49], v[110:113], v[192:195], v[46:49]
	v_mfma_f32_16x16x32_bf16 v[42:45], v[118:121], v[192:195], v[42:45]
	v_mfma_f32_16x16x32_bf16 v[30:33], v[110:113], v[200:203], v[30:33]
	v_mfma_f32_16x16x32_bf16 v[26:29], v[118:121], v[200:203], v[26:29]
	v_mfma_f32_16x16x32_bf16 v[14:17], v[110:113], v[208:211], v[14:17]
	v_mfma_f32_16x16x32_bf16 v[10:13], v[118:121], v[208:211], v[10:13]
	v_mfma_f32_16x16x32_bf16 v[54:57], v[122:125], v[162:165], v[54:57]
	v_mfma_f32_16x16x32_bf16 v[50:53], v[130:133], v[162:165], v[50:53]
	v_mfma_f32_16x16x32_bf16 v[38:41], v[122:125], v[170:173], v[38:41]
	v_mfma_f32_16x16x32_bf16 v[34:37], v[130:133], v[170:173], v[34:37]
	v_mfma_f32_16x16x32_bf16 v[22:25], v[122:125], v[196:199], v[22:25]
	v_mfma_f32_16x16x32_bf16 v[18:21], v[130:133], v[196:199], v[18:21]
	v_mfma_f32_16x16x32_bf16 v[6:9], v[122:125], v[204:207], v[6:9]
	v_mfma_f32_16x16x32_bf16 v[2:5], v[130:133], v[204:207], v[2:5]
	v_mfma_f32_16x16x32_bf16 v[54:57], v[126:129], v[166:169], v[54:57]
	v_mfma_f32_16x16x32_bf16 v[50:53], v[134:137], v[166:169], v[50:53]
	v_mfma_f32_16x16x32_bf16 v[38:41], v[126:129], v[192:195], v[38:41]
	v_mfma_f32_16x16x32_bf16 v[34:37], v[134:137], v[192:195], v[34:37]
	v_mfma_f32_16x16x32_bf16 v[22:25], v[126:129], v[200:203], v[22:25]
	v_mfma_f32_16x16x32_bf16 v[18:21], v[134:137], v[200:203], v[18:21]
	v_mfma_f32_16x16x32_bf16 v[6:9], v[126:129], v[208:211], v[6:9]
	v_mfma_f32_16x16x32_bf16 v[2:5], v[134:137], v[208:211], v[2:5]
	s_setprio 0
	s_add_i32 s68, s68, 2
	s_add_u32 s8, s8, 0x100
	s_addc_u32 s9, s9, 0
	s_add_u32 s66, s66, 0x100
	s_addc_u32 s67, s67, 0
	s_add_u32 s44, s8, 0xfffc0080
	s_addc_u32 s45, s9, -1
	s_add_i32 s69, 0, 0x10000
	s_cmp_eq_u32 s68, 12
	s_cselect_b32 s47, s37, s45
	s_cselect_b32 s46, s43, s44
	s_cselect_b32 s45, s35, s67
	s_cselect_b32 s44, s65, s66
	s_add_i32 s72, 0, 0x14000
	s_cmp_gt_u32 s68, 13
	s_cbranch_scc0 .Lrotb_ffin
	s_barrier
	s_and_b64 vcc, exec, s[24:25]
	s_cbranch_vccz .LBB0_1250
	s_barrier

; template <class Epi, class Sched, bool ALIGN_EPI = false, bool SP2 = false>
; __device__ __forceinline__ void gemm_phase(PG8_LAS unsigned char* lds, const Gemm g, const Sched& S, const Epi& E) {
;     ...
;         const char* nA = has_next ? (const char*)g.A + (size_t)nxt.pm * tstep : cA; const char* nB = has_next ? (const char*)g.Bt + (size_t)nxt.pn * tstep : cB;
;         for (int t = 0; t < nt; t += 2) {
;             const bool last = (t == nt - 2);
;             const char* a1 = cA + (size_t)(t + 1) * kstep;
;             const char* a2 = last ? nA : cA + (size_t)(t + 2) * kstep; const char* b2 = last ? nB : cB + (size_t)(t + 2) * kstep;
;             const char* a3 = a2 + kstep; const char* b3 = b2 + kstep;
.LBB0_1360:
	s_add_u32 s8, s22, 0x100
	s_addc_u32 s9, s23, 0
	s_add_i32 s51, 0, 0x10000
	s_cmp_eq_u32 s50, 40
	s_cselect_b32 s27, s19, s9
	s_cselect_b32 s26, s18, s8
	s_cselect_b32 s25, s21, s49
	s_cselect_b32 s24, s20, s33
	s_add_i32 s52, 0, 0x14000
	s_branch .Lrot_ffout

; #define PG8_STAGE(bufoff, gbase, voff) do { _Pragma("unroll") for (int _i = 0; _i < 2; ++_i) \
;         __builtin_amdgcn_global_load_lds((const unsigned*)((const char*)(gbase) + (voff)[_i]), (PG8_LAS unsigned*)(lds + (bufoff) + ldsw + _i * 8192), 16, 0, 0); } while (0)
; #define PG8_LDA(dst, b, h) do { _Pragma("unroll") for (int m = 0; m < 4; ++m) _Pragma("unroll") for (int k = 0; k < 2; ++k) dst[m][k] = *(const PG8_LAS bf16x8*)(lds + PG8_SA(b, h) + aoff + m * 2048 + k * 1024); } while (0)
; #define PG8_LDB(dst, b, h) do { _Pragma("unroll") for (int n = 0; n < 2; ++n) _Pragma("unroll") for (int k = 0; k < 2; ++k) dst[n][k] = *(const PG8_LAS bf16x8*)(lds + PG8_SB(b, h) + boff + n * 2048 + k * 1024); } while (0)
; #define PG8_MMA(ai, bj, At, Bt) do { __builtin_amdgcn_s_setprio(1); _Pragma("unroll") for (int m = 0; m < 4; ++m) _Pragma("unroll") for (int n = 0; n < 2; ++n) _Pragma("unroll") for (int k = 0; k < 2; ++k) \
;         acc[ai][bj][m][n] = __builtin_amdgcn_mfma_f32_16x16x32_bf16(Bt[n][k], At[m][k], acc[ai][bj][m][n], 0, 0, 0); __builtin_amdgcn_s_setprio(0); } while (0)
; #define PG8_WAIT_V(n) asm volatile("s_waitcnt vmcnt(" #n ")" ::: "memory")
; #define PG8_WAIT_L(n) asm volatile("s_waitcnt lgkmcnt(" #n ")" ::: "memory")
; #define PG8_BAR __builtin_amdgcn_s_barrier()
; #define PG8_SCHED __builtin_amdgcn_sched_barrier(0)
; template <class Epi, class Sched, bool ALIGN_EPI = false, bool SP2 = false>
; __device__ __forceinline__ void gemm_phase(PG8_LAS unsigned char* lds, const Gemm g, const Sched& S, const Epi& E) {
;     ...
;             PG8_LDB(B0, 0, 0); PG8_LDB(B1, 0, 1); PG8_SCHED; PG8_LDA(At, 0, 0); PG8_STAGE(PG8_SA(1, 1), a1 + hstep, voffA);
;             PG8_WAIT_V(8); PG8_WAIT_L(0); PG8_BAR; PG8_MMA(0, 0, At, B0); PG8_MMA(0, 1, At, B1); PG8_BAR; PG8_SCHED;
;     ...
;         for (int a = 0; a < 2; ++a)
; #pragma unroll
;             for (int b = 0; b < 2; ++b)
; #pragma unroll
;                 for (int m = 0; m < 4; ++m)
; #pragma unroll
;                     for (int n = 0; n < 2; ++n) acc[a][b][m][n] = (f32x4){0.f, 0.f, 0.f, 0.f};
.Lrot_ffout:
	v_add_u32_e32 v134, s51, v185
	v_add_u32_e32 v170, s52, v185
	ds_read_b128 v[114:117], v134
	ds_read_b128 v[118:121], v134 offset:1024
	ds_read_b128 v[122:125], v134 offset:2048
	ds_read_b128 v[134:137], v134 offset:3072
	ds_read_b128 v[146:149], v170
	ds_read_b128 v[150:153], v170 offset:1024
	ds_read_b128 v[166:169], v170 offset:2048
	ds_read_b128 v[170:173], v170 offset:3072
	v_lshl_add_u64 v[216:217], s[22:23], 0, v[162:163]
	s_add_i32 m0, s35, 0xc000
	ds_read_b128 v[180:183], v186
	ds_read_b128 v[188:191], v186 offset:1024
	ds_read_b128 v[192:195], v186 offset:2048
	ds_read_b128 v[196:199], v186 offset:3072
	ds_read_b128 v[200:203], v186 offset:4096
	ds_read_b128 v[204:207], v186 offset:5120
	ds_read_b128 v[208:211], v186 offset:6144
	ds_read_b128 v[212:215], v186 offset:7168
	global_load_lds_dwordx4 v[216:217], off
	v_lshl_add_u64 v[216:217], s[22:23], 0, v[164:165]
	s_add_i32 m0, s35, 0xe000
	s_nop 0
	global_load_lds_dwordx4 v[216:217], off
	s_cmp_lg_u32 s50, -2
	s_cbranch_scc1 .Lffout_noz
	v_mov_b32_e32 v2, 0
	v_mov_b32_e32 v3, v2
	v_mov_b32_e32 v4, v2
	v_mov_b32_e32 v5, v2
	v_mov_b32_e32 v6, v2
	v_mov_b32_e32 v7, v2
	v_mov_b32_e32 v8, v2
	v_mov_b32_e32 v9, v2
	v_mov_b32_e32 v18, v2
	v_mov_b32_e32 v19, v2
	v_mov_b32_e32 v20, v2
	v_mov_b32_e32 v21, v2
	v_mov_b32_e32 v22, v2
	v_mov_b32_e32 v23, v2
	v_mov_b32_e32 v24, v2
	v_mov_b32_e32 v25, v2
	v_mov_b32_e32 v34, v2
	v_mov_b32_e32 v35, v2
	v_mov_b32_e32 v36, v2
	v_mov_b32_e32 v37, v2
	v_mov_b32_e32 v38, v2
	v_mov_b32_e32 v39, v2
	v_mov_b32_e32 v40, v2
	v_mov_b32_e32 v41, v2
	v_mov_b32_e32 v50, v2
	v_mov_b32_e32 v51, v2
	v_mov_b32_e32 v52, v2
	v_mov_b32_e32 v53, v2
	v_mov_b32_e32 v54, v2
	v_mov_b32_e32 v55, v2
	v_mov_b32_e32 v56, v2
	v_mov_b32_e32 v57, v2
	v_mov_b32_e32 v10, v2
	v_mov_b32_e32 v11, v2
	v_mov_b32_e32 v12, v2
	v_mov_b32_e32 v13, v2
	v_mov_b32_e32 v14, v2
	v_mov_b32_e32 v15, v2
	v_mov_b32_e32 v16, v2
	v_mov_b32_e32 v17, v2
	v_mov_b32_e32 v26, v2
	v_mov_b32_e32 v27, v2
	v_mov_b32_e32 v28, v2
	v_mov_b32_e32 v29, v2
	v_mov_b32_e32 v30, v2
	v_mov_b32_e32 v31, v2
	v_mov_b32_e32 v32, v2
	v_mov_b32_e32 v33, v2
	v_mov_b32_e32 v42, v2
	v_mov_b32_e32 v43, v2
	v_mov_b32_e32 v44, v2
	v_mov_b32_e32 v45, v2
	v_mov_b32_e32 v46, v2
	v_mov_b32_e32 v47, v2
	v_mov_b32_e32 v48, v2
	v_mov_b32_e32 v49, v2
	v_mov_b32_e32 v58, v2
	v_mov_b32_e32 v59, v2
	v_mov_b32_e32 v60, v2
	v_mov_b32_e32 v61, v2
	v_mov_b32_e32 v62, v2
	v_mov_b32_e32 v63, v2
	v_mov_b32_e32 v64, v2
	v_mov_b32_e32 v65, v2
	v_mov_b32_e32 v66, v2
	v_mov_b32_e32 v67, v2
	v_mov_b32_e32 v68, v2
	v_mov_b32_e32 v69, v2
	v_mov_b32_e32 v70, v2
	v_mov_b32_e32 v71, v2
	v_mov_b32_e32 v72, v2
	v_mov_b32_e32 v73, v2
	v_mov_b32_e32 v82, v2
	v_mov_b32_e32 v83, v2
	v_mov_b32_e32 v84, v2
	v_mov_b32_e32 v85, v2
	v_mov_b32_e32 v86, v2
	v_mov_b32_e32 v87, v2
	v_mov_b32_e32 v88, v2
	v_mov_b32_e32 v89, v2
	v_mov_b32_e32 v98, v2
	v_mov_b32_e32 v99, v2
	v_mov_b32_e32 v100, v2
	v_mov_b32_e32 v101, v2
	v_mov_b32_e32 v102, v2
	v_mov_b32_e32 v103, v2
	v_mov_b32_e32 v104, v2
	v_mov_b32_e32 v105, v2
	v_mov_b32_e32 v126, v2
	v_mov_b32_e32 v127, v2
	v_mov_b32_e32 v128, v2
	v_mov_b32_e32 v129, v2
	v_mov_b32_e32 v130, v2
	v_mov_b32_e32 v131, v2
	v_mov_b32_e32 v132, v2
	v_mov_b32_e32 v133, v2
	v_mov_b32_e32 v74, v2
	v_mov_b32_e32 v75, v2
	v_mov_b32_e32 v76, v2
	v_mov_b32_e32 v77, v2
	v_mov_b32_e32 v78, v2
	v_mov_b32_e32 v79, v2
	v_mov_b32_e32 v80, v2
	v_mov_b32_e32 v81, v2
	v_mov_b32_e32 v90, v2
	v_mov_b32_e32 v91, v2
	v_mov_b32_e32 v92, v2
	v_mov_b32_e32 v93, v2
	v_mov_b32_e32 v94, v2
	v_mov_b32_e32 v95, v2
	v_mov_b32_e32 v96, v2
	v_mov_b32_e32 v97, v2
	v_mov_b32_e32 v106, v2
	v_mov_b32_e32 v107, v2
	v_mov_b32_e32 v108, v2
	v_mov_b32_e32 v109, v2
	v_mov_b32_e32 v110, v2
	v_mov_b32_e32 v111, v2
	v_mov_b32_e32 v112, v2
	v_mov_b32_e32 v113, v2
	v_mov_b32_e32 v138, v2
	v_mov_b32_e32 v139, v2
	v_mov_b32_e32 v140, v2
	v_mov_b32_e32 v141, v2
	v_mov_b32_e32 v142, v2
	v_mov_b32_e32 v143, v2
	v_mov_b32_e32 v144, v2
	v_mov_b32_e32 v145, v2
.Lffout_noz:
	s_waitcnt vmcnt(8)
	s_waitcnt lgkmcnt(0)
	s_barrier
	s_setprio 1
	s_waitcnt lgkmcnt(0)
	v_mfma_f32_16x16x32_bf16 v[142:145], v[114:117], v[180:183], v[142:145]
	v_mfma_f32_16x16x32_bf16 v[138:141], v[122:125], v[180:183], v[138:141]
	v_mfma_f32_16x16x32_bf16 v[110:113], v[114:117], v[192:195], v[110:113]
	v_mfma_f32_16x16x32_bf16 v[106:109], v[122:125], v[192:195], v[106:109]
	v_mfma_f32_16x16x32_bf16 v[94:97], v[114:117], v[200:203], v[94:97]
	v_mfma_f32_16x16x32_bf16 v[90:93], v[122:125], v[200:203], v[90:93]
	v_mfma_f32_16x16x32_bf16 v[78:81], v[114:117], v[208:211], v[78:81]
	v_mfma_f32_16x16x32_bf16 v[74:77], v[122:125], v[208:211], v[74:77]
	v_mfma_f32_16x16x32_bf16 v[142:145], v[118:121], v[188:191], v[142:145]
	v_mfma_f32_16x16x32_bf16 v[138:141], v[134:137], v[188:191], v[138:141]
	v_mfma_f32_16x16x32_bf16 v[110:113], v[118:121], v[196:199], v[110:113]
	v_mfma_f32_16x16x32_bf16 v[106:109], v[134:137], v[196:199], v[106:109]
	v_mfma_f32_16x16x32_bf16 v[94:97], v[118:121], v[204:207], v[94:97]
	v_mfma_f32_16x16x32_bf16 v[90:93], v[134:137], v[204:207], v[90:93]
	v_mfma_f32_16x16x32_bf16 v[78:81], v[118:121], v[212:215], v[78:81]
	v_mfma_f32_16x16x32_bf16 v[74:77], v[134:137], v[212:215], v[74:77]
	v_mfma_f32_16x16x32_bf16 v[130:133], v[146:149], v[180:183], v[130:133]
	v_mfma_f32_16x16x32_bf16 v[126:129], v[166:169], v[180:183], v[126:129]
	v_mfma_f32_16x16x32_bf16 v[102:105], v[146:149], v[192:195], v[102:105]
	v_mfma_f32_16x16x32_bf16 v[98:101], v[166:169], v[192:195], v[98:101]
	v_mfma_f32_16x16x32_bf16 v[86:89], v[146:149], v[200:203], v[86:89]
	v_mfma_f32_16x16x32_bf16 v[82:85], v[166:169], v[200:203], v[82:85]
	v_mfma_f32_16x16x32_bf16 v[70:73], v[146:149], v[208:211], v[70:73]
	v_mfma_f32_16x16x32_bf16 v[66:69], v[166:169], v[208:211], v[66:69]
	v_mfma_f32_16x16x32_bf16 v[130:133], v[150:153], v[188:191], v[130:133]
	v_mfma_f32_16x16x32_bf16 v[126:129], v[170:173], v[188:191], v[126:129]
	v_mfma_f32_16x16x32_bf16 v[102:105], v[150:153], v[196:199], v[102:105]
	v_mfma_f32_16x16x32_bf16 v[98:101], v[170:173], v[196:199], v[98:101]
	v_mfma_f32_16x16x32_bf16 v[86:89], v[150:153], v[204:207], v[86:89]
	v_mfma_f32_16x16x32_bf16 v[82:85], v[170:173], v[204:207], v[82:85]
	v_mfma_f32_16x16x32_bf16 v[70:73], v[150:153], v[212:215], v[70:73]
	v_mfma_f32_16x16x32_bf16 v[66:69], v[170:173], v[212:215], v[66:69]
	s_setprio 0
	s_barrier
; #define PG8_STAGE(bufoff, gbase, voff) do { _Pragma("unroll") for (int _i = 0; _i < 2; ++_i) \
;         __builtin_amdgcn_global_load_lds((const unsigned*)((const char*)(gbase) + (voff)[_i]), (PG8_LAS unsigned*)(lds + (bufoff) + ldsw + _i * 8192), 16, 0, 0); } while (0)
; #define PG8_LDA(dst, b, h) do { _Pragma("unroll") for (int m = 0; m < 4; ++m) _Pragma("unroll") for (int k = 0; k < 2; ++k) dst[m][k] = *(const PG8_LAS bf16x8*)(lds + PG8_SA(b, h) + aoff + m * 2048 + k * 1024); } while (0)
; #define PG8_LDB(dst, b, h) do { _Pragma("unroll") for (int n = 0; n < 2; ++n) _Pragma("unroll") for (int k = 0; k < 2; ++k) dst[n][k] = *(const PG8_LAS bf16x8*)(lds + PG8_SB(b, h) + boff + n * 2048 + k * 1024); } while (0)
; #define PG8_MMA(ai, bj, At, Bt) do { __builtin_amdgcn_s_setprio(1); _Pragma("unroll") for (int m = 0; m < 4; ++m) _Pragma("unroll") for (int n = 0; n < 2; ++n) _Pragma("unroll") for (int k = 0; k < 2; ++k) \
;         acc[ai][bj][m][n] = __builtin_amdgcn_mfma_f32_16x16x32_bf16(Bt[n][k], At[m][k], acc[ai][bj][m][n], 0, 0, 0); __builtin_amdgcn_s_setprio(0); } while (0)
; #define PG8_WAIT_V(n) asm volatile("s_waitcnt vmcnt(" #n ")" ::: "memory")
; #define PG8_WAIT_L(n) asm volatile("s_waitcnt lgkmcnt(" #n ")" ::: "memory")
; #define PG8_BAR __builtin_amdgcn_s_barrier()
; #define PG8_SCHED __builtin_amdgcn_sched_barrier(0)
; template <class Epi, class Sched, bool ALIGN_EPI = false, bool SP2 = false>
; __device__ __forceinline__ void gemm_phase(PG8_LAS unsigned char* lds, const Gemm g, const Sched& S, const Epi& E) {
;     ...
;             PG8_LDA(At, 0, 1); PG8_STAGE(PG8_SB(0, 0), b2, voffB); PG8_STAGE(PG8_SB(0, 1), b2 + hstep, voffB); PG8_STAGE(PG8_SA(0, 0), a2, voffA);
;             PG8_WAIT_V(8); PG8_WAIT_L(0); PG8_BAR; PG8_MMA(1, 0, At, B0); PG8_MMA(1, 1, At, B1); PG8_BAR; PG8_SCHED;
;             PG8_LDB(B0, 1, 0); PG8_LDB(B1, 1, 1); PG8_SCHED; PG8_LDA(At, 1, 0); PG8_STAGE(PG8_SA(0, 1), a2 + hstep, voffA);
;             PG8_WAIT_V(8); PG8_WAIT_L(0); PG8_BAR; PG8_MMA(0, 0, At, B0); PG8_MMA(0, 1, At, B1); PG8_BAR; PG8_SCHED;
	s_add_i32 s22, s51, s34
	v_lshl_add_u64 v[216:217], s[24:25], 0, v[158:159]
	s_mov_b32 m0, s22
	ds_read_b128 v[180:183], v186 offset:16384
	ds_read_b128 v[188:191], v186 offset:17408
	ds_read_b128 v[192:195], v186 offset:18432
	ds_read_b128 v[196:199], v186 offset:19456
	ds_read_b128 v[200:203], v186 offset:20480
	ds_read_b128 v[204:207], v186 offset:21504
	ds_read_b128 v[208:211], v186 offset:22528
	ds_read_b128 v[212:215], v186 offset:23552
	global_load_lds_dwordx4 v[216:217], off
	s_add_i32 m0, s22, 0x2000
	s_add_u32 s22, s24, 0xb0000
	v_lshl_add_u64 v[218:219], s[24:25], 0, v[154:155]
	s_addc_u32 s23, s25, 0
	s_add_i32 s51, s52, s34
	global_load_lds_dwordx4 v[218:219], off
	v_lshl_add_u64 v[220:221], s[22:23], 0, v[158:159]
	s_mov_b32 m0, s51
	v_lshl_add_u64 v[222:223], s[26:27], 0, v[156:157]
	global_load_lds_dwordx4 v[220:221], off
	v_lshl_add_u64 v[220:221], s[22:23], 0, v[154:155]
	s_add_i32 m0, s51, 0x2000
	s_nop 0
	global_load_lds_dwordx4 v[220:221], off
	v_lshl_add_u64 v[220:221], s[26:27], 0, v[160:161]
	s_mov_b32 m0, s35
	s_nop 0
	global_load_lds_dwordx4 v[220:221], off
	s_mov_b32 m0, s36
	s_nop 0
	global_load_lds_dwordx4 v[222:223], off
	s_waitcnt vmcnt(8)
	s_waitcnt lgkmcnt(0)
	s_barrier
	s_setprio 1
	s_waitcnt lgkmcnt(0)
	v_mfma_f32_16x16x32_bf16 v[62:65], v[114:117], v[180:183], v[62:65]
	v_mfma_f32_16x16x32_bf16 v[58:61], v[122:125], v[180:183], v[58:61]
	v_mfma_f32_16x16x32_bf16 v[46:49], v[114:117], v[192:195], v[46:49]
	v_mfma_f32_16x16x32_bf16 v[42:45], v[122:125], v[192:195], v[42:45]
	v_mfma_f32_16x16x32_bf16 v[30:33], v[114:117], v[200:203], v[30:33]
	v_mfma_f32_16x16x32_bf16 v[26:29], v[122:125], v[200:203], v[26:29]
	v_mfma_f32_16x16x32_bf16 v[14:17], v[114:117], v[208:211], v[14:17]
	v_mfma_f32_16x16x32_bf16 v[10:13], v[122:125], v[208:211], v[10:13]
	v_mfma_f32_16x16x32_bf16 v[62:65], v[118:121], v[188:191], v[62:65]
	v_mfma_f32_16x16x32_bf16 v[58:61], v[134:137], v[188:191], v[58:61]
	v_mfma_f32_16x16x32_bf16 v[46:49], v[118:121], v[196:199], v[46:49]
	v_mfma_f32_16x16x32_bf16 v[42:45], v[134:137], v[196:199], v[42:45]
	v_mfma_f32_16x16x32_bf16 v[30:33], v[118:121], v[204:207], v[30:33]
	v_mfma_f32_16x16x32_bf16 v[26:29], v[134:137], v[204:207], v[26:29]
	v_mfma_f32_16x16x32_bf16 v[14:17], v[118:121], v[212:215], v[14:17]
	v_mfma_f32_16x16x32_bf16 v[10:13], v[134:137], v[212:215], v[10:13]
	v_mfma_f32_16x16x32_bf16 v[54:57], v[146:149], v[180:183], v[54:57]
	v_mfma_f32_16x16x32_bf16 v[50:53], v[166:169], v[180:183], v[50:53]
	v_mfma_f32_16x16x32_bf16 v[38:41], v[146:149], v[192:195], v[38:41]
	v_mfma_f32_16x16x32_bf16 v[34:37], v[166:169], v[192:195], v[34:37]
	v_mfma_f32_16x16x32_bf16 v[22:25], v[146:149], v[200:203], v[22:25]
	v_mfma_f32_16x16x32_bf16 v[18:21], v[166:169], v[200:203], v[18:21]
	v_mfma_f32_16x16x32_bf16 v[6:9], v[146:149], v[208:211], v[6:9]
	v_mfma_f32_16x16x32_bf16 v[2:5], v[166:169], v[208:211], v[2:5]
	v_mfma_f32_16x16x32_bf16 v[54:57], v[150:153], v[188:191], v[54:57]
	v_mfma_f32_16x16x32_bf16 v[50:53], v[170:173], v[188:191], v[50:53]
	v_mfma_f32_16x16x32_bf16 v[38:41], v[150:153], v[196:199], v[38:41]
	v_mfma_f32_16x16x32_bf16 v[34:37], v[170:173], v[196:199], v[34:37]
	v_mfma_f32_16x16x32_bf16 v[22:25], v[150:153], v[204:207], v[22:25]
	v_mfma_f32_16x16x32_bf16 v[18:21], v[170:173], v[204:207], v[18:21]
	v_mfma_f32_16x16x32_bf16 v[6:9], v[150:153], v[212:215], v[6:9]
	v_mfma_f32_16x16x32_bf16 v[2:5], v[170:173], v[212:215], v[2:5]
	s_setprio 0
	s_barrier
	s_add_i32 s51, 0, 0x18000
	s_add_i32 s52, 0, 0x1c000
	v_add_u32_e32 v134, s51, v185
	v_add_u32_e32 v170, s52, v185
	ds_read_b128 v[114:117], v134
	ds_read_b128 v[118:121], v134 offset:1024
	ds_read_b128 v[122:125], v134 offset:2048
	ds_read_b128 v[134:137], v134 offset:3072
	ds_read_b128 v[146:149], v170
	ds_read_b128 v[150:153], v170 offset:1024
	ds_read_b128 v[166:169], v170 offset:2048
	ds_read_b128 v[170:173], v170 offset:3072
	s_add_u32 s22, s26, 0xb0000
	s_addc_u32 s23, s27, 0
	s_mov_b32 m0, s37
	v_lshl_add_u64 v[228:229], s[22:23], 0, v[160:161]
	ds_read_b128 v[180:183], v186 offset:32768
	ds_read_b128 v[188:191], v186 offset:33792
	ds_read_b128 v[192:195], v186 offset:34816
	ds_read_b128 v[196:199], v186 offset:35840
	ds_read_b128 v[200:203], v186 offset:36864
	ds_read_b128 v[204:207], v186 offset:37888
	ds_read_b128 v[208:211], v186 offset:38912
	ds_read_b128 v[212:215], v186 offset:39936
	global_load_lds_dwordx4 v[228:229], off
	v_lshl_add_u64 v[228:229], s[22:23], 0, v[156:157]
	s_mov_b32 m0, s38
	s_nop 0
	global_load_lds_dwordx4 v[228:229], off
	s_waitcnt vmcnt(8)
	s_waitcnt lgkmcnt(0)
	s_barrier
; #define PG8_STAGE(bufoff, gbase, voff) do { _Pragma("unroll") for (int _i = 0; _i < 2; ++_i) \
;         __builtin_amdgcn_global_load_lds((const unsigned*)((const char*)(gbase) + (voff)[_i]), (PG8_LAS unsigned*)(lds + (bufoff) + ldsw + _i * 8192), 16, 0, 0); } while (0)
; #define PG8_LDA(dst, b, h) do { _Pragma("unroll") for (int m = 0; m < 4; ++m) _Pragma("unroll") for (int k = 0; k < 2; ++k) dst[m][k] = *(const PG8_LAS bf16x8*)(lds + PG8_SA(b, h) + aoff + m * 2048 + k * 1024); } while (0)
; #define PG8_MMA(ai, bj, At, Bt) do { __builtin_amdgcn_s_setprio(1); _Pragma("unroll") for (int m = 0; m < 4; ++m) _Pragma("unroll") for (int n = 0; n < 2; ++n) _Pragma("unroll") for (int k = 0; k < 2; ++k) \
;         acc[ai][bj][m][n] = __builtin_amdgcn_mfma_f32_16x16x32_bf16(Bt[n][k], At[m][k], acc[ai][bj][m][n], 0, 0, 0); __builtin_amdgcn_s_setprio(0); } while (0)
; #define PG8_WAIT_V(n) asm volatile("s_waitcnt vmcnt(" #n ")" ::: "memory")
; #define PG8_WAIT_L(n) asm volatile("s_waitcnt lgkmcnt(" #n ")" ::: "memory")
; #define PG8_BAR __builtin_amdgcn_s_barrier()
; #define PG8_SCHED __builtin_amdgcn_sched_barrier(0)
; template <class Epi, class Sched, bool ALIGN_EPI = false, bool SP2 = false>
; __device__ __forceinline__ void gemm_phase(PG8_LAS unsigned char* lds, const Gemm g, const Sched& S, const Epi& E) {
;     ...
;         for (int t = 0; t < nt; t += 2) {
;             const bool last = (t == nt - 2);
;             const char* a1 = cA + (size_t)(t + 1) * kstep;
;             const char* a2 = last ? nA : cA + (size_t)(t + 2) * kstep; const char* b2 = last ? nB : cB + (size_t)(t + 2) * kstep;
;             const char* a3 = a2 + kstep; const char* b3 = b2 + kstep;
;     ...
;             PG8_WAIT_V(8); PG8_WAIT_L(0); PG8_BAR; PG8_MMA(0, 0, At, B0); PG8_MMA(0, 1, At, B1); PG8_BAR; PG8_SCHED;
;             PG8_LDA(At, 1, 1); PG8_STAGE(PG8_SB(1, 0), b3, voffB); PG8_STAGE(PG8_SB(1, 1), b3 + hstep, voffB); PG8_STAGE(PG8_SA(1, 0), a3, voffA);
;             PG8_WAIT_V(8); PG8_WAIT_L(0); PG8_BAR; PG8_MMA(1, 0, At, B0); PG8_MMA(1, 1, At, B1); PG8_BAR; PG8_SCHED;
	s_setprio 1
	s_waitcnt lgkmcnt(0)
	v_mfma_f32_16x16x32_bf16 v[142:145], v[114:117], v[180:183], v[142:145]
	v_mfma_f32_16x16x32_bf16 v[138:141], v[122:125], v[180:183], v[138:141]
	v_mfma_f32_16x16x32_bf16 v[110:113], v[114:117], v[192:195], v[110:113]
	v_mfma_f32_16x16x32_bf16 v[106:109], v[122:125], v[192:195], v[106:109]
	v_mfma_f32_16x16x32_bf16 v[94:97], v[114:117], v[200:203], v[94:97]
	v_mfma_f32_16x16x32_bf16 v[90:93], v[122:125], v[200:203], v[90:93]
	v_mfma_f32_16x16x32_bf16 v[78:81], v[114:117], v[208:211], v[78:81]
	v_mfma_f32_16x16x32_bf16 v[74:77], v[122:125], v[208:211], v[74:77]
	v_mfma_f32_16x16x32_bf16 v[142:145], v[118:121], v[188:191], v[142:145]
	v_mfma_f32_16x16x32_bf16 v[138:141], v[134:137], v[188:191], v[138:141]
	v_mfma_f32_16x16x32_bf16 v[110:113], v[118:121], v[196:199], v[110:113]
	v_mfma_f32_16x16x32_bf16 v[106:109], v[134:137], v[196:199], v[106:109]
	v_mfma_f32_16x16x32_bf16 v[94:97], v[118:121], v[204:207], v[94:97]
	v_mfma_f32_16x16x32_bf16 v[90:93], v[134:137], v[204:207], v[90:93]
	v_mfma_f32_16x16x32_bf16 v[78:81], v[118:121], v[212:215], v[78:81]
	v_mfma_f32_16x16x32_bf16 v[74:77], v[134:137], v[212:215], v[74:77]
	v_mfma_f32_16x16x32_bf16 v[130:133], v[146:149], v[180:183], v[130:133]
	v_mfma_f32_16x16x32_bf16 v[126:129], v[166:169], v[180:183], v[126:129]
	v_mfma_f32_16x16x32_bf16 v[102:105], v[146:149], v[192:195], v[102:105]
	v_mfma_f32_16x16x32_bf16 v[98:101], v[166:169], v[192:195], v[98:101]
	v_mfma_f32_16x16x32_bf16 v[86:89], v[146:149], v[200:203], v[86:89]
	v_mfma_f32_16x16x32_bf16 v[82:85], v[166:169], v[200:203], v[82:85]
	v_mfma_f32_16x16x32_bf16 v[70:73], v[146:149], v[208:211], v[70:73]
	v_mfma_f32_16x16x32_bf16 v[66:69], v[166:169], v[208:211], v[66:69]
	v_mfma_f32_16x16x32_bf16 v[130:133], v[150:153], v[188:191], v[130:133]
	v_mfma_f32_16x16x32_bf16 v[126:129], v[170:173], v[188:191], v[126:129]
	v_mfma_f32_16x16x32_bf16 v[102:105], v[150:153], v[196:199], v[102:105]
	v_mfma_f32_16x16x32_bf16 v[98:101], v[170:173], v[196:199], v[98:101]
	v_mfma_f32_16x16x32_bf16 v[86:89], v[150:153], v[204:207], v[86:89]
	v_mfma_f32_16x16x32_bf16 v[82:85], v[170:173], v[204:207], v[82:85]
	v_mfma_f32_16x16x32_bf16 v[70:73], v[150:153], v[212:215], v[70:73]
	v_mfma_f32_16x16x32_bf16 v[66:69], v[170:173], v[212:215], v[66:69]
	s_setprio 0
	s_barrier
	s_add_i32 s22, s51, s34
	v_lshl_add_u64 v[216:217], v[216:217], 0, s[96:97]
	s_mov_b32 m0, s22
	ds_read_b128 v[180:183], v186 offset:49152
	ds_read_b128 v[188:191], v186 offset:50176
	ds_read_b128 v[192:195], v186 offset:51200
	ds_read_b128 v[196:199], v186 offset:52224
	ds_read_b128 v[200:203], v186 offset:53248
	ds_read_b128 v[204:207], v186 offset:54272
	ds_read_b128 v[208:211], v186 offset:55296
	ds_read_b128 v[212:215], v186 offset:56320
	global_load_lds_dwordx4 v[216:217], off
	s_add_i32 m0, s22, 0x2000
	s_add_u32 s22, s24, 0xb0080
	v_lshl_add_u64 v[216:217], v[218:219], 0, s[96:97]
	s_addc_u32 s23, s25, 0
	s_add_i32 s24, s52, s34
	global_load_lds_dwordx4 v[216:217], off
	v_lshl_add_u64 v[216:217], s[22:23], 0, v[158:159]
	s_mov_b32 m0, s24
	s_nop 0
	global_load_lds_dwordx4 v[216:217], off
	v_lshl_add_u64 v[216:217], s[22:23], 0, v[154:155]
	s_add_i32 m0, s24, 0x2000
	s_nop 0
	global_load_lds_dwordx4 v[216:217], off
	v_lshl_add_u64 v[216:217], v[220:221], 0, s[96:97]
	s_mov_b32 m0, s41
	s_nop 0
	global_load_lds_dwordx4 v[216:217], off
	v_lshl_add_u64 v[216:217], v[222:223], 0, s[96:97]
	s_mov_b32 m0, s42
	s_nop 0
	global_load_lds_dwordx4 v[216:217], off
	s_waitcnt vmcnt(8)
	s_waitcnt lgkmcnt(0)
	s_barrier
	s_setprio 1
	s_waitcnt lgkmcnt(0)
	v_mfma_f32_16x16x32_bf16 v[62:65], v[114:117], v[180:183], v[62:65]
	v_mfma_f32_16x16x32_bf16 v[58:61], v[122:125], v[180:183], v[58:61]
	v_mfma_f32_16x16x32_bf16 v[46:49], v[114:117], v[192:195], v[46:49]
	v_mfma_f32_16x16x32_bf16 v[42:45], v[122:125], v[192:195], v[42:45]
	v_mfma_f32_16x16x32_bf16 v[30:33], v[114:117], v[200:203], v[30:33]
	v_mfma_f32_16x16x32_bf16 v[26:29], v[122:125], v[200:203], v[26:29]
	v_mfma_f32_16x16x32_bf16 v[14:17], v[114:117], v[208:211], v[14:17]
	v_mfma_f32_16x16x32_bf16 v[10:13], v[122:125], v[208:211], v[10:13]
	v_mfma_f32_16x16x32_bf16 v[62:65], v[118:121], v[188:191], v[62:65]
	v_mfma_f32_16x16x32_bf16 v[58:61], v[134:137], v[188:191], v[58:61]
	v_mfma_f32_16x16x32_bf16 v[46:49], v[118:121], v[196:199], v[46:49]
	v_mfma_f32_16x16x32_bf16 v[42:45], v[134:137], v[196:199], v[42:45]
	v_mfma_f32_16x16x32_bf16 v[30:33], v[118:121], v[204:207], v[30:33]
	v_mfma_f32_16x16x32_bf16 v[26:29], v[134:137], v[204:207], v[26:29]
	v_mfma_f32_16x16x32_bf16 v[14:17], v[118:121], v[212:215], v[14:17]
	v_mfma_f32_16x16x32_bf16 v[10:13], v[134:137], v[212:215], v[10:13]
	v_mfma_f32_16x16x32_bf16 v[54:57], v[146:149], v[180:183], v[54:57]
	v_mfma_f32_16x16x32_bf16 v[50:53], v[166:169], v[180:183], v[50:53]
	v_mfma_f32_16x16x32_bf16 v[38:41], v[146:149], v[192:195], v[38:41]
	v_mfma_f32_16x16x32_bf16 v[34:37], v[166:169], v[192:195], v[34:37]
	v_mfma_f32_16x16x32_bf16 v[22:25], v[146:149], v[200:203], v[22:25]
	v_mfma_f32_16x16x32_bf16 v[18:21], v[166:169], v[200:203], v[18:21]
	v_mfma_f32_16x16x32_bf16 v[6:9], v[146:149], v[208:211], v[6:9]
	v_mfma_f32_16x16x32_bf16 v[2:5], v[166:169], v[208:211], v[2:5]
	v_mfma_f32_16x16x32_bf16 v[54:57], v[150:153], v[188:191], v[54:57]
	v_mfma_f32_16x16x32_bf16 v[50:53], v[170:173], v[188:191], v[50:53]
	v_mfma_f32_16x16x32_bf16 v[38:41], v[150:153], v[196:199], v[38:41]
	v_mfma_f32_16x16x32_bf16 v[34:37], v[170:173], v[196:199], v[34:37]
	v_mfma_f32_16x16x32_bf16 v[22:25], v[150:153], v[204:207], v[22:25]
	v_mfma_f32_16x16x32_bf16 v[18:21], v[170:173], v[204:207], v[18:21]
	v_mfma_f32_16x16x32_bf16 v[6:9], v[150:153], v[212:215], v[6:9]
	v_mfma_f32_16x16x32_bf16 v[2:5], v[170:173], v[212:215], v[2:5]
	s_setprio 0
	s_add_i32 s50, s50, 2
	s_add_u32 s33, s33, 0x100
	s_addc_u32 s49, s49, 0
	s_mov_b64 s[22:23], s[8:9]
	s_add_u32 s8, s22, 0x100
	s_addc_u32 s9, s23, 0
	s_add_i32 s51, 0, 0x10000
	s_cmp_eq_u32 s50, 40
	s_cselect_b32 s27, s19, s9
	s_cselect_b32 s26, s18, s8
	s_cselect_b32 s25, s21, s49
	s_cselect_b32 s24, s20, s33
	s_add_i32 s52, 0, 0x14000
	s_cmp_gt_u32 s50, 41
	s_cbranch_scc0 .Lrotb_ffout
	s_barrier
	s_and_b64 vcc, exec, s[14:15]
	s_cbranch_vccz .LBB0_1363
	s_barrier
